# routing code placed 4 bytes later, everything behind it at its previous placement (placement trial)
# speedup vs baseline: 1.0081x; 1.0048x over previous
; #define LAS __attribute__((address_space(3)))
; #define MFMA32(a, b, c) __builtin_amdgcn_mfma_f32_32x32x16_bf16((a), (b), (c), 0, 0, 0)
; __device__ __forceinline__ void route_task(int task, int tl0, const bf16* QP  , const LAS bf16* KHL, LAS unsigned short* EL, LAS float* GL, int lane) {
;     const int r = lane & 31, hi = lane >> 5, t = 4 * task + (r >> 3), head = r & 7;
;     int top[2][16]; bf16x8 qa[2][4];
;     { unsigned qo = (unsigned)t * (unsigned)D + (unsigned)(head * 128 + 8 * hi); asm volatile("" : "+v"(qo)); const bf16* qp = QP + qo;
; #pragma unroll
;       for (int hf = 0; hf < 2; ++hf)
; #pragma unroll
;         for (int ks = 0; ks < 4; ++ks) qa[hf][ks] = ldg8(qp + 64 * hf + 16 * ks); }
; #pragma unroll
;     for (int half = 0; half < 2; ++half) {
;         int cur[16];
; #pragma unroll
;         for (int kt = 0; kt < 4; ++kt) {
;             f32x16 X;
; #pragma unroll
;             for (int i = 0; i < 16; ++i) X[i] = 8.f;
;             const LAS bf16* khp = KHL + (half * 128 + 32 * kt + r) * 72 + 8 * hi;
; #pragma unroll
;             for (int ks = 0; ks < 4; ++ks) {
;                 const bf16x8 kh = lds8(khp + 16 * ks);
;                 X = MFMA32(kh, qa[half][ks], X);
;             }
;             int grp[16];
; #pragma unroll
;             for (int i = 0; i < 16; ++i) grp[i] = (int)((__float_as_uint(X[i]) | 127u) - (unsigned)(32 * kt + (i & 3) + 8 * (i >> 2)));
;             sort16_desc(grp);
.LBB0_665:
	v_mov_b32_e32 v20, s53
	v_mov_b32_e32 v21, s49
	v_mov_b32_e32 v22, s52
	v_mov_b32_e32 v23, s48
	v_lshlrev_b32_e32 v24, 4, v19
	v_cmp_gt_u32_e32 vcc, s54, v19
	v_lshlrev_b32_e32 v25, 1, v18
	v_and_b32_e32 v82, 0x7f80, v24
	v_cndmask_b32_e32 v21, v20, v21, vcc
	v_cndmask_b32_e32 v20, v22, v23, vcc
	v_lshl_add_u64 v[20:21], v[20:21], 0, v[82:83]
	v_and_b32_e32 v82, 0x70, v25
	v_lshl_add_u64 v[20:21], v[20:21], 0, v[82:83]
	global_load_dwordx4 v[162:165], v[20:21], off
	v_lshrrev_b32_e32 v24, 3, v19
	v_mul_lo_u32 v24, v24, s56
	v_add3_u32 v178, 0, v24, v82
	v_add_u32_e32 v19, 0x200, v19
	v_add_u32_e32 v18, 0x1000, v18
	v_mov_b32_e32 v20, s53
	v_mov_b32_e32 v21, s49
	v_mov_b32_e32 v22, s52
	v_mov_b32_e32 v23, s48
	v_lshlrev_b32_e32 v24, 4, v19
	v_cmp_gt_u32_e32 vcc, s54, v19
	v_lshlrev_b32_e32 v25, 1, v18
	v_and_b32_e32 v82, 0x7f80, v24
	v_cndmask_b32_e32 v21, v20, v21, vcc
	v_cndmask_b32_e32 v20, v22, v23, vcc
	v_lshl_add_u64 v[20:21], v[20:21], 0, v[82:83]
	v_and_b32_e32 v82, 0x70, v25
	v_lshl_add_u64 v[20:21], v[20:21], 0, v[82:83]
	global_load_dwordx4 v[166:169], v[20:21], off
	v_lshrrev_b32_e32 v24, 3, v19
	v_mul_lo_u32 v24, v24, s56
	v_add3_u32 v179, 0, v24, v82
	v_add_u32_e32 v19, 0x200, v19
	v_add_u32_e32 v18, 0x1000, v18
	v_mov_b32_e32 v20, s53
	v_mov_b32_e32 v21, s49
	v_mov_b32_e32 v22, s52
	v_mov_b32_e32 v23, s48
	v_lshlrev_b32_e32 v24, 4, v19
	v_cmp_gt_u32_e32 vcc, s54, v19
	v_lshlrev_b32_e32 v25, 1, v18
	v_and_b32_e32 v82, 0x7f80, v24
	v_cndmask_b32_e32 v21, v20, v21, vcc
	v_cndmask_b32_e32 v20, v22, v23, vcc
	v_lshl_add_u64 v[20:21], v[20:21], 0, v[82:83]
	v_and_b32_e32 v82, 0x70, v25
	v_lshl_add_u64 v[20:21], v[20:21], 0, v[82:83]
	global_load_dwordx4 v[170:173], v[20:21], off
	v_lshrrev_b32_e32 v24, 3, v19
	v_mul_lo_u32 v24, v24, s56
	v_add3_u32 v180, 0, v24, v82
	v_add_u32_e32 v19, 0x200, v19
	v_add_u32_e32 v18, 0x1000, v18
	v_mov_b32_e32 v20, s53
	v_mov_b32_e32 v21, s49
	v_mov_b32_e32 v22, s52
	v_mov_b32_e32 v23, s48
	v_lshlrev_b32_e32 v24, 4, v19
	v_cmp_gt_u32_e32 vcc, s54, v19
	v_lshlrev_b32_e32 v25, 1, v18
	v_and_b32_e32 v82, 0x7f80, v24
	v_cndmask_b32_e32 v21, v20, v21, vcc
	v_cndmask_b32_e32 v20, v22, v23, vcc
	v_lshl_add_u64 v[20:21], v[20:21], 0, v[82:83]
	v_and_b32_e32 v82, 0x70, v25
	v_lshl_add_u64 v[20:21], v[20:21], 0, v[82:83]
	global_load_dwordx4 v[174:177], v[20:21], off
	v_lshrrev_b32_e32 v24, 3, v19
	v_mul_lo_u32 v24, v24, s56
	v_add3_u32 v181, 0, v24, v82
	v_add_u32_e32 v19, 0x200, v19
	v_add_u32_e32 v18, 0x1000, v18
	s_waitcnt vmcnt(0)
	ds_write_b128 v178, v[162:165]
	ds_write_b128 v179, v[166:169]
	ds_write_b128 v180, v[170:173]
	ds_write_b128 v181, v[174:177]
	s_nop 0
	s_nop 0
	s_nop 0
	s_nop 0
	s_nop 0
	s_nop 0
	s_nop 0
	s_nop 0
	s_nop 0
	s_nop 0
	s_nop 0
	s_nop 0
.LBB0_666:
	s_or_b64 exec, exec, s[10:11]
	s_lshl_b32 s10, s2, 4
	s_add_i32 s10, s10, s95
	s_lshl_b32 s10, s10, 12
	v_or_b32_e32 v82, s10, v88
	s_waitcnt lgkmcnt(0)
	s_barrier
	s_add_i32 s11, 0, 0x12000
	v_lshl_add_u64 v[70:71], v[82:83], 1, s[80:81]
	global_load_dwordx4 v[62:65], v[70:71], off
	global_load_dwordx4 v[54:57], v[70:71], off offset:32
	global_load_dwordx4 v[58:61], v[70:71], off offset:64
	global_load_dwordx4 v[50:53], v[70:71], off offset:96
	ds_read_b128 v[34:37], v94
	ds_read_b128 v[38:41], v94 offset:32
	s_add_i32 s10, s10, 0x8000
	s_mov_b32 s41, 0
	s_waitcnt vmcnt(3) lgkmcnt(1)
	v_mfma_f32_32x32x16_bf16 v[18:33], v[34:37], v[62:65], v[2:17]
	ds_read_b128 v[34:37], v94 offset:64
	ds_read_b128 v[66:69], v94 offset:96
	s_waitcnt vmcnt(2) lgkmcnt(2)
	v_mfma_f32_32x32x16_bf16 v[18:33], v[38:41], v[54:57], v[18:33]
	v_and_b32_e32 v38, 64, v112
	v_add_u32_e32 v122, 64, v38
	v_cmp_lt_i32_e32 vcc, v113, v122
	s_waitcnt vmcnt(1) lgkmcnt(1)
	v_mfma_f32_32x32x16_bf16 v[18:33], v[34:37], v[58:61], v[18:33]
	v_cndmask_b32_e32 v34, v112, v113, vcc
	v_lshlrev_b32_e32 v123, 2, v34
	global_load_dwordx4 v[46:49], v[70:71], off offset:128
	global_load_dwordx4 v[42:45], v[70:71], off offset:160
	global_load_dwordx4 v[38:41], v[70:71], off offset:192
	global_load_dwordx4 v[34:37], v[70:71], off offset:224
	s_waitcnt vmcnt(4) lgkmcnt(0)
	v_mfma_f32_32x32x16_bf16 v[18:33], v[66:69], v[50:53], v[18:33]
	s_nop 11
	s_movk_i32 s42, 0x7f
	s_movk_i32 s43, 0xff80
	v_bitop3_b32 v21, v21, s42, 3 bitop3:0x56
	v_bitop3_b32 v32, v32, s42, 26 bitop3:0x56
	v_bitop3_b32 v22, v22, s42, 8 bitop3:0x56
	v_bitop3_b32 v26, v26, s42, 16 bitop3:0x56
	v_bitop3_b32 v31, v31, s42, 25 bitop3:0x56
	v_bitop3_b32 v23, v23, s42, 9 bitop3:0x56
	v_bitop3_b32 v24, v24, s42, 10 bitop3:0x56
	v_bitop3_b32 v27, v27, s42, 17 bitop3:0x56
	v_bitop3_b32 v28, v28, s42, 18 bitop3:0x56
	v_bitop3_b32 v20, v20, s42, 2 bitop3:0x56
	v_bitop3_b32 v33, v33, s42, 27 bitop3:0x56
	v_bitop3_b32 v25, v25, s42, 11 bitop3:0x56
	v_bitop3_b32 v29, v29, s42, 19 bitop3:0x56
	v_bitop3_b32 v19, v19, s42, 1 bitop3:0x56
	v_bitop3_b32 v30, v30, s42, 24 bitop3:0x56
	v_or_b32_e32 v18, 0x7f, v18
	v_max_i32_e32 v66, v21, v32
	v_max_i32_e32 v67, v22, v26
	v_max_i32_e32 v68, v18, v31
	v_max_i32_e32 v69, v23, v24
	v_min_i32_e32 v70, v27, v28
	v_min_i32_e32 v71, v20, v33
	v_min_i32_e32 v72, v25, v29
	v_min_i32_e32 v73, v19, v30
	v_min_i32_e32 v23, v23, v24
	v_min_i32_e32 v18, v18, v31
	v_min_i32_e32 v22, v22, v26
	v_min_i32_e32 v21, v21, v32
	v_max_i32_e32 v19, v19, v30
	v_max_i32_e32 v24, v25, v29
	v_max_i32_e32 v20, v20, v33
	v_max_i32_e32 v25, v27, v28
	v_min_i32_e32 v26, v66, v67
	v_min_i32_e32 v27, v68, v69
	v_max_i32_e32 v28, v70, v71
	v_max_i32_e32 v29, v72, v73
	v_max_i32_e32 v30, v23, v18
	v_max_i32_e32 v31, v22, v21
	v_min_i32_e32 v32, v19, v24
	v_min_i32_e32 v33, v20, v25
	v_min_i32_e32 v18, v23, v18
; #define LAS __attribute__((address_space(3)))
; #define MFMA32(a, b, c) __builtin_amdgcn_mfma_f32_32x32x16_bf16((a), (b), (c), 0, 0, 0)
; __device__ __forceinline__ void route_task(int task, int tl0, const bf16* QP  , const LAS bf16* KHL, LAS unsigned short* EL, LAS float* GL, int lane) {
;     ...
;         for (int kt = 0; kt < 4; ++kt) {
;             f32x16 X;
; #pragma unroll
;             for (int i = 0; i < 16; ++i) X[i] = 8.f;
;             const LAS bf16* khp = KHL + (half * 128 + 32 * kt + r) * 72 + 8 * hi;
; #pragma unroll
;             for (int ks = 0; ks < 4; ++ks) {
;                 const bf16x8 kh = lds8(khp + 16 * ks);
;                 X = MFMA32(kh, qa[half][ks], X);
;             }
;             int grp[16];
; #pragma unroll
;             for (int i = 0; i < 16; ++i) grp[i] = (int)((__float_as_uint(X[i]) | 127u) - (unsigned)(32 * kt + (i & 3) + 8 * (i >> 2)));
;             sort16_desc(grp);
;             if (kt == 0) {
; #pragma unroll
;                 for (int i = 0; i < 16; ++i) cur[i] = grp[i];
;             } else merge16_desc(cur, grp);
	v_min_i32_e32 v21, v22, v21
	v_min_i32_e32 v22, v70, v71
	v_max_i32_e32 v23, v68, v69
	v_max_i32_e32 v19, v19, v24
	v_max_i32_e32 v20, v20, v25
	v_max_i32_e32 v24, v66, v67
	v_min_i32_e32 v25, v26, v27
	v_max_i32_e32 v67, v30, v31
	v_min_i32_e32 v30, v30, v31
	v_min_i32_e32 v31, v32, v33
	v_max_i32_e32 v26, v26, v27
	v_max_i32_e32 v27, v28, v29
	v_min_i32_e32 v66, v28, v29
	v_max_i32_e32 v68, v32, v33
	v_min_i32_e32 v75, v21, v22
	v_max_i32_e32 v21, v21, v22
	v_min_i32_e32 v22, v23, v19
	v_min_i32_e32 v28, v20, v24
	v_max_i32_e32 v33, v30, v31
	v_min_i32_e32 v69, v26, v27
	v_max_i32_e32 v29, v25, v66
	v_min_i32_e32 v32, v67, v68
	v_min_i32_e32 v77, v25, v66
	v_min_i32_e32 v25, v22, v28
	v_max_i32_e32 v80, v22, v28
	v_min_i32_e32 v22, v33, v69
	v_max_i32_e32 v125, v20, v24
	v_max_i32_e32 v129, v67, v68
	v_max_i32_e32 v24, v33, v69
	ds_read_b128 v[66:69], v95
	v_min_i32_e32 v72, v72, v73
	v_min_i32_e32 v74, v72, v18
	v_max_i32_e32 v18, v72, v18
	v_max_i32_e32 v124, v23, v19
	v_min_i32_e32 v76, v30, v31
	v_max_i32_e32 v78, v74, v75
	v_min_i32_e32 v79, v18, v21
	v_min_i32_e32 v126, v124, v125
	v_max_i32_e32 v128, v26, v27
	v_max_i32_e32 v18, v18, v21
	v_max_i32_e32 v81, v76, v77
	v_max_i32_e32 v82, v78, v79
	v_min_i32_e32 v127, v80, v126
	v_min_i32_e32 v130, v128, v129
	v_min_i32_e32 v21, v29, v32
	v_min_i32_e32 v28, v25, v18
	v_max_i32_e32 v18, v25, v18
	v_max_i32_e32 v30, v81, v82
	v_min_i32_e32 v19, v127, v130
	v_max_i32_e32 v23, v29, v32
	v_max_i32_e32 v25, v21, v22
	v_max_i32_e32 v31, v30, v28
	v_min_i32_e32 v20, v18, v19
	v_min_i32_e32 v26, v23, v24
	v_max_i32_e32 v70, v25, v31
	v_min_i32_e32 v27, v20, v26
	v_min_i32_e32 v131, v70, v27
	v_max_i32_e32 v143, v70, v27
	ds_read_b128 v[70:73], v95 offset:32
	v_min_i32_e32 v132, v25, v31
	v_min_i32_e32 v133, v21, v22
	v_min_i32_e32 v134, v30, v28
	v_max_i32_e32 v138, v18, v19
	v_max_i32_e32 v139, v23, v24
	v_max_i32_e32 v141, v20, v26
	s_waitcnt lgkmcnt(1)
	v_mfma_f32_32x32x16_bf16 v[18:33], v[66:69], v[62:65], v[2:17]
	ds_read_b128 v[66:69], v95 offset:64
	v_max_i32_e32 v135, v133, v134
	v_max_i32_e32 v136, v132, v135
	v_min_i32_e32 v76, v76, v77
	v_min_i32_e32 v77, v78, v79
	v_min_i32_e32 v132, v132, v135
	v_max_i32_e32 v127, v127, v130
	s_waitcnt lgkmcnt(1)
	v_mfma_f32_32x32x16_bf16 v[18:33], v[70:73], v[54:57], v[18:33]
	ds_read_b128 v[70:73], v95 offset:96
	v_max_i32_e32 v80, v80, v126
	v_min_i32_e32 v74, v74, v75
	v_min_i32_e32 v140, v138, v139
	v_max_i32_e32 v78, v76, v77
	v_min_i32_e32 v79, v81, v82
	v_min_i32_e32 v82, v133, v134
	s_waitcnt lgkmcnt(1)
	v_mfma_f32_32x32x16_bf16 v[18:33], v[66:69], v[58:61], v[18:33]
	v_max_i32_e32 v66, v128, v129
	v_max_i32_e32 v134, v138, v139
	v_min_i32_e32 v76, v76, v77
	v_max_i32_e32 v81, v78, v79
	v_min_i32_e32 v78, v78, v79
	v_min_i32_e32 v67, v80, v66
	v_min_i32_e32 v142, v140, v141
	s_waitcnt lgkmcnt(0)
	v_mfma_f32_32x32x16_bf16 v[18:33], v[70:73], v[50:53], v[18:33]
	v_min_i32_e32 v68, v127, v67
	v_min_i32_e32 v137, v131, v136
	v_min_i32_e32 v144, v142, v143
	v_min_i32_e32 v133, v81, v82
	v_min_i32_e32 v69, v134, v68
	s_nop 6
	v_bitop3_b32 v21, v21, s42, 35 bitop3:0x56
	v_bitop3_b32 v32, v32, s42, 58 bitop3:0x56
	v_bitop3_b32 v22, v22, s42, 40 bitop3:0x56
	v_bitop3_b32 v26, v26, s42, 48 bitop3:0x56
	v_bitop3_b32 v18, v18, s42, 32 bitop3:0x56
	v_bitop3_b32 v31, v31, s42, 57 bitop3:0x56
	v_bitop3_b32 v23, v23, s42, 41 bitop3:0x56
	v_bitop3_b32 v24, v24, s42, 42 bitop3:0x56
	v_bitop3_b32 v27, v27, s42, 49 bitop3:0x56
	v_bitop3_b32 v28, v28, s42, 50 bitop3:0x56
	v_bitop3_b32 v20, v20, s42, 34 bitop3:0x56
	v_bitop3_b32 v33, v33, s42, 59 bitop3:0x56
	v_bitop3_b32 v25, v25, s42, 43 bitop3:0x56
	v_bitop3_b32 v29, v29, s42, 51 bitop3:0x56
	v_bitop3_b32 v19, v19, s42, 33 bitop3:0x56
	v_bitop3_b32 v30, v30, s42, 56 bitop3:0x56
	v_max_i32_e32 v70, v21, v32
	v_max_i32_e32 v71, v22, v26
	v_max_i32_e32 v73, v18, v31
	v_max_i32_e32 v75, v23, v24
	v_min_i32_e32 v126, v27, v28
	v_min_i32_e32 v128, v20, v33
	v_min_i32_e32 v130, v25, v29
	v_min_i32_e32 v135, v19, v30
	v_min_i32_e32 v23, v23, v24
	v_min_i32_e32 v18, v18, v31
	v_min_i32_e32 v22, v22, v26
	v_min_i32_e32 v21, v21, v32
	v_max_i32_e32 v19, v19, v30
	v_max_i32_e32 v25, v25, v29
	v_max_i32_e32 v20, v20, v33
	v_max_i32_e32 v27, v27, v28
	v_min_i32_e32 v72, v70, v71
	v_min_i32_e32 v77, v73, v75
	v_max_i32_e32 v129, v126, v128
	v_max_i32_e32 v138, v130, v135
	v_max_i32_e32 v24, v23, v18
	v_max_i32_e32 v26, v22, v21
	v_min_i32_e32 v29, v19, v25
	v_min_i32_e32 v28, v20, v27
	v_min_i32_e32 v130, v130, v135
	v_min_i32_e32 v18, v23, v18
	v_min_i32_e32 v21, v22, v21
	v_min_i32_e32 v22, v126, v128
	v_max_i32_e32 v73, v73, v75
	v_max_i32_e32 v19, v19, v25
	v_max_i32_e32 v20, v20, v27
	v_max_i32_e32 v27, v70, v71
	v_min_i32_e32 v79, v72, v77
	v_min_i32_e32 v139, v129, v138
	v_max_i32_e32 v31, v24, v26
	v_max_i32_e32 v30, v29, v28
	v_min_i32_e32 v24, v24, v26
	v_min_i32_e32 v26, v29, v28
	v_max_i32_e32 v29, v72, v77
	v_max_i32_e32 v72, v129, v138
	v_min_i32_e32 v23, v130, v18
	v_min_i32_e32 v126, v21, v22
	v_max_i32_e32 v18, v130, v18
	v_max_i32_e32 v21, v21, v22
	v_min_i32_e32 v25, v73, v19
	v_min_i32_e32 v70, v20, v27
	v_max_i32_e32 v19, v73, v19
	v_max_i32_e32 v20, v20, v27
	v_min_i32_e32 v32, v31, v30
	v_max_i32_e32 v28, v24, v26
	v_min_i32_e32 v77, v29, v72
	v_min_i32_e32 v24, v24, v26
	v_min_i32_e32 v26, v79, v139
	v_max_i32_e32 v128, v23, v126
	v_min_i32_e32 v22, v18, v21
	v_min_i32_e32 v71, v25, v70
	v_max_i32_e32 v25, v25, v70
	v_min_i32_e32 v27, v19, v20
	v_max_i32_e32 v29, v29, v72
	v_max_i32_e32 v30, v31, v30
	v_max_i32_e32 v145, v79, v139
	v_max_i32_e32 v79, v24, v26
	v_max_i32_e32 v130, v128, v22
; #define LAS __attribute__((address_space(3)))
; #define MFMA32(a, b, c) __builtin_amdgcn_mfma_f32_32x32x16_bf16((a), (b), (c), 0, 0, 0)
; __device__ __forceinline__ void route_task(int task, int tl0, const bf16* QP  , const LAS bf16* KHL, LAS unsigned short* EL, LAS float* GL, int lane) {
;     ...
;         for (int kt = 0; kt < 4; ++kt) {
;             f32x16 X;
; #pragma unroll
;             for (int i = 0; i < 16; ++i) X[i] = 8.f;
;             const LAS bf16* khp = KHL + (half * 128 + 32 * kt + r) * 72 + 8 * hi;
; #pragma unroll
;             for (int ks = 0; ks < 4; ++ks) {
;                 const bf16x8 kh = lds8(khp + 16 * ks);
;                 X = MFMA32(kh, qa[half][ks], X);
;             }
;             int grp[16];
; #pragma unroll
;             for (int i = 0; i < 16; ++i) grp[i] = (int)((__float_as_uint(X[i]) | 127u) - (unsigned)(32 * kt + (i & 3) + 8 * (i >> 2)));
;             sort16_desc(grp);
;             if (kt == 0) {
; #pragma unroll
;                 for (int i = 0; i < 16; ++i) cur[i] = grp[i];
;             } else merge16_desc(cur, grp);
	v_max_i32_e32 v18, v18, v21
	v_min_i32_e32 v70, v25, v27
	v_min_i32_e32 v31, v29, v30
	v_min_i32_e32 v33, v145, v32
	v_min_i32_e32 v129, v28, v77
	v_max_i32_e32 v135, v79, v130
	v_min_i32_e32 v21, v71, v18
	v_max_i32_e32 v18, v71, v18
	v_min_i32_e32 v71, v70, v31
	v_max_i32_e32 v32, v145, v32
	v_max_i32_e32 v28, v28, v77
	v_max_i32_e32 v138, v33, v129
	v_max_i32_e32 v75, v135, v21
	v_min_i32_e32 v72, v18, v71
	v_min_i32_e32 v73, v32, v28
	v_min_i32_e32 v33, v33, v129
	v_min_i32_e32 v21, v135, v21
	v_max_i32_e32 v18, v18, v71
	v_max_i32_e32 v28, v32, v28
	v_min_i32_e32 v24, v24, v26
	v_min_i32_e32 v22, v128, v22
	v_max_i32_e32 v25, v25, v27
	v_max_i32_e32 v27, v29, v30
	v_max_i32_e32 v139, v138, v75
	v_min_i32_e32 v77, v72, v73
	v_min_i32_e32 v75, v138, v75
	v_max_i32_e32 v129, v33, v21
	v_min_i32_e32 v32, v18, v28
	v_max_i32_e32 v71, v72, v73
	v_max_i32_e32 v26, v24, v22
	v_min_i32_e32 v79, v79, v130
	v_max_i32_e32 v18, v18, v28
	v_max_i32_e32 v28, v70, v31
	v_min_i32_e32 v29, v25, v27
	v_min_i32_e32 v145, v139, v77
	v_max_i32_e32 v135, v75, v129
	v_min_i32_e32 v72, v32, v71
	v_max_i32_e32 v73, v139, v77
	v_max_i32_e32 v128, v26, v79
	v_min_i32_e32 v21, v33, v21
	v_min_i32_e32 v30, v28, v29
	v_min_i32_e32 v138, v145, v135
	v_min_i32_e32 v77, v72, v73
	v_min_i32_e32 v33, v128, v21
	v_min_i32_e32 v75, v75, v129
	v_min_i32_e32 v31, v18, v30
	v_min_i32_e32 v26, v26, v79
	v_min_i32_e32 v22, v24, v22
	v_min_i32_e32 v23, v23, v126
	v_max3_i32 v23, v124, v125, v23
	v_max3_i32 v22, v80, v66, v22
	v_max3_i32 v24, v127, v67, v26
	v_max3_i32 v26, v134, v68, v33
	v_max3_i32 v21, v69, v128, v21
	v_max3_i32 v33, v140, v141, v75
	v_max3_i32 v66, v142, v143, v138
	v_max3_i32 v67, v144, v145, v135
	v_max3_i32 v68, v131, v136, v77
	v_max3_i32 v69, v137, v72, v73
	v_max3_i32 v32, v132, v32, v71
	v_max3_i32 v31, v81, v82, v31
	v_max3_i32 v18, v133, v18, v30
	v_max3_i32 v28, v78, v28, v29
	v_max3_i32 v25, v76, v25, v27
	v_max3_i32 v19, v74, v19, v20
	v_max_i32_e32 v20, v23, v68
	v_min_i32_e32 v23, v23, v68
	v_max_i32_e32 v27, v22, v69
	v_min_i32_e32 v22, v22, v69
	v_max_i32_e32 v29, v24, v32
	v_min_i32_e32 v24, v24, v32
	v_max_i32_e32 v30, v26, v31
	v_min_i32_e32 v26, v26, v31
	v_max_i32_e32 v31, v21, v18
	v_min_i32_e32 v18, v21, v18
	v_max_i32_e32 v21, v33, v28
	v_min_i32_e32 v28, v33, v28
	v_max_i32_e32 v32, v66, v25
	v_min_i32_e32 v25, v66, v25
	v_max_i32_e32 v33, v67, v19
	v_min_i32_e32 v19, v67, v19
	ds_read_b128 v[66:69], v94 offset:9216
	v_max_i32_e32 v70, v20, v31
	v_min_i32_e32 v74, v20, v31
	v_max_i32_e32 v20, v27, v21
	v_min_i32_e32 v75, v27, v21
	v_max_i32_e32 v21, v29, v32
	v_max_i32_e32 v27, v30, v33
	v_max_i32_e32 v127, v70, v21
	v_min_i32_e32 v128, v70, v21
	ds_read_b128 v[70:73], v94 offset:9248
	v_min_i32_e32 v76, v29, v32
	v_min_i32_e32 v77, v30, v33
	v_max_i32_e32 v78, v23, v18
	v_min_i32_e32 v79, v23, v18
	v_max_i32_e32 v80, v22, v28
	v_min_i32_e32 v81, v22, v28
	v_max_i32_e32 v82, v24, v25
	v_min_i32_e32 v124, v24, v25
	v_max_i32_e32 v125, v26, v19
	v_min_i32_e32 v126, v26, v19
	v_max_i32_e32 v129, v20, v27
	v_min_i32_e32 v130, v20, v27
	s_waitcnt lgkmcnt(1)
	v_mfma_f32_32x32x16_bf16 v[18:33], v[66:69], v[62:65], v[2:17]
	ds_read_b128 v[66:69], v94 offset:9280
	v_max_i32_e32 v131, v74, v76
	v_min_i32_e32 v74, v74, v76
	v_max_i32_e32 v76, v75, v77
	v_min_i32_e32 v75, v75, v77
	v_max_i32_e32 v77, v78, v82
	v_min_i32_e32 v78, v78, v82
	s_waitcnt lgkmcnt(1)
	v_mfma_f32_32x32x16_bf16 v[18:33], v[70:73], v[54:57], v[18:33]
	ds_read_b128 v[70:73], v94 offset:9312
	v_max_i32_e32 v82, v80, v125
	v_min_i32_e32 v80, v80, v125
	v_max_i32_e32 v125, v79, v124
	v_min_i32_e32 v79, v79, v124
	v_max_i32_e32 v124, v81, v126
	v_min_i32_e32 v81, v81, v126
	s_waitcnt lgkmcnt(1)
	v_mfma_f32_32x32x16_bf16 v[18:33], v[66:69], v[58:61], v[18:33]
	v_min_i32_e32 v126, v127, v129
	v_min_i32_e32 v66, v128, v130
	v_min_i32_e32 v67, v131, v76
	v_min_i32_e32 v69, v77, v82
	v_min_i32_e32 v132, v78, v80
	v_min_i32_e32 v133, v125, v124
	v_min_i32_e32 v68, v74, v75
	s_waitcnt lgkmcnt(0)
	v_mfma_f32_32x32x16_bf16 v[18:33], v[70:73], v[50:53], v[18:33]
	v_min_i32_e32 v134, v79, v81
	s_nop 10
	v_and_or_b32 v21, v21, s43, 60
	v_and_or_b32 v32, v32, s43, 37
	v_and_or_b32 v22, v22, s43, 55
	v_and_or_b32 v26, v26, s43, 47
	v_bitop3_b32 v18, v18, s42, 64 bitop3:0x56
	v_and_or_b32 v31, v31, s43, 38
	v_and_or_b32 v23, v23, s43, 54
	v_and_or_b32 v24, v24, s43, 53
	v_and_or_b32 v27, v27, s43, 46
	v_and_or_b32 v28, v28, s43, 45
	v_and_or_b32 v20, v20, s43, 61
	v_and_or_b32 v33, v33, s43, 36
	v_and_or_b32 v25, v25, s43, 52
	v_and_or_b32 v29, v29, s43, 44
	v_and_or_b32 v19, v19, s43, 62
	v_and_or_b32 v30, v30, s43, 39
	v_max_i32_e32 v70, v21, v32
	v_max_i32_e32 v71, v22, v26
	v_max_i32_e32 v73, v18, v31
	v_max_i32_e32 v135, v23, v24
	v_min_i32_e32 v138, v27, v28
	v_min_i32_e32 v139, v20, v33
	v_min_i32_e32 v141, v25, v29
	v_min_i32_e32 v142, v19, v30
	v_min_i32_e32 v23, v23, v24
	v_min_i32_e32 v18, v18, v31
	v_min_i32_e32 v22, v22, v26
	v_min_i32_e32 v21, v21, v32
	v_max_i32_e32 v19, v19, v30
	v_max_i32_e32 v25, v25, v29
	v_max_i32_e32 v20, v20, v33
	v_max_i32_e32 v27, v27, v28
	v_min_i32_e32 v72, v70, v71
	v_min_i32_e32 v136, v73, v135
	v_max_i32_e32 v140, v138, v139
	v_max_i32_e32 v143, v141, v142
	v_max_i32_e32 v24, v23, v18
	v_max_i32_e32 v26, v22, v21
	v_min_i32_e32 v29, v19, v25
	v_min_i32_e32 v28, v20, v27
	v_min_i32_e32 v141, v141, v142
	v_min_i32_e32 v18, v23, v18
	v_min_i32_e32 v21, v22, v21
	v_min_i32_e32 v22, v138, v139
	v_max_i32_e32 v73, v73, v135
	v_max_i32_e32 v19, v19, v25
	v_max_i32_e32 v20, v20, v27
	v_max_i32_e32 v27, v70, v71
	v_min_i32_e32 v137, v72, v136
; #define LAS __attribute__((address_space(3)))
; #define MFMA32(a, b, c) __builtin_amdgcn_mfma_f32_32x32x16_bf16((a), (b), (c), 0, 0, 0)
; __device__ __forceinline__ void route_task(int task, int tl0, const bf16* QP  , const LAS bf16* KHL, LAS unsigned short* EL, LAS float* GL, int lane) {
;     ...
;         for (int kt = 0; kt < 4; ++kt) {
;             f32x16 X;
; #pragma unroll
;             for (int i = 0; i < 16; ++i) X[i] = 8.f;
;             const LAS bf16* khp = KHL + (half * 128 + 32 * kt + r) * 72 + 8 * hi;
; #pragma unroll
;             for (int ks = 0; ks < 4; ++ks) {
;                 const bf16x8 kh = lds8(khp + 16 * ks);
;                 X = MFMA32(kh, qa[half][ks], X);
;             }
;             int grp[16];
; #pragma unroll
;             for (int i = 0; i < 16; ++i) grp[i] = (int)((__float_as_uint(X[i]) | 127u) - (unsigned)(32 * kt + (i & 3) + 8 * (i >> 2)));
;             sort16_desc(grp);
;             if (kt == 0) {
; #pragma unroll
;                 for (int i = 0; i < 16; ++i) cur[i] = grp[i];
;             } else merge16_desc(cur, grp);
	v_min_i32_e32 v144, v140, v143
	v_max_i32_e32 v31, v24, v26
	v_max_i32_e32 v30, v29, v28
	v_min_i32_e32 v24, v24, v26
	v_min_i32_e32 v26, v29, v28
	v_max_i32_e32 v29, v72, v136
	v_max_i32_e32 v72, v140, v143
	v_min_i32_e32 v23, v141, v18
	v_min_i32_e32 v138, v21, v22
	v_max_i32_e32 v18, v141, v18
	v_max_i32_e32 v21, v21, v22
	v_min_i32_e32 v25, v73, v19
	v_min_i32_e32 v70, v20, v27
	v_max_i32_e32 v19, v73, v19
	v_max_i32_e32 v20, v20, v27
	v_min_i32_e32 v32, v31, v30
	v_max_i32_e32 v28, v24, v26
	v_min_i32_e32 v136, v29, v72
	v_min_i32_e32 v24, v24, v26
	v_min_i32_e32 v26, v137, v144
	v_max_i32_e32 v139, v23, v138
	v_min_i32_e32 v22, v18, v21
	v_min_i32_e32 v71, v25, v70
	v_max_i32_e32 v25, v25, v70
	v_min_i32_e32 v27, v19, v20
	v_max_i32_e32 v29, v29, v72
	v_max_i32_e32 v30, v31, v30
	v_max_i32_e32 v145, v137, v144
	v_max_i32_e32 v137, v24, v26
	v_max_i32_e32 v141, v139, v22
	v_max_i32_e32 v18, v18, v21
	v_min_i32_e32 v70, v25, v27
	v_min_i32_e32 v31, v29, v30
	v_min_i32_e32 v33, v145, v32
	v_min_i32_e32 v140, v28, v136
	v_max_i32_e32 v142, v137, v141
	v_min_i32_e32 v21, v71, v18
	v_max_i32_e32 v18, v71, v18
	v_min_i32_e32 v71, v70, v31
	v_max_i32_e32 v32, v145, v32
	v_max_i32_e32 v28, v28, v136
	v_max_i32_e32 v143, v33, v140
	v_max_i32_e32 v135, v142, v21
	v_min_i32_e32 v72, v18, v71
	v_min_i32_e32 v73, v32, v28
	v_min_i32_e32 v33, v33, v140
	v_min_i32_e32 v21, v142, v21
	v_max_i32_e32 v18, v18, v71
	v_max_i32_e32 v28, v32, v28
	v_min_i32_e32 v24, v24, v26
	v_min_i32_e32 v22, v139, v22
	v_max_i32_e32 v25, v25, v27
	v_max_i32_e32 v27, v29, v30
	v_max_i32_e32 v144, v143, v135
	v_min_i32_e32 v136, v72, v73
	v_min_i32_e32 v135, v143, v135
	v_max_i32_e32 v140, v33, v21
	v_min_i32_e32 v32, v18, v28
	v_max_i32_e32 v71, v72, v73
	v_max_i32_e32 v26, v24, v22
	v_min_i32_e32 v137, v137, v141
	v_max_i32_e32 v18, v18, v28
	v_max_i32_e32 v28, v70, v31
	v_min_i32_e32 v29, v25, v27
	v_min_i32_e32 v145, v144, v136
	v_max_i32_e32 v142, v135, v140
	v_min_i32_e32 v72, v32, v71
	v_max_i32_e32 v73, v144, v136
	v_max_i32_e32 v139, v26, v137
	v_min_i32_e32 v21, v33, v21
	v_min_i32_e32 v30, v28, v29
	v_min_i32_e32 v143, v145, v142
	v_min_i32_e32 v136, v72, v73
	v_min_i32_e32 v33, v139, v21
	v_max_i32_e32 v21, v139, v21
	v_min_i32_e32 v135, v135, v140
	v_max_i32_e32 v32, v32, v71
	v_min_i32_e32 v31, v18, v30
	v_max_i32_e32 v18, v18, v30
	v_min_i32_e32 v26, v26, v137
	v_min_i32_e32 v22, v24, v22
	v_max_i32_e32 v24, v25, v27
	v_min_i32_e32 v23, v23, v138
	v_max3_i32 v23, v127, v129, v23
	v_max_i32_e32 v22, v126, v22
	v_max3_i32 v25, v128, v130, v26
	v_max_i32_e32 v26, v66, v33
	v_max3_i32 v21, v131, v76, v21
	v_max_i32_e32 v27, v67, v135
	v_max3_i32 v30, v74, v75, v143
	v_max3_i32 v66, v77, v82, v136
	v_max3_i32 v67, v69, v72, v73
	v_max3_i32 v32, v78, v80, v32
	v_max_i32_e32 v31, v132, v31
	v_max3_i32 v18, v125, v124, v18
	v_max3_i32 v28, v133, v28, v29
	v_max3_i32 v24, v79, v81, v24
	v_max3_i32 v33, v68, v145, v142
	v_max3_i32 v19, v134, v19, v20
	v_max_i32_e32 v20, v23, v66
	v_min_i32_e32 v23, v23, v66
	v_max_i32_e32 v29, v22, v67
	v_max_i32_e32 v66, v25, v32
	v_min_i32_e32 v25, v25, v32
	v_max_i32_e32 v32, v26, v31
	v_min_i32_e32 v26, v26, v31
	v_max_i32_e32 v31, v21, v18
	v_min_i32_e32 v18, v21, v18
	v_max_i32_e32 v21, v27, v28
	v_min_i32_e32 v27, v27, v28
	v_max_i32_e32 v28, v30, v24
	v_min_i32_e32 v22, v22, v67
	v_min_i32_e32 v24, v30, v24
	v_max_i32_e32 v30, v33, v19
	v_min_i32_e32 v19, v33, v19
	v_max_i32_e32 v33, v20, v31
	v_min_i32_e32 v74, v20, v31
	v_max_i32_e32 v20, v29, v21
	v_min_i32_e32 v75, v29, v21
	v_max_i32_e32 v21, v66, v28
	v_min_i32_e32 v76, v66, v28
	ds_read_b128 v[66:69], v96
	ds_read_b128 v[70:73], v96 offset:32
	v_max_i32_e32 v28, v32, v30
	v_min_i32_e32 v77, v32, v30
	v_max_i32_e32 v78, v23, v18
	v_min_i32_e32 v79, v23, v18
	v_max_i32_e32 v80, v22, v27
	v_min_i32_e32 v81, v22, v27
	v_max_i32_e32 v82, v25, v24
	v_min_i32_e32 v124, v25, v24
	v_max_i32_e32 v125, v26, v19
	v_min_i32_e32 v126, v26, v19
	v_max_i32_e32 v127, v33, v21
	v_min_i32_e32 v128, v33, v21
	v_max_i32_e32 v129, v20, v28
	v_min_i32_e32 v130, v20, v28
	s_waitcnt lgkmcnt(1)
	v_mfma_f32_32x32x16_bf16 v[18:33], v[66:69], v[62:65], v[2:17]
	ds_read_b128 v[62:65], v96 offset:64
	v_max_i32_e32 v67, v75, v77
	v_min_i32_e32 v68, v75, v77
	v_max_i32_e32 v75, v80, v125
	v_max_i32_e32 v131, v74, v76
	v_min_i32_e32 v66, v74, v76
	v_max_i32_e32 v69, v78, v82
	s_waitcnt lgkmcnt(1)
	v_mfma_f32_32x32x16_bf16 v[18:33], v[70:73], v[54:57], v[18:33]
	ds_read_b128 v[54:57], v96 offset:96
	v_min_i32_e32 v70, v80, v125
	v_max_i32_e32 v71, v79, v124
	v_min_i32_e32 v72, v79, v124
	v_min_i32_e32 v74, v78, v82
	v_max_i32_e32 v73, v81, v126
	v_min_i32_e32 v76, v81, v126
	s_waitcnt lgkmcnt(1)
	v_mfma_f32_32x32x16_bf16 v[18:33], v[62:65], v[58:61], v[18:33]
	v_min_i32_e32 v77, v127, v129
	v_min_i32_e32 v58, v128, v130
	v_min_i32_e32 v59, v131, v67
	v_min_i32_e32 v60, v66, v68
	v_min_i32_e32 v61, v69, v75
	v_min_i32_e32 v62, v74, v70
	v_min_i32_e32 v63, v71, v73
	s_waitcnt lgkmcnt(0)
; #define LAS __attribute__((address_space(3)))
; #define MFMA32(a, b, c) __builtin_amdgcn_mfma_f32_32x32x16_bf16((a), (b), (c), 0, 0, 0)
; __device__ __forceinline__ void route_task(int task, int tl0, const bf16* QP  , const LAS bf16* KHL, LAS unsigned short* EL, LAS float* GL, int lane) {
;     ...
;         for (int kt = 0; kt < 4; ++kt) {
;             f32x16 X;
; #pragma unroll
;             for (int i = 0; i < 16; ++i) X[i] = 8.f;
;             const LAS bf16* khp = KHL + (half * 128 + 32 * kt + r) * 72 + 8 * hi;
; #pragma unroll
;             for (int ks = 0; ks < 4; ++ks) {
;                 const bf16x8 kh = lds8(khp + 16 * ks);
;                 X = MFMA32(kh, qa[half][ks], X);
;             }
;             int grp[16];
; #pragma unroll
;             for (int i = 0; i < 16; ++i) grp[i] = (int)((__float_as_uint(X[i]) | 127u) - (unsigned)(32 * kt + (i & 3) + 8 * (i >> 2)));
;             sort16_desc(grp);
;             if (kt == 0) {
; #pragma unroll
;                 for (int i = 0; i < 16; ++i) cur[i] = grp[i];
;             } else merge16_desc(cur, grp);
	v_mfma_f32_32x32x16_bf16 v[18:33], v[54:57], v[50:53], v[18:33]
	v_min_i32_e32 v64, v72, v76
	s_nop 10
	v_and_or_b32 v25, v25, s43, 20
	v_and_or_b32 v29, v29, s43, 12
	v_and_or_b32 v19, v19, s43, 30
	v_and_or_b32 v30, v30, s43, 7
	v_and_or_b32 v23, v23, s43, 22
	v_and_or_b32 v24, v24, s43, 21
	v_and_or_b32 v18, v18, s43, 31
	v_and_or_b32 v31, v31, s43, 6
	v_and_or_b32 v22, v22, s43, 23
	v_and_or_b32 v26, v26, s43, 15
	v_and_or_b32 v21, v21, s43, 28
	v_and_or_b32 v32, v32, s43, 5
	v_and_or_b32 v27, v27, s43, 14
	v_and_or_b32 v28, v28, s43, 13
	v_and_or_b32 v20, v20, s43, 29
	v_and_or_b32 v33, v33, s43, 4
	v_min_i32_e32 v50, v25, v29
	v_min_i32_e32 v51, v19, v30
	v_min_i32_e32 v53, v23, v24
	v_min_i32_e32 v54, v18, v31
	v_min_i32_e32 v57, v22, v26
	v_min_i32_e32 v65, v21, v32
	v_min_i32_e32 v79, v27, v28
	v_min_i32_e32 v80, v20, v33
	v_max_i32_e32 v18, v18, v31
	v_max_i32_e32 v23, v23, v24
	v_max_i32_e32 v19, v19, v30
	v_max_i32_e32 v25, v25, v29
	v_max_i32_e32 v20, v20, v33
	v_max_i32_e32 v27, v27, v28
	v_max_i32_e32 v21, v21, v32
	v_max_i32_e32 v22, v22, v26
	v_max_i32_e32 v24, v18, v23
	v_max_i32_e32 v29, v19, v25
	v_max_i32_e32 v28, v20, v27
	v_max_i32_e32 v26, v21, v22
	v_min_i32_e32 v30, v24, v29
	v_min_i32_e32 v31, v28, v26
	v_min_i32_e32 v55, v53, v54
	v_min_i32_e32 v32, v30, v31
	v_max_i32_e32 v30, v30, v31
	v_min_i32_e32 v21, v21, v22
	v_min_i32_e32 v18, v18, v23
	v_max_i32_e32 v23, v79, v80
	v_max_i32_e32 v31, v50, v51
	v_max_i32_e32 v53, v53, v54
	v_max_i32_e32 v54, v57, v65
	v_min_i32_e32 v19, v19, v25
	v_min_i32_e32 v20, v20, v27
	v_min_i32_e32 v52, v50, v51
	v_min_i32_e32 v78, v57, v65
	v_min_i32_e32 v81, v79, v80
	v_max_i32_e32 v22, v21, v18
	v_max_i32_e32 v57, v53, v54
	v_max_i32_e32 v25, v19, v20
	v_min_i32_e32 v18, v21, v18
	v_min_i32_e32 v21, v23, v31
	v_min_i32_e32 v56, v52, v55
	v_min_i32_e32 v82, v78, v81
	v_max_i32_e32 v33, v52, v55
	v_max_i32_e32 v52, v78, v81
	v_max_i32_e32 v24, v24, v29
	v_max_i32_e32 v26, v28, v26
	v_max_i32_e32 v50, v23, v31
	v_max_i32_e32 v27, v57, v25
	v_max_i32_e32 v23, v18, v21
	v_min_i32_e32 v25, v57, v25
	v_min_i32_e32 v53, v53, v54
	v_min_i32_e32 v19, v19, v20
	v_max_i32_e32 v55, v33, v52
	v_min_i32_e32 v28, v24, v26
	v_max_i32_e32 v51, v22, v50
	v_max_i32_e32 v31, v23, v25
	v_max_i32_e32 v20, v53, v19
	v_min_i32_e32 v23, v23, v25
	v_min_i32_e32 v19, v53, v19
	v_min_i32_e32 v18, v18, v21
	v_max_i32_e32 v25, v56, v82
	v_min_i32_e32 v33, v33, v52
	v_min_i32_e32 v29, v30, v28
	v_min_i32_e32 v65, v51, v27
	v_min_i32_e32 v22, v22, v50
	v_max_i32_e32 v21, v19, v18
	v_max_i32_e32 v52, v25, v33
	v_max_i32_e32 v78, v32, v55
	v_min_i32_e32 v79, v29, v65
	v_max_i32_e32 v50, v20, v22
	v_min_i32_e32 v20, v20, v22
	v_max_i32_e32 v53, v21, v52
	v_min_i32_e32 v32, v32, v55
	v_max_i32_e32 v80, v78, v79
	v_max_i32_e32 v54, v31, v50
	v_min_i32_e32 v78, v78, v79
	v_min_i32_e32 v31, v31, v50
	v_max_i32_e32 v22, v23, v20
	v_max_i32_e32 v55, v53, v32
	v_min_i32_e32 v18, v19, v18
	v_min_i32_e32 v19, v25, v33
	v_min_i32_e32 v20, v23, v20
	v_min_i32_e32 v23, v53, v32
	v_max_i32_e32 v28, v30, v28
	v_max_i32_e32 v27, v51, v27
	v_min_i32_e32 v124, v56, v82
	v_min_i32_e32 v57, v80, v54
	v_max_i32_e32 v50, v78, v31
	v_max_i32_e32 v56, v22, v55
	v_min_i32_e32 v31, v78, v31
	v_max_i32_e32 v25, v18, v19
	v_min_i32_e32 v21, v21, v52
	v_min_i32_e32 v32, v20, v23
	v_max_i32_e32 v29, v29, v65
	v_min_i32_e32 v30, v28, v27
	v_min_i32_e32 v22, v22, v55
	v_max_i32_e32 v20, v20, v23
	v_min_i32_e32 v79, v57, v50
	v_max_i32_e32 v78, v56, v31
	v_max_i32_e32 v33, v25, v21
	v_max_i32_e32 v53, v80, v54
	v_min_i32_e32 v51, v29, v30
	v_min_i32_e32 v31, v56, v31
	v_max_i32_e32 v23, v22, v20
	v_min_i32_e32 v81, v79, v78
	v_max_i32_e32 v52, v33, v32
	v_max_i32_e32 v54, v53, v51
	v_min_i32_e32 v21, v25, v21
	v_max_i32_e32 v25, v57, v50
	v_min_i32_e32 v55, v31, v23
	v_max_i32_e32 v27, v28, v27
	v_min_i32_e32 v18, v18, v19
	v_min_i32_e32 v20, v22, v20
	v_min_i32_e32 v32, v33, v32
	v_min_i32_e32 v33, v53, v51
	v_max3_i32 v124, v127, v129, v124
	v_max3_i32 v69, v69, v75, v81
	v_max3_i32 v52, v131, v67, v52
	v_max3_i32 v54, v71, v73, v54
	v_max3_i32 v21, v128, v130, v21
	v_max3_i32 v25, v74, v70, v25
	v_max3_i32 v55, v66, v68, v55
	v_max3_i32 v27, v72, v76, v27
	v_max_i32_e32 v18, v77, v18
	v_max3_i32 v19, v61, v79, v78
	v_max_i32_e32 v20, v59, v20
	v_max3_i32 v22, v63, v29, v30
	v_max_i32_e32 v32, v58, v32
	v_max_i32_e32 v33, v62, v33
	v_max3_i32 v23, v60, v31, v23
	v_max3_i32 v24, v64, v24, v26
	v_min_i32_e32 v65, v52, v54
	v_min_i32_e32 v50, v21, v25
	v_min_i32_e32 v61, v18, v19
	v_min_i32_e32 v29, v20, v22
	v_min_i32_e32 v26, v23, v24
	v_max_i32_e32 v59, v124, v69
	v_max_i32_e32 v52, v52, v54
	v_max_i32_e32 v21, v21, v25
	v_max_i32_e32 v25, v55, v27
	v_max_i32_e32 v18, v18, v19
	v_max_i32_e32 v19, v20, v22
	v_max_i32_e32 v22, v32, v33
	v_max_i32_e32 v23, v23, v24
	v_min_i32_e32 v28, v55, v27
	v_max_i32_e32 v54, v59, v52
	v_max_i32_e32 v27, v21, v25
	v_max_i32_e32 v20, v18, v19
	v_max_i32_e32 v24, v22, v23
	v_min_i32_e32 v51, v32, v33
	v_max_i32_e32 v55, v54, v27
	v_max_i32_e32 v32, v20, v24
	v_min_i32_e32 v27, v54, v27
	v_min_i32_e32 v20, v20, v24
	v_max_i32_e32 v24, v27, v20
	v_min_i32_e32 v20, v27, v20
	v_min_i32_e32 v27, v59, v52
	v_min_i32_e32 v21, v21, v25
	v_min_i32_e32 v18, v18, v19
	v_min_i32_e32 v19, v22, v23
	v_min_i32_e32 v75, v124, v69
	v_max_i32_e32 v25, v27, v21
	v_max_i32_e32 v22, v18, v19
	v_min_i32_e32 v21, v27, v21
	v_min_i32_e32 v18, v18, v19
	v_min_i32_e32 v56, v50, v28
	v_min_i32_e32 v31, v51, v26
	v_max_i32_e32 v23, v25, v22
	v_min_i32_e32 v22, v25, v22
	v_max_i32_e32 v19, v21, v18
	v_min_i32_e32 v18, v21, v18
; __device__ __forceinline__ void route_task(int task, int tl0, const bf16* QP  , const LAS bf16* KHL, LAS unsigned short* EL, LAS float* GL, int lane) {
;     ...
;             } else merge16_desc(cur, grp);
;         }
;         { const unsigned h4 = 4u * (unsigned)hi;
; #pragma unroll
;           for (int i = 0; i < 16; ++i) cur[i] -= (int)h4; }
;         int oth[16];
; #pragma unroll
;         for (int i = 0; i < 16; ++i) oth[i] = __shfl_xor(cur[i], 32);
;         merge16_desc(cur, oth);
; #pragma unroll
;         for (int i = 0; i < 16; ++i) top[half][i] = cur[i];
;     }
	v_max_i32_e32 v21, v75, v65
	v_max_i32_e32 v25, v50, v28
	v_max_i32_e32 v28, v61, v29
	v_max_i32_e32 v26, v51, v26
	v_min_i32_e32 v67, v75, v65
	v_min_i32_e32 v30, v61, v29
	v_max_i32_e32 v27, v21, v25
	v_min_i32_e32 v21, v21, v25
	v_min_i32_e32 v25, v28, v26
	v_min_i32_e32 v57, v67, v56
	v_min_i32_e32 v53, v30, v31
	v_max_i32_e32 v29, v28, v26
	v_max_i32_e32 v26, v21, v25
	v_min_i32_e32 v21, v21, v25
	v_max_i32_e32 v25, v67, v56
	v_max_i32_e32 v28, v30, v31
	v_min_i32_e32 v58, v57, v53
	v_max_i32_e32 v33, v55, v32
	v_min_i32_e32 v32, v55, v32
	v_max_i32_e32 v50, v27, v29
	v_min_i32_e32 v27, v27, v29
	v_max_i32_e32 v29, v25, v28
	v_min_i32_e32 v25, v25, v28
	v_max_i32_e32 v28, v57, v53
	v_sub_u32_e32 v30, v33, v87
	v_sub_u32_e32 v31, v32, v87
	v_sub_u32_e32 v24, v24, v87
	v_sub_u32_e32 v20, v20, v87
	v_sub_u32_e32 v23, v23, v87
	v_sub_u32_e32 v22, v22, v87
	v_sub_u32_e32 v19, v19, v87
	v_sub_u32_e32 v18, v18, v87
	v_sub_u32_e32 v32, v50, v87
	v_sub_u32_e32 v27, v27, v87
	v_sub_u32_e32 v26, v26, v87
	v_sub_u32_e32 v21, v21, v87
	v_sub_u32_e32 v29, v29, v87
	v_sub_u32_e32 v25, v25, v87
	v_sub_u32_e32 v28, v28, v87
	v_sub_u32_e32 v33, v58, v87
	ds_bpermute_b32 v50, v123, v30
	ds_bpermute_b32 v51, v123, v31
	ds_bpermute_b32 v52, v123, v24
	ds_bpermute_b32 v53, v123, v20
	ds_bpermute_b32 v54, v123, v23
	ds_bpermute_b32 v55, v123, v22
	ds_bpermute_b32 v56, v123, v19
	ds_bpermute_b32 v57, v123, v18
	ds_bpermute_b32 v58, v123, v32
	ds_bpermute_b32 v59, v123, v27
	ds_bpermute_b32 v60, v123, v26
	ds_bpermute_b32 v61, v123, v33
	ds_bpermute_b32 v62, v123, v28
	ds_bpermute_b32 v63, v123, v25
	ds_bpermute_b32 v64, v123, v29
	ds_bpermute_b32 v65, v123, v21
	s_waitcnt lgkmcnt(4)
	v_max_i32_e32 v30, v30, v61
	s_waitcnt lgkmcnt(3)
	v_max_i32_e32 v31, v31, v62
	s_waitcnt lgkmcnt(2)
	v_max_i32_e32 v24, v24, v63
	s_waitcnt lgkmcnt(1)
	v_max_i32_e32 v20, v20, v64
	s_waitcnt lgkmcnt(0)
	v_max_i32_e32 v23, v23, v65
	v_max_i32_e32 v22, v22, v60
	v_max_i32_e32 v19, v19, v59
	v_max_i32_e32 v18, v18, v58
	v_max_i32_e32 v32, v32, v57
	v_max_i32_e32 v27, v27, v56
	v_max_i32_e32 v26, v26, v55
	v_max_i32_e32 v21, v21, v54
	v_max_i32_e32 v29, v29, v53
	v_max_i32_e32 v25, v25, v52
	v_max_i32_e32 v28, v28, v51
	v_max_i32_e32 v33, v33, v50
	v_max_i32_e32 v50, v30, v32
	v_min_i32_e32 v30, v30, v32
	v_max_i32_e32 v32, v31, v27
	v_min_i32_e32 v27, v31, v27
	v_max_i32_e32 v31, v24, v26
	v_min_i32_e32 v24, v24, v26
	v_max_i32_e32 v26, v20, v21
	v_min_i32_e32 v20, v20, v21
	v_max_i32_e32 v21, v23, v29
	v_min_i32_e32 v23, v23, v29
	v_max_i32_e32 v29, v22, v25
	v_min_i32_e32 v22, v22, v25
	v_max_i32_e32 v25, v19, v28
	v_min_i32_e32 v19, v19, v28
	v_max_i32_e32 v28, v18, v33
	v_min_i32_e32 v18, v18, v33
	v_max_i32_e32 v33, v50, v21
	v_min_i32_e32 v21, v50, v21
	v_max_i32_e32 v50, v32, v29
	v_min_i32_e32 v29, v32, v29
	v_max_i32_e32 v32, v31, v25
	v_min_i32_e32 v25, v31, v25
	v_max_i32_e32 v31, v26, v28
	v_max_i32_e32 v64, v50, v31
	v_min_i32_e32 v67, v50, v31
	ds_read_b128 v[50:53], v94 offset:18432
	ds_read_b128 v[54:57], v94 offset:18464
	v_min_i32_e32 v26, v26, v28
	v_max_i32_e32 v28, v30, v23
	v_min_i32_e32 v58, v30, v23
	v_max_i32_e32 v23, v27, v22
	v_min_i32_e32 v59, v27, v22
	v_max_i32_e32 v22, v24, v19
	v_min_i32_e32 v60, v24, v19
	v_max_i32_e32 v19, v20, v18
	v_min_i32_e32 v61, v20, v18
	v_max_i32_e32 v62, v33, v32
	v_min_i32_e32 v66, v33, v32
	v_max_i32_e32 v68, v21, v25
	v_min_i32_e32 v69, v21, v25
	v_max_i32_e32 v70, v29, v26
	v_min_i32_e32 v71, v29, v26
	v_max_i32_e32 v72, v28, v22
	v_min_i32_e32 v73, v28, v22
	v_max_i32_e32 v74, v23, v19
	v_min_i32_e32 v75, v23, v19
	s_waitcnt vmcnt(3) lgkmcnt(1)
	v_mfma_f32_32x32x16_bf16 v[18:33], v[50:53], v[46:49], v[2:17]
	ds_read_b128 v[50:53], v94 offset:18496
	v_max_i32_e32 v76, v58, v60
	v_min_i32_e32 v77, v58, v60
	v_max_i32_e32 v78, v59, v61
	v_min_i32_e32 v79, v59, v61
	v_max_i32_e32 v63, v62, v64
	v_min_i32_e32 v65, v62, v64
	s_waitcnt vmcnt(2) lgkmcnt(1)
	v_mfma_f32_32x32x16_bf16 v[18:33], v[54:57], v[42:45], v[18:33]
	v_max_i32_e32 v64, v66, v67
	v_min_i32_e32 v62, v66, v67
	v_max_i32_e32 v61, v68, v70
	v_min_i32_e32 v60, v68, v70
	v_max_i32_e32 v59, v69, v71
	v_min_i32_e32 v57, v69, v71
	ds_read_b128 v[66:69], v94 offset:18528
	s_waitcnt vmcnt(1) lgkmcnt(1)
	v_mfma_f32_32x32x16_bf16 v[18:33], v[50:53], v[38:41], v[18:33]
	v_max_i32_e32 v55, v72, v74
	v_min_i32_e32 v58, v72, v74
	v_max_i32_e32 v56, v73, v75
	v_min_i32_e32 v54, v73, v75
	v_max_i32_e32 v53, v76, v78
	v_min_i32_e32 v52, v76, v78
	v_max_i32_e32 v51, v77, v79
	s_waitcnt vmcnt(0) lgkmcnt(0)
; #define LAS __attribute__((address_space(3)))
; #define MFMA32(a, b, c) __builtin_amdgcn_mfma_f32_32x32x16_bf16((a), (b), (c), 0, 0, 0)
; __device__ __forceinline__ void route_task(int task, int tl0, const bf16* QP  , const LAS bf16* KHL, LAS unsigned short* EL, LAS float* GL, int lane) {
;     const int r = lane & 31, hi = lane >> 5, t = 4 * task + (r >> 3), head = r & 7;
;     int top[2][16]; bf16x8 qa[2][4];
;     { unsigned qo = (unsigned)t * (unsigned)D + (unsigned)(head * 128 + 8 * hi); asm volatile("" : "+v"(qo)); const bf16* qp = QP + qo;
; #pragma unroll
;       for (int hf = 0; hf < 2; ++hf)
; #pragma unroll
;         for (int ks = 0; ks < 4; ++ks) qa[hf][ks] = ldg8(qp + 64 * hf + 16 * ks); }
; #pragma unroll
;     for (int half = 0; half < 2; ++half) {
;         int cur[16];
; #pragma unroll
;         for (int kt = 0; kt < 4; ++kt) {
;             f32x16 X;
; #pragma unroll
;             for (int i = 0; i < 16; ++i) X[i] = 8.f;
;             const LAS bf16* khp = KHL + (half * 128 + 32 * kt + r) * 72 + 8 * hi;
; #pragma unroll
;             for (int ks = 0; ks < 4; ++ks) {
;                 const bf16x8 kh = lds8(khp + 16 * ks);
;                 X = MFMA32(kh, qa[half][ks], X);
;             }
;             int grp[16];
; #pragma unroll
;             for (int i = 0; i < 16; ++i) grp[i] = (int)((__float_as_uint(X[i]) | 127u) - (unsigned)(32 * kt + (i & 3) + 8 * (i >> 2)));
;             sort16_desc(grp);
;             if (kt == 0) {
; #pragma unroll
;                 for (int i = 0; i < 16; ++i) cur[i] = grp[i];
;             } else merge16_desc(cur, grp);
	v_or_b32_e32 v146, s10, v88
	v_mov_b32_e32 v147, v83
	v_lshl_add_u64 v[148:149], v[146:147], 1, s[80:81]
	global_load_dwordx4 v[150:153], v[148:149], off
	global_load_dwordx4 v[154:157], v[148:149], off offset:32
	global_load_dwordx4 v[158:161], v[148:149], off offset:64
	global_load_dwordx4 v[162:165], v[148:149], off offset:96
	global_load_dwordx4 v[166:169], v[148:149], off offset:128
	global_load_dwordx4 v[170:173], v[148:149], off offset:160
	global_load_dwordx4 v[174:177], v[148:149], off offset:192
	global_load_dwordx4 v[178:181], v[148:149], off offset:224
	v_mfma_f32_32x32x16_bf16 v[18:33], v[66:69], v[34:37], v[18:33]
	v_min_i32_e32 v50, v77, v79
	s_nop 10
	v_bitop3_b32 v21, v21, s42, 3 bitop3:0x56
	v_bitop3_b32 v32, v32, s42, 26 bitop3:0x56
	v_bitop3_b32 v22, v22, s42, 8 bitop3:0x56
	v_bitop3_b32 v26, v26, s42, 16 bitop3:0x56
	v_bitop3_b32 v31, v31, s42, 25 bitop3:0x56
	v_bitop3_b32 v23, v23, s42, 9 bitop3:0x56
	v_bitop3_b32 v24, v24, s42, 10 bitop3:0x56
	v_bitop3_b32 v27, v27, s42, 17 bitop3:0x56
	v_bitop3_b32 v28, v28, s42, 18 bitop3:0x56
	v_bitop3_b32 v20, v20, s42, 2 bitop3:0x56
	v_bitop3_b32 v33, v33, s42, 27 bitop3:0x56
	v_bitop3_b32 v25, v25, s42, 11 bitop3:0x56
	v_bitop3_b32 v29, v29, s42, 19 bitop3:0x56
	v_bitop3_b32 v19, v19, s42, 1 bitop3:0x56
	v_bitop3_b32 v30, v30, s42, 24 bitop3:0x56
	v_or_b32_e32 v18, 0x7f, v18
	v_max_i32_e32 v66, v21, v32
	v_max_i32_e32 v67, v22, v26
	v_max_i32_e32 v69, v18, v31
	v_max_i32_e32 v70, v23, v24
	v_min_i32_e32 v73, v27, v28
	v_min_i32_e32 v74, v20, v33
	v_min_i32_e32 v76, v25, v29
	v_min_i32_e32 v77, v19, v30
	v_min_i32_e32 v23, v23, v24
	v_min_i32_e32 v18, v18, v31
	v_min_i32_e32 v22, v22, v26
	v_min_i32_e32 v21, v21, v32
	v_max_i32_e32 v19, v19, v30
	v_max_i32_e32 v25, v25, v29
	v_max_i32_e32 v20, v20, v33
	v_max_i32_e32 v27, v27, v28
	v_max_i32_e32 v24, v23, v18
	v_max_i32_e32 v26, v22, v21
	v_min_i32_e32 v29, v19, v25
	v_min_i32_e32 v28, v20, v27
	v_max_i32_e32 v31, v24, v26
	v_min_i32_e32 v24, v24, v26
	v_min_i32_e32 v26, v29, v28
	v_min_i32_e32 v68, v66, v67
	v_min_i32_e32 v71, v69, v70
	v_max_i32_e32 v75, v73, v74
	v_max_i32_e32 v78, v76, v77
	v_max_i32_e32 v30, v29, v28
	v_max_i32_e32 v28, v24, v26
	v_min_i32_e32 v81, v24, v26
	v_min_i32_e32 v24, v76, v77
	v_min_i32_e32 v18, v23, v18
	v_min_i32_e32 v21, v22, v21
	v_min_i32_e32 v22, v73, v74
	v_min_i32_e32 v72, v68, v71
	v_min_i32_e32 v79, v75, v78
	v_min_i32_e32 v76, v24, v18
	v_min_i32_e32 v74, v21, v22
	v_max_i32_e32 v18, v24, v18
	v_max_i32_e32 v21, v21, v22
	v_max_i32_e32 v23, v69, v70
	v_max_i32_e32 v19, v19, v25
	v_max_i32_e32 v20, v20, v27
	v_max_i32_e32 v25, v66, v67
	v_max_i32_e32 v80, v72, v79
	v_max_i32_e32 v29, v68, v71
	v_max_i32_e32 v68, v75, v78
	v_min_i32_e32 v79, v72, v79
	v_max_i32_e32 v77, v76, v74
	v_min_i32_e32 v124, v18, v21
	v_min_i32_e32 v24, v23, v19
	v_min_i32_e32 v26, v20, v25
	v_min_i32_e32 v32, v31, v30
	v_min_i32_e32 v71, v29, v68
	v_max_i32_e32 v82, v81, v79
	v_max_i32_e32 v125, v77, v124
	v_min_i32_e32 v27, v24, v26
	v_max_i32_e32 v18, v18, v21
	v_min_i32_e32 v33, v80, v32
	v_min_i32_e32 v75, v28, v71
	v_max_i32_e32 v22, v82, v125
	v_min_i32_e32 v21, v27, v18
	v_max_i32_e32 v78, v33, v75
	v_max_i32_e32 v66, v22, v21
	v_max_i32_e32 v70, v78, v66
	v_max_i32_e32 v131, v29, v68
	v_min_i32_e32 v78, v78, v66
	ds_read_b128 v[66:69], v97
	v_max_i32_e32 v127, v23, v19
	v_max_i32_e32 v128, v20, v25
	v_max_i32_e32 v126, v24, v26
	v_min_i32_e32 v129, v127, v128
	v_max_i32_e32 v132, v31, v30
	v_min_i32_e32 v130, v126, v129
	v_min_i32_e32 v133, v131, v132
	v_max_i32_e32 v18, v27, v18
	v_min_i32_e32 v19, v130, v133
	v_max_i32_e32 v23, v80, v32
	v_max_i32_e32 v24, v28, v71
	v_min_i32_e32 v20, v18, v19
	v_min_i32_e32 v25, v23, v24
	v_min_i32_e32 v26, v20, v25
	v_min_i32_e32 v80, v70, v26
	v_max_i32_e32 v143, v70, v26
	ds_read_b128 v[70:73], v97 offset:32
	v_min_i32_e32 v75, v33, v75
	v_min_i32_e32 v134, v22, v21
	v_max_i32_e32 v138, v18, v19
	v_max_i32_e32 v139, v23, v24
	v_max_i32_e32 v141, v20, v25
	s_waitcnt lgkmcnt(1)
	v_mfma_f32_32x32x16_bf16 v[18:33], v[66:69], v[46:49], v[2:17]
	ds_read_b128 v[66:69], v97 offset:64
	v_max_i32_e32 v135, v75, v134
	v_max_i32_e32 v136, v78, v135
	v_min_i32_e32 v79, v81, v79
	v_min_i32_e32 v77, v77, v124
	v_min_i32_e32 v78, v78, v135
	v_max_i32_e32 v130, v130, v133
	s_waitcnt lgkmcnt(1)
	v_mfma_f32_32x32x16_bf16 v[18:33], v[70:73], v[42:45], v[18:33]
	ds_read_b128 v[70:73], v97 offset:96
	v_max_i32_e32 v126, v126, v129
	v_min_i32_e32 v74, v76, v74
	v_min_i32_e32 v140, v138, v139
	v_max_i32_e32 v81, v79, v77
	v_min_i32_e32 v82, v82, v125
	v_min_i32_e32 v75, v75, v134
	s_waitcnt lgkmcnt(1)
	v_mfma_f32_32x32x16_bf16 v[18:33], v[66:69], v[38:41], v[18:33]
	v_max_i32_e32 v66, v131, v132
	v_max_i32_e32 v134, v138, v139
	v_min_i32_e32 v77, v79, v77
	v_max_i32_e32 v124, v81, v82
	v_min_i32_e32 v81, v81, v82
	v_min_i32_e32 v67, v126, v66
	v_min_i32_e32 v142, v140, v141
	s_waitcnt lgkmcnt(0)
; #define LAS __attribute__((address_space(3)))
; #define MFMA32(a, b, c) __builtin_amdgcn_mfma_f32_32x32x16_bf16((a), (b), (c), 0, 0, 0)
; __device__ __forceinline__ void route_task(int task, int tl0, const bf16* QP  , const LAS bf16* KHL, LAS unsigned short* EL, LAS float* GL, int lane) {
;     ...
;         for (int kt = 0; kt < 4; ++kt) {
;             f32x16 X;
; #pragma unroll
;             for (int i = 0; i < 16; ++i) X[i] = 8.f;
;             const LAS bf16* khp = KHL + (half * 128 + 32 * kt + r) * 72 + 8 * hi;
; #pragma unroll
;             for (int ks = 0; ks < 4; ++ks) {
;                 const bf16x8 kh = lds8(khp + 16 * ks);
;                 X = MFMA32(kh, qa[half][ks], X);
;             }
;             int grp[16];
; #pragma unroll
;             for (int i = 0; i < 16; ++i) grp[i] = (int)((__float_as_uint(X[i]) | 127u) - (unsigned)(32 * kt + (i & 3) + 8 * (i >> 2)));
;             sort16_desc(grp);
;             if (kt == 0) {
; #pragma unroll
;                 for (int i = 0; i < 16; ++i) cur[i] = grp[i];
;             } else merge16_desc(cur, grp);
	v_mfma_f32_32x32x16_bf16 v[18:33], v[70:73], v[34:37], v[18:33]
	v_min_i32_e32 v68, v130, v67
	v_min_i32_e32 v137, v80, v136
	v_min_i32_e32 v144, v142, v143
	v_min_i32_e32 v125, v124, v75
	v_min_i32_e32 v69, v134, v68
	s_nop 6
	v_bitop3_b32 v21, v21, s42, 35 bitop3:0x56
	v_bitop3_b32 v32, v32, s42, 58 bitop3:0x56
	v_bitop3_b32 v22, v22, s42, 40 bitop3:0x56
	v_bitop3_b32 v26, v26, s42, 48 bitop3:0x56
	v_bitop3_b32 v18, v18, s42, 32 bitop3:0x56
	v_bitop3_b32 v31, v31, s42, 57 bitop3:0x56
	v_bitop3_b32 v23, v23, s42, 41 bitop3:0x56
	v_bitop3_b32 v24, v24, s42, 42 bitop3:0x56
	v_bitop3_b32 v27, v27, s42, 49 bitop3:0x56
	v_bitop3_b32 v28, v28, s42, 50 bitop3:0x56
	v_bitop3_b32 v20, v20, s42, 34 bitop3:0x56
	v_bitop3_b32 v33, v33, s42, 59 bitop3:0x56
	v_bitop3_b32 v25, v25, s42, 43 bitop3:0x56
	v_bitop3_b32 v29, v29, s42, 51 bitop3:0x56
	v_bitop3_b32 v19, v19, s42, 33 bitop3:0x56
	v_bitop3_b32 v30, v30, s42, 56 bitop3:0x56
	v_max_i32_e32 v70, v21, v32
	v_max_i32_e32 v71, v22, v26
	v_max_i32_e32 v73, v18, v31
	v_max_i32_e32 v76, v23, v24
	v_min_i32_e32 v129, v27, v28
	v_min_i32_e32 v131, v20, v33
	v_min_i32_e32 v133, v25, v29
	v_min_i32_e32 v135, v19, v30
	v_min_i32_e32 v23, v23, v24
	v_min_i32_e32 v18, v18, v31
	v_min_i32_e32 v22, v22, v26
	v_min_i32_e32 v21, v21, v32
	v_max_i32_e32 v19, v19, v30
	v_max_i32_e32 v25, v25, v29
	v_max_i32_e32 v20, v20, v33
	v_max_i32_e32 v27, v27, v28
	v_min_i32_e32 v72, v70, v71
	v_min_i32_e32 v79, v73, v76
	v_max_i32_e32 v132, v129, v131
	v_max_i32_e32 v138, v133, v135
	v_max_i32_e32 v24, v23, v18
	v_max_i32_e32 v26, v22, v21
	v_min_i32_e32 v29, v19, v25
	v_min_i32_e32 v28, v20, v27
	v_min_i32_e32 v133, v133, v135
	v_min_i32_e32 v18, v23, v18
	v_min_i32_e32 v21, v22, v21
	v_min_i32_e32 v22, v129, v131
	v_max_i32_e32 v73, v73, v76
	v_max_i32_e32 v19, v19, v25
	v_max_i32_e32 v20, v20, v27
	v_max_i32_e32 v27, v70, v71
	v_min_i32_e32 v82, v72, v79
	v_min_i32_e32 v139, v132, v138
	v_max_i32_e32 v31, v24, v26
	v_max_i32_e32 v30, v29, v28
	v_min_i32_e32 v24, v24, v26
	v_min_i32_e32 v26, v29, v28
	v_max_i32_e32 v29, v72, v79
	v_max_i32_e32 v72, v132, v138
	v_min_i32_e32 v23, v133, v18
	v_min_i32_e32 v129, v21, v22
	v_max_i32_e32 v18, v133, v18
	v_max_i32_e32 v21, v21, v22
	v_min_i32_e32 v25, v73, v19
	v_min_i32_e32 v70, v20, v27
	v_max_i32_e32 v19, v73, v19
	v_max_i32_e32 v20, v20, v27
	v_min_i32_e32 v32, v31, v30
	v_max_i32_e32 v28, v24, v26
	v_min_i32_e32 v79, v29, v72
	v_min_i32_e32 v24, v24, v26
	v_min_i32_e32 v26, v82, v139
	v_max_i32_e32 v131, v23, v129
	v_min_i32_e32 v22, v18, v21
	v_min_i32_e32 v71, v25, v70
	v_max_i32_e32 v25, v25, v70
	v_min_i32_e32 v27, v19, v20
	v_max_i32_e32 v29, v29, v72
	v_max_i32_e32 v30, v31, v30
	v_max_i32_e32 v145, v82, v139
	v_max_i32_e32 v82, v24, v26
	v_max_i32_e32 v133, v131, v22
	v_max_i32_e32 v18, v18, v21
	v_min_i32_e32 v70, v25, v27
	v_min_i32_e32 v31, v29, v30
	v_min_i32_e32 v33, v145, v32
	v_min_i32_e32 v132, v28, v79
	v_max_i32_e32 v135, v82, v133
	v_min_i32_e32 v21, v71, v18
	v_max_i32_e32 v18, v71, v18
	v_min_i32_e32 v71, v70, v31
	v_max_i32_e32 v32, v145, v32
	v_max_i32_e32 v28, v28, v79
	v_max_i32_e32 v138, v33, v132
	v_max_i32_e32 v76, v135, v21
	v_min_i32_e32 v72, v18, v71
	v_min_i32_e32 v73, v32, v28
	v_min_i32_e32 v33, v33, v132
	v_min_i32_e32 v21, v135, v21
	v_max_i32_e32 v18, v18, v71
	v_max_i32_e32 v28, v32, v28
	v_min_i32_e32 v24, v24, v26
	v_min_i32_e32 v22, v131, v22
	v_max_i32_e32 v25, v25, v27
	v_max_i32_e32 v27, v29, v30
	v_max_i32_e32 v139, v138, v76
	v_min_i32_e32 v79, v72, v73
	v_min_i32_e32 v76, v138, v76
	v_max_i32_e32 v132, v33, v21
	v_min_i32_e32 v32, v18, v28
	v_max_i32_e32 v71, v72, v73
	v_max_i32_e32 v26, v24, v22
	v_min_i32_e32 v82, v82, v133
	v_max_i32_e32 v18, v18, v28
	v_max_i32_e32 v28, v70, v31
	v_min_i32_e32 v29, v25, v27
	v_min_i32_e32 v145, v139, v79
	v_max_i32_e32 v135, v76, v132
	v_min_i32_e32 v72, v32, v71
	v_max_i32_e32 v73, v139, v79
	v_max_i32_e32 v131, v26, v82
	v_min_i32_e32 v21, v33, v21
	v_min_i32_e32 v30, v28, v29
	v_min_i32_e32 v138, v145, v135
	v_min_i32_e32 v79, v72, v73
	v_min_i32_e32 v33, v131, v21
	v_min_i32_e32 v76, v76, v132
	v_min_i32_e32 v31, v18, v30
	v_min_i32_e32 v26, v26, v82
	v_min_i32_e32 v22, v24, v22
	v_min_i32_e32 v23, v23, v129
	v_max3_i32 v23, v127, v128, v23
	v_max3_i32 v22, v126, v66, v22
	v_max3_i32 v24, v130, v67, v26
	v_max3_i32 v26, v134, v68, v33
	v_max3_i32 v21, v69, v131, v21
	v_max3_i32 v33, v140, v141, v76
	v_max3_i32 v66, v142, v143, v138
	v_max3_i32 v67, v144, v145, v135
	v_max3_i32 v68, v80, v136, v79
	v_max3_i32 v69, v137, v72, v73
	v_max3_i32 v32, v78, v32, v71
	v_max3_i32 v31, v124, v75, v31
	v_max3_i32 v18, v125, v18, v30
	v_max3_i32 v28, v81, v28, v29
	v_max3_i32 v25, v77, v25, v27
	v_max3_i32 v19, v74, v19, v20
	v_max_i32_e32 v20, v23, v68
	v_min_i32_e32 v23, v23, v68
	v_max_i32_e32 v27, v22, v69
	v_min_i32_e32 v22, v22, v69
	v_max_i32_e32 v29, v24, v32
	v_min_i32_e32 v24, v24, v32
	v_max_i32_e32 v30, v26, v31
	v_min_i32_e32 v26, v26, v31
	v_max_i32_e32 v31, v21, v18
	v_min_i32_e32 v18, v21, v18
	v_max_i32_e32 v21, v33, v28
	v_min_i32_e32 v28, v33, v28
	v_max_i32_e32 v32, v66, v25
	v_min_i32_e32 v25, v66, v25
	v_max_i32_e32 v33, v67, v19
	v_min_i32_e32 v19, v67, v19
	ds_read_b128 v[66:69], v94 offset:27648
	v_max_i32_e32 v70, v20, v31
	v_min_i32_e32 v74, v20, v31
	v_max_i32_e32 v20, v27, v21
	v_min_i32_e32 v75, v27, v21
	v_max_i32_e32 v21, v29, v32
	v_max_i32_e32 v27, v30, v33
	v_max_i32_e32 v127, v70, v21
	v_min_i32_e32 v128, v70, v21
	ds_read_b128 v[70:73], v94 offset:27680
	v_min_i32_e32 v76, v29, v32
	v_min_i32_e32 v77, v30, v33
	v_max_i32_e32 v78, v23, v18
	v_min_i32_e32 v79, v23, v18
	v_max_i32_e32 v80, v22, v28
	v_min_i32_e32 v81, v22, v28
	v_max_i32_e32 v82, v24, v25
	v_min_i32_e32 v124, v24, v25
	v_max_i32_e32 v125, v26, v19
	v_min_i32_e32 v126, v26, v19
	v_max_i32_e32 v129, v20, v27
	v_min_i32_e32 v130, v20, v27
	s_waitcnt lgkmcnt(1)
; #define LAS __attribute__((address_space(3)))
; #define MFMA32(a, b, c) __builtin_amdgcn_mfma_f32_32x32x16_bf16((a), (b), (c), 0, 0, 0)
; __device__ __forceinline__ void route_task(int task, int tl0, const bf16* QP  , const LAS bf16* KHL, LAS unsigned short* EL, LAS float* GL, int lane) {
;     ...
;         for (int kt = 0; kt < 4; ++kt) {
;             f32x16 X;
; #pragma unroll
;             for (int i = 0; i < 16; ++i) X[i] = 8.f;
;             const LAS bf16* khp = KHL + (half * 128 + 32 * kt + r) * 72 + 8 * hi;
; #pragma unroll
;             for (int ks = 0; ks < 4; ++ks) {
;                 const bf16x8 kh = lds8(khp + 16 * ks);
;                 X = MFMA32(kh, qa[half][ks], X);
;             }
;             int grp[16];
; #pragma unroll
;             for (int i = 0; i < 16; ++i) grp[i] = (int)((__float_as_uint(X[i]) | 127u) - (unsigned)(32 * kt + (i & 3) + 8 * (i >> 2)));
;             sort16_desc(grp);
;             if (kt == 0) {
; #pragma unroll
;                 for (int i = 0; i < 16; ++i) cur[i] = grp[i];
;             } else merge16_desc(cur, grp);
	v_mfma_f32_32x32x16_bf16 v[18:33], v[66:69], v[46:49], v[2:17]
	ds_read_b128 v[66:69], v94 offset:27712
	v_max_i32_e32 v131, v74, v76
	v_min_i32_e32 v74, v74, v76
	v_max_i32_e32 v76, v75, v77
	v_min_i32_e32 v75, v75, v77
	v_max_i32_e32 v77, v78, v82
	v_min_i32_e32 v78, v78, v82
	s_waitcnt lgkmcnt(1)
	v_mfma_f32_32x32x16_bf16 v[18:33], v[70:73], v[42:45], v[18:33]
	ds_read_b128 v[70:73], v94 offset:27744
	v_max_i32_e32 v82, v80, v125
	v_min_i32_e32 v80, v80, v125
	v_max_i32_e32 v125, v79, v124
	v_min_i32_e32 v79, v79, v124
	v_max_i32_e32 v124, v81, v126
	v_min_i32_e32 v81, v81, v126
	s_waitcnt lgkmcnt(1)
	v_mfma_f32_32x32x16_bf16 v[18:33], v[66:69], v[38:41], v[18:33]
	v_min_i32_e32 v126, v127, v129
	v_min_i32_e32 v66, v128, v130
	v_min_i32_e32 v67, v131, v76
	v_min_i32_e32 v69, v77, v82
	v_min_i32_e32 v132, v78, v80
	v_min_i32_e32 v133, v125, v124
	v_min_i32_e32 v68, v74, v75
	s_waitcnt lgkmcnt(0)
	v_mfma_f32_32x32x16_bf16 v[18:33], v[70:73], v[34:37], v[18:33]
	v_min_i32_e32 v134, v79, v81
	s_nop 10
	v_and_or_b32 v21, v21, s43, 60
	v_and_or_b32 v32, v32, s43, 37
	v_and_or_b32 v22, v22, s43, 55
	v_and_or_b32 v26, v26, s43, 47
	v_bitop3_b32 v18, v18, s42, 64 bitop3:0x56
	v_and_or_b32 v31, v31, s43, 38
	v_and_or_b32 v23, v23, s43, 54
	v_and_or_b32 v24, v24, s43, 53
	v_and_or_b32 v27, v27, s43, 46
	v_and_or_b32 v28, v28, s43, 45
	v_and_or_b32 v20, v20, s43, 61
	v_and_or_b32 v33, v33, s43, 36
	v_and_or_b32 v25, v25, s43, 52
	v_and_or_b32 v29, v29, s43, 44
	v_and_or_b32 v19, v19, s43, 62
	v_and_or_b32 v30, v30, s43, 39
	v_max_i32_e32 v70, v21, v32
	v_max_i32_e32 v71, v22, v26
	v_max_i32_e32 v73, v18, v31
	v_max_i32_e32 v135, v23, v24
	v_min_i32_e32 v138, v27, v28
	v_min_i32_e32 v139, v20, v33
	v_min_i32_e32 v141, v25, v29
	v_min_i32_e32 v142, v19, v30
	v_min_i32_e32 v23, v23, v24
	v_min_i32_e32 v18, v18, v31
	v_min_i32_e32 v22, v22, v26
	v_min_i32_e32 v21, v21, v32
	v_max_i32_e32 v19, v19, v30
	v_max_i32_e32 v25, v25, v29
	v_max_i32_e32 v20, v20, v33
	v_max_i32_e32 v27, v27, v28
	v_min_i32_e32 v72, v70, v71
	v_min_i32_e32 v136, v73, v135
	v_max_i32_e32 v140, v138, v139
	v_max_i32_e32 v143, v141, v142
	v_max_i32_e32 v24, v23, v18
	v_max_i32_e32 v26, v22, v21
	v_min_i32_e32 v29, v19, v25
	v_min_i32_e32 v28, v20, v27
	v_min_i32_e32 v141, v141, v142
	v_min_i32_e32 v18, v23, v18
	v_min_i32_e32 v21, v22, v21
	v_min_i32_e32 v22, v138, v139
	v_max_i32_e32 v73, v73, v135
	v_max_i32_e32 v19, v19, v25
	v_max_i32_e32 v20, v20, v27
	v_max_i32_e32 v27, v70, v71
	v_min_i32_e32 v137, v72, v136
	v_min_i32_e32 v144, v140, v143
	v_max_i32_e32 v31, v24, v26
	v_max_i32_e32 v30, v29, v28
	v_min_i32_e32 v24, v24, v26
	v_min_i32_e32 v26, v29, v28
	v_max_i32_e32 v29, v72, v136
	v_max_i32_e32 v72, v140, v143
	v_min_i32_e32 v23, v141, v18
	v_min_i32_e32 v138, v21, v22
	v_max_i32_e32 v18, v141, v18
	v_max_i32_e32 v21, v21, v22
	v_min_i32_e32 v25, v73, v19
	v_min_i32_e32 v70, v20, v27
	v_max_i32_e32 v19, v73, v19
	v_max_i32_e32 v20, v20, v27
	v_min_i32_e32 v32, v31, v30
	v_max_i32_e32 v28, v24, v26
	v_min_i32_e32 v136, v29, v72
	v_min_i32_e32 v24, v24, v26
	v_min_i32_e32 v26, v137, v144
	v_max_i32_e32 v139, v23, v138
	v_min_i32_e32 v22, v18, v21
	v_min_i32_e32 v71, v25, v70
	v_max_i32_e32 v25, v25, v70
	v_min_i32_e32 v27, v19, v20
	v_max_i32_e32 v29, v29, v72
	v_max_i32_e32 v30, v31, v30
	v_max_i32_e32 v145, v137, v144
	v_max_i32_e32 v137, v24, v26
	v_max_i32_e32 v141, v139, v22
	v_max_i32_e32 v18, v18, v21
	v_min_i32_e32 v70, v25, v27
	v_min_i32_e32 v31, v29, v30
	v_min_i32_e32 v33, v145, v32
	v_min_i32_e32 v140, v28, v136
	v_max_i32_e32 v142, v137, v141
	v_min_i32_e32 v21, v71, v18
	v_max_i32_e32 v18, v71, v18
	v_min_i32_e32 v71, v70, v31
	v_max_i32_e32 v32, v145, v32
	v_max_i32_e32 v28, v28, v136
	v_max_i32_e32 v143, v33, v140
	v_max_i32_e32 v135, v142, v21
	v_min_i32_e32 v72, v18, v71
	v_min_i32_e32 v73, v32, v28
	v_min_i32_e32 v33, v33, v140
	v_min_i32_e32 v21, v142, v21
	v_max_i32_e32 v18, v18, v71
	v_max_i32_e32 v28, v32, v28
	v_min_i32_e32 v24, v24, v26
	v_min_i32_e32 v22, v139, v22
	v_max_i32_e32 v25, v25, v27
	v_max_i32_e32 v27, v29, v30
	v_max_i32_e32 v144, v143, v135
	v_min_i32_e32 v136, v72, v73
	v_min_i32_e32 v135, v143, v135
	v_max_i32_e32 v140, v33, v21
	v_min_i32_e32 v32, v18, v28
	v_max_i32_e32 v71, v72, v73
	v_max_i32_e32 v26, v24, v22
	v_min_i32_e32 v137, v137, v141
	v_max_i32_e32 v18, v18, v28
	v_max_i32_e32 v28, v70, v31
	v_min_i32_e32 v29, v25, v27
	v_min_i32_e32 v145, v144, v136
	v_max_i32_e32 v142, v135, v140
	v_min_i32_e32 v72, v32, v71
	v_max_i32_e32 v73, v144, v136
	v_max_i32_e32 v139, v26, v137
	v_min_i32_e32 v21, v33, v21
	v_min_i32_e32 v30, v28, v29
	v_min_i32_e32 v143, v145, v142
	v_min_i32_e32 v136, v72, v73
	v_min_i32_e32 v33, v139, v21
	v_max_i32_e32 v21, v139, v21
	v_min_i32_e32 v135, v135, v140
	v_max_i32_e32 v32, v32, v71
	v_min_i32_e32 v31, v18, v30
	v_max_i32_e32 v18, v18, v30
	v_min_i32_e32 v26, v26, v137
	v_min_i32_e32 v22, v24, v22
	v_max_i32_e32 v24, v25, v27
	v_min_i32_e32 v23, v23, v138
	v_max3_i32 v23, v127, v129, v23
	v_max_i32_e32 v22, v126, v22
	v_max3_i32 v25, v128, v130, v26
	v_max_i32_e32 v26, v66, v33
	v_max3_i32 v21, v131, v76, v21
	v_max_i32_e32 v27, v67, v135
	v_max3_i32 v30, v74, v75, v143
	v_max3_i32 v66, v77, v82, v136
	v_max3_i32 v67, v69, v72, v73
	v_max3_i32 v32, v78, v80, v32
	v_max_i32_e32 v31, v132, v31
	v_max3_i32 v18, v125, v124, v18
	v_max3_i32 v28, v133, v28, v29
	v_max3_i32 v24, v79, v81, v24
	v_max3_i32 v33, v68, v145, v142
	v_max3_i32 v19, v134, v19, v20
	v_max_i32_e32 v20, v23, v66
	v_min_i32_e32 v23, v23, v66
	v_max_i32_e32 v29, v22, v67
	v_max_i32_e32 v66, v25, v32
	v_min_i32_e32 v25, v25, v32
	v_max_i32_e32 v32, v26, v31
	v_min_i32_e32 v26, v26, v31
	v_max_i32_e32 v31, v21, v18
	v_min_i32_e32 v18, v21, v18
	v_max_i32_e32 v21, v27, v28
	v_min_i32_e32 v27, v27, v28
	v_max_i32_e32 v28, v30, v24
	v_min_i32_e32 v22, v22, v67
	v_min_i32_e32 v24, v30, v24
	v_max_i32_e32 v30, v33, v19
	v_min_i32_e32 v19, v33, v19
	v_max_i32_e32 v33, v20, v31
	v_min_i32_e32 v74, v20, v31
	v_max_i32_e32 v20, v29, v21
	v_min_i32_e32 v75, v29, v21
	v_max_i32_e32 v21, v66, v28
	v_min_i32_e32 v76, v66, v28
	ds_read_b128 v[66:69], v98
	ds_read_b128 v[70:73], v98 offset:32
	v_max_i32_e32 v28, v32, v30
	v_min_i32_e32 v77, v32, v30
	v_max_i32_e32 v78, v23, v18
	v_min_i32_e32 v79, v23, v18
	v_max_i32_e32 v80, v22, v27
	v_min_i32_e32 v81, v22, v27
	v_max_i32_e32 v82, v25, v24
	v_min_i32_e32 v124, v25, v24
	v_max_i32_e32 v125, v26, v19
	v_min_i32_e32 v126, v26, v19
	v_max_i32_e32 v127, v33, v21
	v_min_i32_e32 v128, v33, v21
	v_max_i32_e32 v129, v20, v28
	v_min_i32_e32 v130, v20, v28
	s_waitcnt lgkmcnt(1)
; #define LAS __attribute__((address_space(3)))
; #define MFMA32(a, b, c) __builtin_amdgcn_mfma_f32_32x32x16_bf16((a), (b), (c), 0, 0, 0)
; __device__ __forceinline__ void route_task(int task, int tl0, const bf16* QP  , const LAS bf16* KHL, LAS unsigned short* EL, LAS float* GL, int lane) {
;     ...
;         for (int kt = 0; kt < 4; ++kt) {
;             f32x16 X;
; #pragma unroll
;             for (int i = 0; i < 16; ++i) X[i] = 8.f;
;             const LAS bf16* khp = KHL + (half * 128 + 32 * kt + r) * 72 + 8 * hi;
; #pragma unroll
;             for (int ks = 0; ks < 4; ++ks) {
;                 const bf16x8 kh = lds8(khp + 16 * ks);
;                 X = MFMA32(kh, qa[half][ks], X);
;             }
;             int grp[16];
; #pragma unroll
;             for (int i = 0; i < 16; ++i) grp[i] = (int)((__float_as_uint(X[i]) | 127u) - (unsigned)(32 * kt + (i & 3) + 8 * (i >> 2)));
;             sort16_desc(grp);
;             if (kt == 0) {
; #pragma unroll
;                 for (int i = 0; i < 16; ++i) cur[i] = grp[i];
;             } else merge16_desc(cur, grp);
	v_mfma_f32_32x32x16_bf16 v[18:33], v[66:69], v[46:49], v[2:17]
	ds_read_b128 v[46:49], v98 offset:64
	v_max_i32_e32 v67, v75, v77
	v_min_i32_e32 v68, v75, v77
	v_max_i32_e32 v75, v80, v125
	v_max_i32_e32 v131, v74, v76
	v_min_i32_e32 v66, v74, v76
	v_max_i32_e32 v69, v78, v82
	s_waitcnt lgkmcnt(1)
	v_mfma_f32_32x32x16_bf16 v[18:33], v[70:73], v[42:45], v[18:33]
	ds_read_b128 v[42:45], v98 offset:96
	v_min_i32_e32 v70, v80, v125
	v_max_i32_e32 v71, v79, v124
	v_min_i32_e32 v72, v79, v124
	v_min_i32_e32 v74, v78, v82
	v_max_i32_e32 v73, v81, v126
	v_min_i32_e32 v76, v81, v126
	s_waitcnt lgkmcnt(1)
	v_mfma_f32_32x32x16_bf16 v[18:33], v[46:49], v[38:41], v[18:33]
	v_min_i32_e32 v77, v127, v129
	v_min_i32_e32 v38, v128, v130
	v_min_i32_e32 v39, v131, v67
	v_min_i32_e32 v40, v66, v68
	v_min_i32_e32 v41, v69, v75
	v_min_i32_e32 v46, v74, v70
	v_min_i32_e32 v47, v71, v73
	s_waitcnt lgkmcnt(0)
	v_mfma_f32_32x32x16_bf16 v[18:33], v[42:45], v[34:37], v[18:33]
	v_min_i32_e32 v48, v72, v76
	s_nop 10
	v_and_or_b32 v25, v25, s43, 20
	v_and_or_b32 v29, v29, s43, 12
	v_and_or_b32 v19, v19, s43, 30
	v_and_or_b32 v30, v30, s43, 7
	v_and_or_b32 v23, v23, s43, 22
	v_and_or_b32 v24, v24, s43, 21
	v_and_or_b32 v18, v18, s43, 31
	v_and_or_b32 v31, v31, s43, 6
	v_and_or_b32 v22, v22, s43, 23
	v_and_or_b32 v26, v26, s43, 15
	v_and_or_b32 v21, v21, s43, 28
	v_and_or_b32 v32, v32, s43, 5
	v_and_or_b32 v27, v27, s43, 14
	v_and_or_b32 v28, v28, s43, 13
	v_and_or_b32 v20, v20, s43, 29
	v_and_or_b32 v33, v33, s43, 4
	v_min_i32_e32 v34, v25, v29
	v_min_i32_e32 v35, v19, v30
	v_min_i32_e32 v37, v23, v24
	v_min_i32_e32 v42, v18, v31
	v_min_i32_e32 v45, v22, v26
	v_min_i32_e32 v49, v21, v32
	v_min_i32_e32 v79, v27, v28
	v_min_i32_e32 v80, v20, v33
	v_max_i32_e32 v18, v18, v31
	v_max_i32_e32 v23, v23, v24
	v_max_i32_e32 v19, v19, v30
	v_max_i32_e32 v25, v25, v29
	v_max_i32_e32 v20, v20, v33
	v_max_i32_e32 v27, v27, v28
	v_max_i32_e32 v21, v21, v32
	v_max_i32_e32 v22, v22, v26
	v_max_i32_e32 v24, v18, v23
	v_max_i32_e32 v29, v19, v25
	v_max_i32_e32 v28, v20, v27
	v_max_i32_e32 v26, v21, v22
	v_min_i32_e32 v30, v24, v29
	v_min_i32_e32 v31, v28, v26
	v_min_i32_e32 v43, v37, v42
	v_min_i32_e32 v32, v30, v31
	v_max_i32_e32 v30, v30, v31
	v_min_i32_e32 v21, v21, v22
	v_min_i32_e32 v18, v18, v23
	v_max_i32_e32 v23, v79, v80
	v_max_i32_e32 v31, v34, v35
	v_max_i32_e32 v37, v37, v42
	v_max_i32_e32 v42, v45, v49
	v_min_i32_e32 v19, v19, v25
	v_min_i32_e32 v20, v20, v27
	v_min_i32_e32 v36, v34, v35
	v_min_i32_e32 v78, v45, v49
	v_min_i32_e32 v81, v79, v80
	v_max_i32_e32 v22, v21, v18
	v_max_i32_e32 v45, v37, v42
	v_max_i32_e32 v25, v19, v20
	v_min_i32_e32 v18, v21, v18
	v_min_i32_e32 v21, v23, v31
	v_min_i32_e32 v44, v36, v43
	v_min_i32_e32 v82, v78, v81
	v_max_i32_e32 v33, v36, v43
	v_max_i32_e32 v36, v78, v81
	v_max_i32_e32 v24, v24, v29
	v_max_i32_e32 v26, v28, v26
	v_max_i32_e32 v34, v23, v31
	v_max_i32_e32 v27, v45, v25
	v_max_i32_e32 v23, v18, v21
	v_min_i32_e32 v25, v45, v25
	v_min_i32_e32 v37, v37, v42
	v_min_i32_e32 v19, v19, v20
	v_max_i32_e32 v43, v33, v36
	v_min_i32_e32 v28, v24, v26
	v_max_i32_e32 v35, v22, v34
	v_max_i32_e32 v31, v23, v25
	v_max_i32_e32 v20, v37, v19
	v_min_i32_e32 v23, v23, v25
	v_min_i32_e32 v19, v37, v19
	v_min_i32_e32 v18, v18, v21
	v_max_i32_e32 v25, v44, v82
	v_min_i32_e32 v33, v33, v36
	v_min_i32_e32 v29, v30, v28
	v_min_i32_e32 v49, v35, v27
	v_min_i32_e32 v22, v22, v34
	v_max_i32_e32 v21, v19, v18
	v_max_i32_e32 v36, v25, v33
	v_max_i32_e32 v78, v32, v43
	v_min_i32_e32 v79, v29, v49
	v_max_i32_e32 v34, v20, v22
	v_min_i32_e32 v20, v20, v22
	v_max_i32_e32 v37, v21, v36
	v_min_i32_e32 v32, v32, v43
	v_max_i32_e32 v80, v78, v79
	v_max_i32_e32 v42, v31, v34
	v_min_i32_e32 v78, v78, v79
	v_min_i32_e32 v31, v31, v34
	v_max_i32_e32 v22, v23, v20
	v_max_i32_e32 v43, v37, v32
	v_min_i32_e32 v18, v19, v18
	v_min_i32_e32 v19, v25, v33
	v_min_i32_e32 v20, v23, v20
	v_min_i32_e32 v23, v37, v32
	v_max_i32_e32 v28, v30, v28
	v_max_i32_e32 v27, v35, v27
	v_min_i32_e32 v124, v44, v82
	v_min_i32_e32 v45, v80, v42
	v_max_i32_e32 v34, v78, v31
	v_max_i32_e32 v44, v22, v43
	v_min_i32_e32 v31, v78, v31
	v_max_i32_e32 v25, v18, v19
	v_min_i32_e32 v21, v21, v36
	v_min_i32_e32 v32, v20, v23
	v_max_i32_e32 v29, v29, v49
	v_min_i32_e32 v30, v28, v27
	v_min_i32_e32 v22, v22, v43
	v_max_i32_e32 v20, v20, v23
	v_min_i32_e32 v79, v45, v34
	v_max_i32_e32 v78, v44, v31
	v_max_i32_e32 v33, v25, v21
	v_max_i32_e32 v37, v80, v42
	v_min_i32_e32 v35, v29, v30
	v_min_i32_e32 v31, v44, v31
	v_max_i32_e32 v23, v22, v20
	v_min_i32_e32 v81, v79, v78
	v_max_i32_e32 v36, v33, v32
	v_max_i32_e32 v42, v37, v35
	v_min_i32_e32 v21, v25, v21
	v_max_i32_e32 v25, v45, v34
	v_min_i32_e32 v43, v31, v23
	v_max_i32_e32 v27, v28, v27
	v_min_i32_e32 v18, v18, v19
	v_min_i32_e32 v20, v22, v20
	v_min_i32_e32 v32, v33, v32
	v_min_i32_e32 v33, v37, v35
	v_max3_i32 v124, v127, v129, v124
	v_max3_i32 v69, v69, v75, v81
	v_max3_i32 v36, v131, v67, v36
	v_max3_i32 v42, v71, v73, v42
	v_max3_i32 v21, v128, v130, v21
	v_max3_i32 v25, v74, v70, v25
	v_max3_i32 v43, v66, v68, v43
	v_max3_i32 v27, v72, v76, v27
	v_max_i32_e32 v18, v77, v18
	v_max3_i32 v19, v41, v79, v78
	v_max_i32_e32 v20, v39, v20
	v_max3_i32 v22, v47, v29, v30
	v_max_i32_e32 v32, v38, v32
	v_max_i32_e32 v33, v46, v33
	v_max3_i32 v23, v40, v31, v23
	v_max3_i32 v24, v48, v24, v26
	v_min_i32_e32 v49, v36, v42
	v_min_i32_e32 v34, v21, v25
	v_min_i32_e32 v41, v18, v19
	v_min_i32_e32 v29, v20, v22
	v_min_i32_e32 v26, v23, v24
	v_max_i32_e32 v39, v124, v69
	v_max_i32_e32 v36, v36, v42
	v_max_i32_e32 v21, v21, v25
	v_max_i32_e32 v25, v43, v27
; __device__ __forceinline__ void route_task(int task, int tl0, const bf16* QP  , const LAS bf16* KHL, LAS unsigned short* EL, LAS float* GL, int lane) {
;     ...
;             } else merge16_desc(cur, grp);
;         }
;         { const unsigned h4 = 4u * (unsigned)hi;
; #pragma unroll
;           for (int i = 0; i < 16; ++i) cur[i] -= (int)h4; }
;         int oth[16];
; #pragma unroll
;         for (int i = 0; i < 16; ++i) oth[i] = __shfl_xor(cur[i], 32);
;         merge16_desc(cur, oth);
; #pragma unroll
;         for (int i = 0; i < 16; ++i) top[half][i] = cur[i];
;     }
;     unsigned P1[4], P2[4];
; #pragma unroll
;     for (int q = 0; q < 4; ++q) { P1[q] = 0u; P2[q] = 0u;
; #pragma unroll
;         for (int s = 0; s < 4; ++s) { P1[q] |= (127u - ((unsigned)top[0][4 * q + s] & 127u)) << (8 * s); P2[q] |= (127u - ((unsigned)top[1][4 * q + s] & 127u)) << (8 * s); } }
	v_max_i32_e32 v18, v18, v19
	v_max_i32_e32 v19, v20, v22
	v_max_i32_e32 v22, v32, v33
	v_max_i32_e32 v23, v23, v24
	v_min_i32_e32 v28, v43, v27
	v_max_i32_e32 v40, v39, v36
	v_max_i32_e32 v27, v21, v25
	v_max_i32_e32 v20, v18, v19
	v_max_i32_e32 v24, v22, v23
	v_min_i32_e32 v35, v32, v33
	v_max_i32_e32 v42, v40, v27
	v_max_i32_e32 v32, v20, v24
	v_min_i32_e32 v27, v40, v27
	v_min_i32_e32 v20, v20, v24
	v_max_i32_e32 v24, v27, v20
	v_min_i32_e32 v20, v27, v20
	v_min_i32_e32 v27, v39, v36
	v_min_i32_e32 v21, v21, v25
	v_min_i32_e32 v18, v18, v19
	v_min_i32_e32 v19, v22, v23
	v_min_i32_e32 v75, v124, v69
	v_max_i32_e32 v25, v27, v21
	v_max_i32_e32 v22, v18, v19
	v_min_i32_e32 v21, v27, v21
	v_min_i32_e32 v18, v18, v19
	v_min_i32_e32 v44, v34, v28
	v_min_i32_e32 v31, v35, v26
	v_max_i32_e32 v23, v25, v22
	v_min_i32_e32 v22, v25, v22
	v_max_i32_e32 v19, v21, v18
	v_min_i32_e32 v18, v21, v18
	v_max_i32_e32 v21, v75, v49
	v_max_i32_e32 v25, v34, v28
	v_max_i32_e32 v28, v41, v29
	v_max_i32_e32 v26, v35, v26
	v_min_i32_e32 v67, v75, v49
	v_min_i32_e32 v30, v41, v29
	v_max_i32_e32 v27, v21, v25
	v_min_i32_e32 v21, v21, v25
	v_min_i32_e32 v25, v28, v26
	v_min_i32_e32 v45, v67, v44
	v_min_i32_e32 v37, v30, v31
	v_max_i32_e32 v29, v28, v26
	v_max_i32_e32 v26, v21, v25
	v_min_i32_e32 v21, v21, v25
	v_max_i32_e32 v25, v67, v44
	v_max_i32_e32 v28, v30, v31
	v_min_i32_e32 v38, v45, v37
	v_max_i32_e32 v33, v42, v32
	v_min_i32_e32 v32, v42, v32
	v_max_i32_e32 v34, v27, v29
	v_min_i32_e32 v27, v27, v29
	v_max_i32_e32 v29, v25, v28
	v_min_i32_e32 v25, v25, v28
	v_max_i32_e32 v28, v45, v37
	v_sub_u32_e32 v30, v33, v87
	v_sub_u32_e32 v31, v32, v87
	v_sub_u32_e32 v24, v24, v87
	v_sub_u32_e32 v20, v20, v87
	v_sub_u32_e32 v23, v23, v87
	v_sub_u32_e32 v22, v22, v87
	v_sub_u32_e32 v19, v19, v87
	v_sub_u32_e32 v18, v18, v87
	v_sub_u32_e32 v32, v34, v87
	v_sub_u32_e32 v27, v27, v87
	v_sub_u32_e32 v26, v26, v87
	v_sub_u32_e32 v21, v21, v87
	v_sub_u32_e32 v29, v29, v87
	v_sub_u32_e32 v25, v25, v87
	v_sub_u32_e32 v28, v28, v87
	v_sub_u32_e32 v33, v38, v87
	ds_bpermute_b32 v34, v123, v30
	ds_bpermute_b32 v35, v123, v31
	ds_bpermute_b32 v36, v123, v24
	ds_bpermute_b32 v37, v123, v20
	ds_bpermute_b32 v38, v123, v23
	ds_bpermute_b32 v39, v123, v22
	ds_bpermute_b32 v40, v123, v19
	ds_bpermute_b32 v41, v123, v18
	ds_bpermute_b32 v42, v123, v32
	ds_bpermute_b32 v43, v123, v27
	ds_bpermute_b32 v44, v123, v26
	ds_bpermute_b32 v45, v123, v33
	ds_bpermute_b32 v46, v123, v28
	ds_bpermute_b32 v47, v123, v25
	ds_bpermute_b32 v48, v123, v29
	ds_bpermute_b32 v49, v123, v21
	s_waitcnt lgkmcnt(4)
	v_max_i32_e32 v30, v30, v45
	s_waitcnt lgkmcnt(3)
	v_max_i32_e32 v31, v31, v46
	s_waitcnt lgkmcnt(2)
	v_max_i32_e32 v24, v24, v47
	s_waitcnt lgkmcnt(1)
	v_max_i32_e32 v20, v20, v48
	s_waitcnt lgkmcnt(0)
	v_max_i32_e32 v23, v23, v49
	v_max_i32_e32 v22, v22, v44
	v_max_i32_e32 v19, v19, v43
	v_max_i32_e32 v18, v18, v42
	v_max_i32_e32 v32, v32, v41
	v_max_i32_e32 v27, v27, v40
	v_max_i32_e32 v26, v26, v39
	v_max_i32_e32 v21, v21, v38
	v_max_i32_e32 v29, v29, v37
	v_max_i32_e32 v25, v25, v36
	v_max_i32_e32 v28, v28, v35
	v_max_i32_e32 v33, v33, v34
	v_max_i32_e32 v34, v30, v32
	v_min_i32_e32 v30, v30, v32
	v_max_i32_e32 v32, v31, v27
	v_min_i32_e32 v27, v31, v27
	v_max_i32_e32 v31, v24, v26
	v_min_i32_e32 v24, v24, v26
	v_max_i32_e32 v26, v20, v21
	v_min_i32_e32 v20, v20, v21
	v_max_i32_e32 v21, v23, v29
	v_min_i32_e32 v23, v23, v29
	v_max_i32_e32 v29, v22, v25
	v_min_i32_e32 v22, v22, v25
	v_max_i32_e32 v25, v19, v28
	v_min_i32_e32 v19, v19, v28
	v_max_i32_e32 v28, v18, v33
	v_min_i32_e32 v18, v18, v33
	v_max_i32_e32 v33, v34, v21
	v_min_i32_e32 v21, v34, v21
	v_max_i32_e32 v34, v32, v29
	v_min_i32_e32 v29, v32, v29
	v_max_i32_e32 v32, v31, v25
	v_min_i32_e32 v25, v31, v25
	v_max_i32_e32 v31, v26, v28
	v_min_i32_e32 v26, v26, v28
	v_max_i32_e32 v28, v30, v23
	v_min_i32_e32 v23, v30, v23
	v_max_i32_e32 v30, v27, v22
	v_min_i32_e32 v22, v27, v22
	v_max_i32_e32 v27, v24, v19
	v_min_i32_e32 v19, v24, v19
	v_max_i32_e32 v24, v20, v18
	v_min_i32_e32 v18, v20, v18
	v_max_i32_e32 v20, v33, v32
	v_min_i32_e32 v32, v33, v32
	v_max_i32_e32 v33, v34, v31
	v_min_i32_e32 v31, v34, v31
	v_max_i32_e32 v34, v21, v25
	v_min_i32_e32 v21, v21, v25
	v_max_i32_e32 v25, v29, v26
	v_min_i32_e32 v29, v29, v26
	v_max_i32_e32 v35, v28, v27
	v_min_i32_e32 v27, v28, v27
	v_max_i32_e32 v28, v30, v24
	v_min_i32_e32 v24, v30, v24
	v_max_i32_e32 v30, v23, v19
	v_min_i32_e32 v19, v23, v19
	v_max_i32_e32 v23, v22, v18
	v_min_i32_e32 v18, v22, v18
	v_max_i32_e32 v26, v20, v33
	v_min_i32_e32 v33, v20, v33
	v_lshlrev_b32_e32 v20, 8, v65
	v_lshlrev_b32_e32 v22, 16, v64
	v_max_i32_e32 v36, v32, v31
	v_max_i32_e32 v40, v19, v18
	v_min_i32_e32 v41, v19, v18
	v_and_b32_e32 v18, 0x7f, v63
	v_and_b32_e32 v20, 0x7f00, v20
	v_and_b32_e32 v22, 0x7f0000, v22
	v_max_i32_e32 v37, v21, v29
	v_min_i32_e32 v29, v21, v29
	v_lshlrev_b32_e32 v21, 8, v33
	v_or3_b32 v18, v20, v18, v22
	v_lshlrev_b32_e32 v20, 16, v36
	v_and_b32_e32 v19, 0x7f, v26
	v_and_b32_e32 v21, 0x7f00, v21
	v_and_b32_e32 v20, 0x7f0000, v20
	v_or3_b32 v20, v21, v19, v20
	v_lshlrev_b32_e32 v19, 24, v62
	v_min_i32_e32 v31, v32, v31
	v_and_b32_e32 v19, 0x7f000000, v19
	v_bitop3_b32 v19, v18, s68, v19 bitop3:0x36
	v_lshlrev_b32_e32 v18, 24, v31
	v_max_i32_e32 v38, v35, v28
	v_min_i32_e32 v28, v35, v28
	v_max_i32_e32 v35, v27, v24
	v_min_i32_e32 v27, v27, v24
	v_and_b32_e32 v18, 0x7f000000, v18
	v_lshlrev_b32_e32 v22, 8, v60
	v_lshlrev_b32_e32 v24, 16, v59
	v_max_i32_e32 v32, v34, v25
	v_min_i32_e32 v34, v34, v25
	v_bitop3_b32 v18, v20, s68, v18 bitop3:0x36
	v_and_b32_e32 v20, 0x7f, v61
; __device__ __forceinline__ void route_task(int task, int tl0, const bf16* QP  , const LAS bf16* KHL, LAS unsigned short* EL, LAS float* GL, int lane) {
;     ...
;     unsigned P1[4], P2[4];
; #pragma unroll
;     for (int q = 0; q < 4; ++q) { P1[q] = 0u; P2[q] = 0u;
; #pragma unroll
;         for (int s = 0; s < 4; ++s) { P1[q] |= (127u - ((unsigned)top[0][4 * q + s] & 127u)) << (8 * s); P2[q] |= (127u - ((unsigned)top[1][4 * q + s] & 127u)) << (8 * s); } }
;     int bk[16];
;     {
;         int hi2 = hi; asm volatile("" : "+v"(hi2));
;         const bool h1 = hi2 != 0;
;         constexpr int A1[16] = {1, 1, 1, 1, 1, 1, 1, 1, 2, 2, 2, 2, 2, 3, 3, 3}, B1[16] = {0, 1, 2, 3, 4, 5, 6, 7, 0, 1, 2, 3, 4, 0, 1, 2};
; #pragma unroll
;         for (int i = 0; i < 16; ++i) { const float ta = __int_as_float(h1 ? top[0][A1[i]] : top[0][0]), tb = __int_as_float(h1 ? top[1][B1[i]] : top[1][i]); const unsigned code = h1 ? (unsigned)(A1[i] * 16 + B1[i]) : (unsigned)i;
;             bk[i] = (int)((__float_as_uint(ta + tb) | 255u) - code); }
;         sort16_desc(bk);
	v_and_b32_e32 v22, 0x7f00, v22
	v_and_b32_e32 v24, 0x7f0000, v24
	v_max_i32_e32 v39, v30, v23
	v_min_i32_e32 v30, v30, v23
	v_lshlrev_b32_e32 v23, 8, v34
	v_or3_b32 v20, v22, v20, v24
	v_lshlrev_b32_e32 v22, 16, v37
	v_and_b32_e32 v21, 0x7f, v32
	v_and_b32_e32 v23, 0x7f00, v23
	v_and_b32_e32 v22, 0x7f0000, v22
	v_or3_b32 v22, v23, v21, v22
	v_lshlrev_b32_e32 v21, 24, v57
	v_and_b32_e32 v21, 0x7f000000, v21
	v_bitop3_b32 v21, v20, s68, v21 bitop3:0x36
	v_lshlrev_b32_e32 v20, 24, v29
	v_and_b32_e32 v20, 0x7f000000, v20
	v_lshlrev_b32_e32 v24, 8, v58
	v_lshlrev_b32_e32 v42, 16, v56
	v_bitop3_b32 v20, v22, s68, v20 bitop3:0x36
	v_and_b32_e32 v22, 0x7f, v55
	v_and_b32_e32 v24, 0x7f00, v24
	v_and_b32_e32 v42, 0x7f0000, v42
	v_lshlrev_b32_e32 v25, 8, v28
	v_or3_b32 v22, v24, v22, v42
	v_lshlrev_b32_e32 v24, 16, v35
	v_and_b32_e32 v23, 0x7f, v38
	v_and_b32_e32 v25, 0x7f00, v25
	v_and_b32_e32 v24, 0x7f0000, v24
	v_or3_b32 v24, v25, v23, v24
	v_lshlrev_b32_e32 v23, 24, v54
	v_and_b32_e32 v23, 0x7f000000, v23
	v_bitop3_b32 v23, v22, s68, v23 bitop3:0x36
	v_lshlrev_b32_e32 v22, 24, v27
	v_and_b32_e32 v22, 0x7f000000, v22
	v_lshlrev_b32_e32 v42, 8, v52
	v_lshlrev_b32_e32 v44, 16, v51
	v_bitop3_b32 v22, v24, s68, v22 bitop3:0x36
	v_and_b32_e32 v24, 0x7f, v53
	v_and_b32_e32 v42, 0x7f00, v42
	v_and_b32_e32 v44, 0x7f0000, v44
	v_lshlrev_b32_e32 v43, 8, v30
	v_or3_b32 v24, v42, v24, v44
	v_lshlrev_b32_e32 v42, 16, v40
	v_and_b32_e32 v25, 0x7f, v39
	v_and_b32_e32 v43, 0x7f00, v43
	v_and_b32_e32 v42, 0x7f0000, v42
	v_or3_b32 v42, v43, v25, v42
	v_lshlrev_b32_e32 v25, 24, v50
	v_and_b32_e32 v25, 0x7f000000, v25
	v_bitop3_b32 v25, v24, s68, v25 bitop3:0x36
	v_lshlrev_b32_e32 v24, 24, v41
	v_and_b32_e32 v24, 0x7f000000, v24
	v_bitop3_b32 v24, v42, s68, v24 bitop3:0x36
	v_mov_b32_e32 v42, v86
	v_add_f32_e32 v55, v55, v26
	v_cmp_eq_u32_e32 vcc, 0, v42
	v_add_f32_e32 v56, v56, v26
	v_add_f32_e32 v54, v54, v26
	v_cndmask_b32_e32 v42, v65, v63, vcc
	v_add_f32_e32 v44, v42, v26
	v_cndmask_b32_e64 v43, -16, 0, vcc
	v_or_b32_e32 v44, 0xff, v44
	v_add_f32_e32 v45, v42, v33
	v_add_u32_e32 v43, v44, v43
	v_cndmask_b32_e64 v44, v99, -1, vcc
	v_or_b32_e32 v45, 0xff, v45
	v_add_f32_e32 v46, v42, v36
	v_add_u32_e32 v44, v45, v44
	v_cndmask_b32_e64 v45, v100, -2, vcc
	v_or_b32_e32 v46, 0xff, v46
	v_add_f32_e32 v47, v42, v31
	v_add_u32_e32 v45, v46, v45
	v_cndmask_b32_e64 v46, v101, -3, vcc
	v_or_b32_e32 v47, 0xff, v47
	v_add_f32_e32 v48, v42, v32
	v_add_u32_e32 v46, v47, v46
	v_cndmask_b32_e64 v47, v102, -4, vcc
	v_or_b32_e32 v48, 0xff, v48
	v_add_f32_e32 v34, v42, v34
	v_add_f32_e32 v37, v42, v37
	v_add_f32_e32 v29, v42, v29
	v_cndmask_b32_e32 v42, v64, v63, vcc
	v_cndmask_b32_e32 v32, v32, v39, vcc
	v_add_u32_e32 v47, v48, v47
	v_cndmask_b32_e64 v48, v103, -5, vcc
	v_or_b32_e32 v34, 0xff, v34
	v_add_f32_e32 v32, v42, v32
	v_add_u32_e32 v34, v34, v48
	v_cndmask_b32_e64 v48, v104, -6, vcc
	v_or_b32_e32 v37, 0xff, v37
	v_cndmask_b32_e32 v38, v26, v38, vcc
	v_cndmask_b32_e64 v39, v116, -12, vcc
	v_or_b32_e32 v32, 0xff, v32
	v_add_u32_e32 v37, v37, v48
	v_cndmask_b32_e64 v48, v105, -7, vcc
	v_or_b32_e32 v29, 0xff, v29
	v_add_f32_e32 v38, v42, v38
	v_cndmask_b32_e32 v28, v33, v28, vcc
	v_add_u32_e32 v32, v32, v39
	v_cndmask_b32_e32 v39, v62, v63, vcc
	v_cndmask_b32_e32 v30, v26, v30, vcc
	v_add_u32_e32 v29, v29, v48
	v_cndmask_b32_e64 v48, v106, -8, vcc
	v_or_b32_e32 v38, 0xff, v38
	v_add_f32_e32 v28, v42, v28
	v_cndmask_b32_e32 v35, v36, v35, vcc
	v_cndmask_b32_e32 v27, v31, v27, vcc
	v_add_f32_e32 v30, v39, v30
	v_cndmask_b32_e32 v40, v33, v40, vcc
	v_add_u32_e32 v38, v38, v48
	v_cndmask_b32_e64 v48, v107, -9, vcc
	v_or_b32_e32 v28, 0xff, v28
	v_add_f32_e32 v35, v42, v35
	v_add_f32_e32 v27, v42, v27
	v_cndmask_b32_e64 v42, v117, -13, vcc
	v_or_b32_e32 v30, 0xff, v30
	v_add_f32_e32 v40, v39, v40
	v_cndmask_b32_e32 v41, v36, v41, vcc
	v_add_u32_e32 v28, v28, v48
	v_cndmask_b32_e64 v48, v114, -10, vcc
	v_or_b32_e32 v35, 0xff, v35
	v_add_u32_e32 v30, v30, v42
	v_cndmask_b32_e64 v42, v118, -14, vcc
	v_or_b32_e32 v40, 0xff, v40
	v_add_f32_e32 v39, v39, v41
	v_add_u32_e32 v35, v35, v48
	v_cndmask_b32_e64 v48, v115, -11, vcc
	v_or_b32_e32 v27, 0xff, v27
	v_add_u32_e32 v40, v40, v42
	v_cndmask_b32_e64 v42, v119, -15, vcc
	v_or_b32_e32 v39, 0xff, v39
	v_add_u32_e32 v27, v27, v48
	v_add_u32_e32 v39, v39, v42
	v_max_i32_e32 v41, v43, v30
	v_min_i32_e32 v30, v43, v30
	v_max_i32_e32 v42, v44, v32
	v_min_i32_e32 v32, v44, v32
	v_max_i32_e32 v43, v45, v39
	v_min_i32_e32 v39, v45, v39
	v_max_i32_e32 v44, v46, v40
	v_min_i32_e32 v40, v46, v40
	v_max_i32_e32 v45, v47, v38
	v_min_i32_e32 v38, v47, v38
	v_max_i32_e32 v46, v34, v37
	v_min_i32_e32 v34, v34, v37
	v_max_i32_e32 v37, v29, v27
	v_min_i32_e32 v27, v29, v27
	v_max_i32_e32 v29, v28, v35
	v_min_i32_e32 v28, v28, v35
	v_max_i32_e32 v35, v41, v46
	v_min_i32_e32 v41, v41, v46
	v_max_i32_e32 v46, v42, v37
	v_min_i32_e32 v37, v42, v37
	v_max_i32_e32 v42, v43, v29
	v_min_i32_e32 v29, v43, v29
	v_max_i32_e32 v43, v44, v45
	v_min_i32_e32 v44, v44, v45
	v_max_i32_e32 v45, v34, v30
	v_min_i32_e32 v30, v34, v30
	v_max_i32_e32 v34, v38, v40
	v_min_i32_e32 v38, v38, v40
	v_max_i32_e32 v40, v28, v39
	v_min_i32_e32 v28, v28, v39
	v_max_i32_e32 v39, v27, v32
	v_min_i32_e32 v27, v27, v32
	v_max_i32_e32 v32, v35, v46
	v_min_i32_e32 v35, v35, v46
	v_max_i32_e32 v46, v42, v43
	v_min_i32_e32 v42, v42, v43
	v_max_i32_e32 v43, v44, v41
	v_min_i32_e32 v41, v44, v41
	v_max_i32_e32 v44, v45, v34
	v_min_i32_e32 v34, v45, v34
	v_max_i32_e32 v45, v37, v29
	v_min_i32_e32 v29, v37, v29
	v_max_i32_e32 v37, v40, v39
	v_min_i32_e32 v39, v40, v39
	v_max_i32_e32 v40, v27, v30
; #define CAND(a, b) (int)((__float_as_uint(__int_as_float(top[0][a]) + __int_as_float(top[1][b])) | 255u) - (unsigned)((a) * 16 + (b)))
; __device__ __forceinline__ void route_task(int task, int tl0, const bf16* QP  , const LAS bf16* KHL, LAS unsigned short* EL, LAS float* GL, int lane) {
;     ...
;         sort16_desc(bk);
;         int oth[16];
; #pragma unroll
;         for (int i = 0; i < 16; ++i) oth[i] = __shfl_xor(bk[i], 32);
;         merge16_desc(bk, oth);
;     }
;     ...
;     {
;         int gk[16];
;         gk[0] = CAND(3, 3); gk[1] = CAND(4, 0); gk[2] = CAND(4, 1); gk[3] = CAND(4, 2); gk[4] = CAND(5, 0); gk[5] = CAND(5, 1); gk[6] = CAND(6, 0); gk[7] = CAND(6, 1);
;         gk[8] = CAND(7, 0); gk[9] = CAND(7, 1); gk[10] = CAND(8, 0); gk[11] = CAND(9, 0); gk[12] = CAND(10, 0); gk[13] = CAND(11, 0); gk[14] = CAND(12, 0); gk[15] = CAND(13, 0);
;         sort16_desc(gk);
	v_min_i32_e32 v27, v27, v30
	v_max_i32_e32 v30, v38, v28
	v_min_i32_e32 v28, v38, v28
	v_max_i32_e32 v38, v32, v46
	v_min_i32_e32 v32, v32, v46
	v_max_i32_e32 v46, v35, v42
	v_min_i32_e32 v35, v35, v42
	v_max_i32_e32 v42, v43, v37
	v_min_i32_e32 v37, v43, v37
	v_max_i32_e32 v43, v41, v39
	v_min_i32_e32 v39, v41, v39
	v_max_i32_e32 v41, v44, v45
	v_min_i32_e32 v44, v44, v45
	v_max_i32_e32 v45, v34, v29
	v_min_i32_e32 v29, v34, v29
	v_max_i32_e32 v34, v40, v30
	v_min_i32_e32 v30, v40, v30
	v_max_i32_e32 v40, v27, v28
	v_min_i32_e32 v27, v27, v28
	v_max_i32_e32 v28, v46, v32
	v_min_i32_e32 v32, v46, v32
	v_max_i32_e32 v46, v35, v34
	v_min_i32_e32 v34, v35, v34
	v_max_i32_e32 v35, v42, v41
	v_min_i32_e32 v41, v42, v41
	v_max_i32_e32 v42, v43, v44
	v_min_i32_e32 v43, v43, v44
	v_max_i32_e32 v44, v45, v37
	v_min_i32_e32 v37, v45, v37
	v_max_i32_e32 v45, v29, v39
	v_min_i32_e32 v29, v29, v39
	v_max_i32_e32 v39, v40, v30
	v_min_i32_e32 v30, v40, v30
	v_max_i32_e32 v40, v28, v35
	v_min_i32_e32 v28, v28, v35
	v_max_i32_e32 v35, v32, v41
	v_min_i32_e32 v32, v32, v41
	v_max_i32_e32 v41, v42, v44
	v_min_i32_e32 v42, v42, v44
	v_max_i32_e32 v44, v43, v37
	v_min_i32_e32 v37, v43, v37
	v_max_i32_e32 v43, v45, v39
	v_min_i32_e32 v39, v45, v39
	v_max_i32_e32 v45, v29, v30
	v_min_i32_e32 v29, v29, v30
	v_max_i32_e32 v30, v35, v28
	v_min_i32_e32 v28, v35, v28
	v_max_i32_e32 v35, v46, v32
	v_min_i32_e32 v32, v46, v32
	v_max_i32_e32 v46, v43, v34
	v_min_i32_e32 v34, v43, v34
	v_max_i32_e32 v43, v45, v39
	v_min_i32_e32 v39, v45, v39
	v_max_i32_e32 v45, v35, v41
	v_min_i32_e32 v35, v35, v41
	v_max_i32_e32 v41, v32, v42
	v_min_i32_e32 v32, v32, v42
	v_max_i32_e32 v42, v44, v46
	v_min_i32_e32 v44, v44, v46
	v_max_i32_e32 v46, v37, v34
	v_min_i32_e32 v34, v37, v34
	v_max_i32_e32 v37, v45, v28
	v_min_i32_e32 v28, v45, v28
	v_max_i32_e32 v45, v35, v41
	v_min_i32_e32 v35, v35, v41
	v_max_i32_e32 v41, v42, v32
	v_min_i32_e32 v32, v42, v32
	v_max_i32_e32 v42, v44, v46
	v_min_i32_e32 v44, v44, v46
	v_max_i32_e32 v46, v43, v34
	v_min_i32_e32 v34, v43, v34
	v_max_i32_e32 v43, v35, v41
	v_min_i32_e32 v35, v35, v41
	v_max_i32_e32 v41, v32, v42
	v_min_i32_e32 v32, v32, v42
	ds_bpermute_b32 v67, v123, v41
	ds_bpermute_b32 v68, v123, v32
	ds_bpermute_b32 v69, v123, v44
	ds_bpermute_b32 v64, v123, v45
	ds_bpermute_b32 v65, v123, v43
	ds_bpermute_b32 v66, v123, v35
	s_waitcnt lgkmcnt(4)
	v_max_i32_e32 v43, v43, v68
	s_waitcnt lgkmcnt(3)
	v_max_i32_e32 v45, v45, v69
	v_max_i32_e32 v35, v35, v67
	v_add_f32_e32 v31, v62, v31
	v_add_f32_e32 v62, v61, v26
	v_add_f32_e32 v67, v61, v33
	v_add_f32_e32 v36, v61, v36
	v_add_f32_e32 v61, v60, v26
	v_add_f32_e32 v60, v60, v33
	v_add_f32_e32 v68, v59, v26
	v_add_f32_e32 v59, v59, v33
	v_add_f32_e32 v69, v57, v26
	v_add_f32_e32 v33, v57, v33
	v_add_f32_e32 v57, v58, v26
	v_add_f32_e32 v53, v53, v26
	v_add_f32_e32 v52, v52, v26
	ds_bpermute_b32 v70, v123, v27
	v_or_b32_e32 v31, 0xff, v31
	v_or_b32_e32 v62, 0xff, v62
	v_or_b32_e32 v67, 0xff, v67
	v_or_b32_e32 v36, 0xff, v36
	v_or_b32_e32 v61, 0xff, v61
	v_or_b32_e32 v60, 0xff, v60
	v_or_b32_e32 v68, 0xff, v68
	v_or_b32_e32 v59, 0xff, v59
	v_or_b32_e32 v69, 0xff, v69
	v_or_b32_e32 v33, 0xff, v33
	v_or_b32_e32 v55, 0xff, v55
	v_or_b32_e32 v57, 0xff, v57
	v_or_b32_e32 v56, 0xff, v56
	v_or_b32_e32 v54, 0xff, v54
	v_or_b32_e32 v53, 0xff, v53
	v_or_b32_e32 v52, 0xff, v52
	v_subrev_u32_e32 v31, 51, v31
	v_subrev_u32_e32 v62, 64, v62
	v_add_u32_e32 v67, 0xffffffbf, v67
	v_add_u32_e32 v36, 0xffffffbe, v36
	v_add_u32_e32 v61, 0xffffffb0, v61
	v_add_u32_e32 v60, 0xffffffaf, v60
	v_add_u32_e32 v68, 0xffffffa0, v68
	v_add_u32_e32 v59, 0xffffff9f, v59
	v_add_u32_e32 v69, 0xffffff90, v69
	v_add_u32_e32 v33, 0xffffff8f, v33
	v_add_u32_e32 v55, 0xffffff80, v55
	v_add_u32_e32 v57, 0xffffff70, v57
	v_add_u32_e32 v56, 0xffffff60, v56
	v_add_u32_e32 v54, 0xffffff50, v54
	v_add_u32_e32 v53, 0xffffff40, v53
	v_add_u32_e32 v52, 0xffffff30, v52
	ds_bpermute_b32 v42, v123, v38
	ds_bpermute_b32 v47, v123, v40
	ds_bpermute_b32 v48, v123, v30
	ds_bpermute_b32 v49, v123, v37
	ds_bpermute_b32 v63, v123, v28
	ds_bpermute_b32 v71, v123, v29
	ds_bpermute_b32 v72, v123, v39
	ds_bpermute_b32 v73, v123, v34
	ds_bpermute_b32 v74, v123, v46
	v_max_i32_e32 v58, v31, v54
	v_min_i32_e32 v31, v31, v54
	v_max_i32_e32 v54, v62, v56
	v_min_i32_e32 v56, v62, v56
	v_max_i32_e32 v62, v67, v52
	v_min_i32_e32 v52, v67, v52
	v_max_i32_e32 v67, v36, v53
	v_min_i32_e32 v36, v36, v53
	v_max_i32_e32 v53, v61, v69
	v_min_i32_e32 v61, v61, v69
	v_max_i32_e32 v69, v60, v68
	v_min_i32_e32 v60, v60, v68
	v_max_i32_e32 v68, v59, v57
	v_min_i32_e32 v57, v59, v57
	v_max_i32_e32 v59, v33, v55
	v_min_i32_e32 v33, v33, v55
	v_max_i32_e32 v55, v58, v69
	v_min_i32_e32 v58, v58, v69
	v_max_i32_e32 v69, v54, v68
	v_min_i32_e32 v54, v54, v68
	v_max_i32_e32 v68, v62, v59
	v_min_i32_e32 v59, v62, v59
	v_max_i32_e32 v62, v67, v53
	v_min_i32_e32 v53, v67, v53
	v_max_i32_e32 v67, v60, v31
	v_min_i32_e32 v31, v60, v31
	v_max_i32_e32 v60, v61, v36
	v_min_i32_e32 v36, v61, v36
	v_max_i32_e32 v61, v33, v52
	v_min_i32_e32 v33, v33, v52
	v_max_i32_e32 v52, v57, v56
	v_min_i32_e32 v56, v57, v56
	v_max_i32_e32 v57, v55, v69
	v_min_i32_e32 v55, v55, v69
	v_max_i32_e32 v69, v68, v62
	v_min_i32_e32 v62, v68, v62
	v_max_i32_e32 v68, v53, v58
	v_min_i32_e32 v53, v53, v58
	v_max_i32_e32 v58, v67, v60
	v_min_i32_e32 v60, v67, v60
	v_max_i32_e32 v67, v54, v59
	v_min_i32_e32 v54, v54, v59
	v_max_i32_e32 v59, v61, v52
	v_min_i32_e32 v52, v61, v52
	v_max_i32_e32 v61, v56, v31
	v_min_i32_e32 v31, v56, v31
	v_max_i32_e32 v56, v36, v33
	v_min_i32_e32 v33, v36, v33
	s_waitcnt lgkmcnt(9)
; #define CAND(a, b) (int)((__float_as_uint(__int_as_float(top[0][a]) + __int_as_float(top[1][b])) | 255u) - (unsigned)((a) * 16 + (b)))
; __device__ __forceinline__ void route_task(int task, int tl0, const bf16* QP  , const LAS bf16* KHL, LAS unsigned short* EL, LAS float* GL, int lane) {
;     ...
;         merge16_desc(bk, oth);
;     }
;     ...
;     {
;         int gk[16];
;         gk[0] = CAND(3, 3); gk[1] = CAND(4, 0); gk[2] = CAND(4, 1); gk[3] = CAND(4, 2); gk[4] = CAND(5, 0); gk[5] = CAND(5, 1); gk[6] = CAND(6, 0); gk[7] = CAND(6, 1);
;         gk[8] = CAND(7, 0); gk[9] = CAND(7, 1); gk[10] = CAND(8, 0); gk[11] = CAND(9, 0); gk[12] = CAND(10, 0); gk[13] = CAND(11, 0); gk[14] = CAND(12, 0); gk[15] = CAND(13, 0);
;         sort16_desc(gk);
;         merge16_desc(bk, gk);
	v_max_i32_e32 v38, v38, v70
	v_min_i32_e32 v36, v57, v69
	v_max_i32_e32 v70, v55, v62
	v_min_i32_e32 v55, v55, v62
	v_max_i32_e32 v62, v68, v59
	v_min_i32_e32 v59, v68, v59
	v_max_i32_e32 v68, v53, v52
	v_min_i32_e32 v52, v53, v52
	v_max_i32_e32 v53, v58, v67
	v_min_i32_e32 v58, v58, v67
	v_max_i32_e32 v67, v60, v54
	v_min_i32_e32 v54, v60, v54
	v_max_i32_e32 v60, v61, v56
	v_min_i32_e32 v56, v61, v56
	v_max_i32_e32 v61, v31, v33
	v_min_i32_e32 v31, v31, v33
	v_max_i32_e32 v33, v70, v36
	v_min_i32_e32 v36, v70, v36
	v_max_i32_e32 v70, v55, v60
	v_min_i32_e32 v55, v55, v60
	v_max_i32_e32 v60, v62, v53
	v_min_i32_e32 v53, v62, v53
	v_max_i32_e32 v62, v68, v58
	v_min_i32_e32 v58, v68, v58
	v_max_i32_e32 v68, v67, v59
	v_min_i32_e32 v59, v67, v59
	v_max_i32_e32 v67, v54, v52
	v_min_i32_e32 v52, v54, v52
	v_max_i32_e32 v54, v61, v56
	s_waitcnt lgkmcnt(3)
	v_max_i32_e32 v40, v40, v71
	s_waitcnt lgkmcnt(2)
	v_max_i32_e32 v30, v30, v72
	s_waitcnt lgkmcnt(1)
	v_max_i32_e32 v37, v37, v73
	s_waitcnt lgkmcnt(0)
	v_max_i32_e32 v28, v28, v74
	v_max_i32_e32 v41, v41, v66
	v_max_i32_e32 v32, v32, v65
	v_max_i32_e32 v44, v44, v64
	v_max_i32_e32 v46, v46, v63
	v_max_i32_e32 v34, v34, v49
	v_max_i32_e32 v39, v39, v48
	v_max_i32_e32 v29, v29, v47
	v_max_i32_e32 v27, v27, v42
	v_min_i32_e32 v56, v61, v56
	v_max_i32_e32 v61, v33, v60
	v_min_i32_e32 v33, v33, v60
	v_max_i32_e32 v60, v36, v53
	v_min_i32_e32 v36, v36, v53
	v_max_i32_e32 v53, v62, v68
	v_min_i32_e32 v62, v62, v68
	v_max_i32_e32 v68, v58, v59
	v_min_i32_e32 v58, v58, v59
	v_max_i32_e32 v59, v67, v54
	v_max_i32_e32 v42, v38, v41
	v_min_i32_e32 v38, v38, v41
	v_max_i32_e32 v41, v40, v32
	v_min_i32_e32 v32, v40, v32
	v_max_i32_e32 v40, v30, v44
	v_min_i32_e32 v30, v30, v44
	v_max_i32_e32 v44, v37, v46
	v_min_i32_e32 v37, v37, v46
	v_max_i32_e32 v46, v28, v34
	v_min_i32_e32 v28, v28, v34
	v_max_i32_e32 v34, v45, v39
	v_min_i32_e32 v39, v45, v39
	v_max_i32_e32 v45, v43, v29
	v_min_i32_e32 v29, v43, v29
	v_max_i32_e32 v43, v35, v27
	v_min_i32_e32 v27, v35, v27
	v_min_i32_e32 v54, v67, v54
	v_max_i32_e32 v67, v52, v56
	v_max_i32_e32 v71, v70, v36
	v_min_i32_e32 v36, v70, v36
	v_max_i32_e32 v70, v59, v55
	v_min_i32_e32 v55, v59, v55
	v_max_i32_e32 v35, v42, v46
	v_min_i32_e32 v42, v42, v46
	v_max_i32_e32 v46, v41, v34
	v_min_i32_e32 v34, v41, v34
	v_max_i32_e32 v41, v40, v45
	v_min_i32_e32 v40, v40, v45
	v_max_i32_e32 v45, v44, v43
	v_min_i32_e32 v43, v44, v43
	v_max_i32_e32 v44, v38, v28
	v_min_i32_e32 v28, v38, v28
	v_max_i32_e32 v38, v32, v39
	v_min_i32_e32 v32, v32, v39
	v_max_i32_e32 v39, v30, v29
	v_min_i32_e32 v29, v30, v29
	v_max_i32_e32 v30, v37, v27
	v_min_i32_e32 v27, v37, v27
	v_min_i32_e32 v52, v52, v56
	v_min_i32_e32 v56, v60, v33
	v_max_i32_e32 v59, v67, v54
	v_min_i32_e32 v54, v67, v54
	v_max_i32_e32 v67, v71, v53
	v_min_i32_e32 v53, v71, v53
	v_max_i32_e32 v71, v36, v62
	v_min_i32_e32 v36, v36, v62
	v_max_i32_e32 v62, v68, v70
	v_min_i32_e32 v68, v68, v70
	v_max_i32_e32 v70, v58, v55
	v_max_i32_e32 v37, v35, v41
	v_min_i32_e32 v35, v35, v41
	v_max_i32_e32 v41, v46, v45
	v_min_i32_e32 v45, v46, v45
	v_max_i32_e32 v46, v42, v40
	v_min_i32_e32 v40, v42, v40
	v_max_i32_e32 v42, v34, v43
	v_min_i32_e32 v34, v34, v43
	v_max_i32_e32 v43, v44, v39
	v_min_i32_e32 v39, v44, v39
	v_max_i32_e32 v44, v38, v30
	v_min_i32_e32 v30, v38, v30
	v_max_i32_e32 v38, v28, v29
	v_min_i32_e32 v28, v28, v29
	v_max_i32_e32 v29, v32, v27
	v_min_i32_e32 v27, v32, v27
	v_min_i32_e32 v55, v58, v55
	v_max_i32_e32 v58, v67, v56
	v_min_i32_e32 v56, v67, v56
	v_max_i32_e32 v67, v53, v71
	v_min_i32_e32 v53, v53, v71
	v_max_i32_e32 v71, v62, v36
	v_min_i32_e32 v36, v62, v36
	v_max_i32_e32 v62, v68, v70
	v_min_i32_e32 v32, v37, v41
	v_min_i32_e32 v47, v35, v45
	v_min_i32_e32 v48, v46, v42
	v_min_i32_e32 v49, v40, v34
	v_min_i32_e32 v63, v43, v44
	v_min_i32_e32 v64, v39, v30
	v_min_i32_e32 v65, v38, v29
	v_min_i32_e32 v66, v28, v27
	v_min_i32_e32 v68, v68, v70
	v_max_i32_e32 v70, v59, v55
	v_min_i32_e32 v55, v59, v55
	v_min_i32_e32 v59, v53, v71
	v_min_i32_e32 v72, v36, v62
	v_max3_i32 v31, v37, v41, v31
	v_max_i32_e32 v32, v32, v52
	v_max3_i32 v35, v35, v45, v54
	v_max_i32_e32 v37, v47, v55
	v_max3_i32 v41, v46, v42, v70
	v_max_i32_e32 v42, v48, v68
	v_max3_i32 v34, v40, v34, v72
	v_max3_i32 v36, v49, v36, v62
	v_max3_i32 v40, v43, v44, v59
	v_max3_i32 v43, v63, v53, v71
	v_max3_i32 v30, v39, v30, v67
	v_max_i32_e32 v39, v64, v56
	v_max3_i32 v29, v38, v29, v58
	v_max3_i32 v33, v65, v60, v33
	v_max3_i32 v27, v28, v27, v61
	v_max3_i32 v28, v66, v57, v69
	v_max_i32_e32 v38, v31, v40
	v_min_i32_e32 v31, v31, v40
	v_max_i32_e32 v40, v32, v43
	v_min_i32_e32 v32, v32, v43
	v_max_i32_e32 v43, v35, v30
	v_min_i32_e32 v30, v35, v30
	v_max_i32_e32 v35, v37, v39
	v_min_i32_e32 v37, v37, v39
	v_max_i32_e32 v39, v41, v29
	v_min_i32_e32 v29, v41, v29
	v_max_i32_e32 v41, v42, v33
	v_min_i32_e32 v33, v42, v33
	v_max_i32_e32 v42, v34, v27
	v_min_i32_e32 v27, v34, v27
	v_max_i32_e32 v34, v36, v28
	v_min_i32_e32 v28, v36, v28
	v_max_i32_e32 v36, v38, v39
	v_min_i32_e32 v38, v38, v39
	v_max_i32_e32 v39, v40, v41
	v_min_i32_e32 v40, v40, v41
	v_max_i32_e32 v41, v43, v42
	v_min_i32_e32 v42, v43, v42
	v_max_i32_e32 v43, v35, v34
	v_min_i32_e32 v34, v35, v34
	v_max_i32_e32 v35, v31, v29
	v_min_i32_e32 v29, v31, v29
	v_max_i32_e32 v31, v32, v33
	v_min_i32_e32 v32, v32, v33
	v_max_i32_e32 v33, v30, v27
	v_min_i32_e32 v27, v30, v27
	v_max_i32_e32 v30, v37, v28
	v_min_i32_e32 v28, v37, v28
	v_max_i32_e32 v37, v36, v41
	v_min_i32_e32 v36, v36, v41
	v_max_i32_e32 v41, v39, v43
	v_min_i32_e32 v39, v39, v43
	v_max_i32_e32 v43, v38, v42
	v_min_i32_e32 v38, v38, v42
; #define CAND(a, b) (int)((__float_as_uint(__int_as_float(top[0][a]) + __int_as_float(top[1][b])) | 255u) - (unsigned)((a) * 16 + (b)))
; __device__ __forceinline__ void route_task(int task, int tl0, const bf16* QP  , const LAS bf16* KHL, LAS unsigned short* EL, LAS float* GL, int lane) {
;     ...
;         merge16_desc(bk, gk);
;     }
;     {
;         const int c14 = CAND(14, 0), c15 = CAND(15, 0);
;         const int n14 = max(bk[14], c14), n15 = max(min(bk[14], c14), max(bk[15], c15));
;         bk[14] = n14; bk[15] = n15;
;     }
;     ...
;     int my[8];
; #pragma unroll
;     for (int i = 0; i < 8; ++i) { int lo_ = bk[i], hi_ = bk[8 + i]; asm volatile("" : "+v"(lo_), "+v"(hi_)); my[i] = hi ? hi_ : lo_; }
;     int bv[8];
; #pragma unroll
;     for (int i = 0; i < 8; ++i) {
;         const unsigned cd = 255u - ((unsigned)my[i] & 255u), ca = cd >> 4, cb = cd & 15u;
;         const unsigned wa = (ca >> 2) == 0u ? P1[0] : (ca >> 2) == 1u ? P1[1] : (ca >> 2) == 2u ? P1[2] : P1[3];
;         const unsigned wb = (cb >> 2) == 0u ? P2[0] : (cb >> 2) == 1u ? P2[1] : (cb >> 2) == 2u ? P2[2] : P2[3];
;         bv[i] = (int)((((wa >> (8u * (ca & 3u))) & 255u) << 7) | ((wb >> (8u * (cb & 3u))) & 255u));
	v_max_i32_e32 v42, v40, v34
	v_min_i32_e32 v34, v40, v34
	v_max_i32_e32 v40, v35, v33
	v_min_i32_e32 v33, v35, v33
	v_max_i32_e32 v35, v31, v30
	v_min_i32_e32 v30, v31, v30
	v_max_i32_e32 v31, v29, v27
	v_min_i32_e32 v27, v29, v27
	v_max_i32_e32 v29, v32, v28
	v_min_i32_e32 v28, v32, v28
	v_max_i32_e32 v32, v37, v41
	v_min_i32_e32 v37, v37, v41
	v_max_i32_e32 v41, v36, v39
	v_min_i32_e32 v36, v36, v39
	v_max_i32_e32 v39, v43, v42
	v_min_i32_e32 v42, v43, v42
	v_max_i32_e32 v43, v38, v34
	v_min_i32_e32 v34, v38, v34
	v_max_i32_e32 v38, v40, v35
	v_min_i32_e32 v35, v40, v35
	v_max_i32_e32 v40, v33, v30
	v_min_i32_e32 v30, v33, v30
	v_max_i32_e32 v33, v31, v29
	v_min_i32_e32 v29, v31, v29
	v_max_i32_e32 v31, v27, v28
	v_min_i32_e32 v27, v27, v28
	v_add_f32_e32 v28, v51, v26
	v_or_b32_e32 v28, 0xff, v28
	v_add_f32_e32 v26, v50, v26
	v_add_u32_e32 v28, 0xffffff20, v28
	v_or_b32_e32 v26, 0xff, v26
	v_add_u32_e32 v26, 0xffffff10, v26
	v_max_i32_e32 v44, v31, v28
	v_min_i32_e32 v28, v31, v28
	v_max3_i32 v26, v28, v27, v26
	v_mov_b32_e32 v27, v32
	s_nop 0
	v_cndmask_b32_e64 v27, v38, v27, s[6:7]
	v_not_b32_e32 v28, v27
	v_bfe_u32 v45, v28, 6, 2
	v_cmp_eq_u32_e32 vcc, 2, v45
	v_cndmask_b32_e64 v34, v26, v34, s[6:7]
	v_bitop3_b32 v26, v27, s3, v27 bitop3:0xc
	v_cndmask_b32_e32 v46, v25, v23, vcc
	v_cmp_eq_u32_e32 vcc, 1, v45
	v_cndmask_b32_e64 v31, v35, v37, s[6:7]
	v_not_b32_e32 v35, v31
	v_cndmask_b32_e32 v45, v46, v21, vcc
	v_cmp_gt_u32_e32 vcc, 64, v26
	v_cndmask_b32_e64 v37, v40, v41, s[6:7]
	v_cndmask_b32_e64 v41, v44, v43, s[6:7]
	v_cndmask_b32_e32 v26, v45, v19, vcc
	v_bfe_u32 v45, v28, 2, 2
	v_cmp_eq_u32_e32 vcc, 2, v45
	v_bitop3_b32 v44, v27, 15, v27 bitop3:0xc
	v_bfe_u32 v47, v35, 6, 2
	v_cndmask_b32_e32 v46, v24, v22, vcc
	v_cmp_eq_u32_e32 vcc, 1, v45
	v_not_b32_e32 v38, v37
	v_bfe_u32 v49, v38, 6, 2
	v_cndmask_b32_e32 v45, v46, v20, vcc
	v_cmp_gt_u32_e32 vcc, 4, v44
	v_bitop3_b32 v46, v31, 15, v31 bitop3:0xc
	v_cndmask_b32_e64 v30, v30, v36, s[6:7]
	v_cndmask_b32_e32 v44, v45, v18, vcc
	v_cmp_eq_u32_e32 vcc, 2, v47
	v_bitop3_b32 v45, v31, s3, v31 bitop3:0xc
	v_not_b32_e32 v36, v30
	v_cndmask_b32_e32 v48, v25, v23, vcc
	v_cmp_eq_u32_e32 vcc, 1, v47
	v_bfe_u32 v51, v36, 6, 2
	v_cndmask_b32_e64 v33, v33, v39, s[6:7]
	v_cndmask_b32_e32 v47, v48, v21, vcc
	v_cmp_gt_u32_e32 vcc, 64, v45
	v_not_b32_e32 v39, v33
	v_bfe_u32 v53, v39, 6, 2
	v_cndmask_b32_e32 v45, v47, v19, vcc
	v_bfe_u32 v47, v35, 2, 2
	v_cmp_eq_u32_e32 vcc, 2, v47
	v_cndmask_b32_e64 v29, v29, v42, s[6:7]
	v_not_b32_e32 v40, v29
	v_cndmask_b32_e32 v48, v24, v22, vcc
	v_cmp_eq_u32_e32 vcc, 1, v47
	v_bfe_u32 v55, v40, 6, 2
	v_not_b32_e32 v42, v41
	v_cndmask_b32_e32 v47, v48, v20, vcc
	v_cmp_gt_u32_e32 vcc, 4, v46
	v_bitop3_b32 v48, v37, 15, v37 bitop3:0xc
	v_bfe_u32 v57, v42, 6, 2
	v_cndmask_b32_e32 v46, v47, v18, vcc
	v_cmp_eq_u32_e32 vcc, 2, v49
	v_bitop3_b32 v47, v37, s3, v37 bitop3:0xc
	v_not_b32_e32 v43, v34
	v_cndmask_b32_e32 v50, v25, v23, vcc
	v_cmp_eq_u32_e32 vcc, 1, v49
	v_bfe_u32 v59, v43, 6, 2
	v_or_b32_e32 v82, s10, v88
	v_cndmask_b32_e32 v49, v50, v21, vcc
	v_cmp_gt_u32_e32 vcc, 64, v47
	s_nop 1
	v_cndmask_b32_e32 v47, v49, v19, vcc
	v_bfe_u32 v49, v38, 2, 2
	v_cmp_eq_u32_e32 vcc, 2, v49
	s_nop 1
	v_cndmask_b32_e32 v50, v24, v22, vcc
	v_cmp_eq_u32_e32 vcc, 1, v49
	s_nop 1
	v_cndmask_b32_e32 v49, v50, v20, vcc
	v_cmp_gt_u32_e32 vcc, 4, v48
	v_bitop3_b32 v50, v30, 15, v30 bitop3:0xc
	s_nop 0
	v_cndmask_b32_e32 v48, v49, v18, vcc
	v_cmp_eq_u32_e32 vcc, 2, v51
	v_bitop3_b32 v49, v30, s3, v30 bitop3:0xc
	s_nop 0
	v_cndmask_b32_e32 v52, v25, v23, vcc
	v_cmp_eq_u32_e32 vcc, 1, v51
	s_nop 1
	v_cndmask_b32_e32 v51, v52, v21, vcc
	v_cmp_gt_u32_e32 vcc, 64, v49
	s_nop 1
	v_cndmask_b32_e32 v49, v51, v19, vcc
	v_bfe_u32 v51, v36, 2, 2
	v_cmp_eq_u32_e32 vcc, 2, v51
	s_nop 1
	v_cndmask_b32_e32 v52, v24, v22, vcc
	v_cmp_eq_u32_e32 vcc, 1, v51
	s_nop 1
	v_cndmask_b32_e32 v51, v52, v20, vcc
	v_cmp_gt_u32_e32 vcc, 4, v50
	v_bitop3_b32 v52, v33, 15, v33 bitop3:0xc
	s_nop 0
	v_cndmask_b32_e32 v50, v51, v18, vcc
	v_cmp_eq_u32_e32 vcc, 2, v53
	v_bitop3_b32 v51, v33, s3, v33 bitop3:0xc
	s_nop 0
	v_cndmask_b32_e32 v54, v25, v23, vcc
	v_cmp_eq_u32_e32 vcc, 1, v53
	s_nop 1
	v_cndmask_b32_e32 v53, v54, v21, vcc
	v_cmp_gt_u32_e32 vcc, 64, v51
	s_nop 1
	v_cndmask_b32_e32 v51, v53, v19, vcc
	v_bfe_u32 v53, v39, 2, 2
	v_cmp_eq_u32_e32 vcc, 2, v53
	s_nop 1
	v_cndmask_b32_e32 v54, v24, v22, vcc
	v_cmp_eq_u32_e32 vcc, 1, v53
	s_nop 1
	v_cndmask_b32_e32 v53, v54, v20, vcc
	v_cmp_gt_u32_e32 vcc, 4, v52
	v_bitop3_b32 v54, v29, 15, v29 bitop3:0xc
	s_nop 0
	v_cndmask_b32_e32 v52, v53, v18, vcc
	v_cmp_eq_u32_e32 vcc, 2, v55
	v_bitop3_b32 v53, v29, s3, v29 bitop3:0xc
	s_nop 0
	v_cndmask_b32_e32 v56, v25, v23, vcc
	v_cmp_eq_u32_e32 vcc, 1, v55
	s_nop 1
	v_cndmask_b32_e32 v55, v56, v21, vcc
	v_cmp_gt_u32_e32 vcc, 64, v53
	s_nop 1
	v_cndmask_b32_e32 v53, v55, v19, vcc
	v_bfe_u32 v55, v40, 2, 2
	v_cmp_eq_u32_e32 vcc, 2, v55
	s_nop 1
	v_cndmask_b32_e32 v56, v24, v22, vcc
	v_cmp_eq_u32_e32 vcc, 1, v55
	s_nop 1
	v_cndmask_b32_e32 v55, v56, v20, vcc
	v_cmp_gt_u32_e32 vcc, 4, v54
	v_bitop3_b32 v56, v41, 15, v41 bitop3:0xc
	s_nop 0
	v_cndmask_b32_e32 v54, v55, v18, vcc
	v_cmp_eq_u32_e32 vcc, 2, v57
	v_bitop3_b32 v55, v41, s3, v41 bitop3:0xc
	s_nop 0
	v_cndmask_b32_e32 v58, v25, v23, vcc
	v_cmp_eq_u32_e32 vcc, 1, v57
	s_nop 1
	v_cndmask_b32_e32 v57, v58, v21, vcc
	v_cmp_gt_u32_e32 vcc, 64, v55
	s_nop 1
	v_cndmask_b32_e32 v55, v57, v19, vcc
	v_bfe_u32 v57, v42, 2, 2
	v_cmp_eq_u32_e32 vcc, 2, v57
	s_nop 1
	v_cndmask_b32_e32 v58, v24, v22, vcc
	v_cmp_eq_u32_e32 vcc, 1, v57
	s_nop 1
	v_cndmask_b32_e32 v57, v58, v20, vcc
; #define LAS __attribute__((address_space(3)))
; __device__ __forceinline__ void route_task(int task, int tl0, const bf16* QP  , const LAS bf16* KHL, LAS unsigned short* EL, LAS float* GL, int lane) {
;     ...
;     { unsigned qo = (unsigned)t * (unsigned)D + (unsigned)(head * 128 + 8 * hi); asm volatile("" : "+v"(qo)); const bf16* qp = QP + qo;
; #pragma unroll
;       for (int hf = 0; hf < 2; ++hf)
; #pragma unroll
;         for (int ks = 0; ks < 4; ++ks) qa[hf][ks] = ldg8(qp + 64 * hf + 16 * ks); }
; #pragma unroll
;     for (int half = 0; half < 2; ++half) {
;         int cur[16];
; #pragma unroll
;         for (int kt = 0; kt < 4; ++kt) {
;             f32x16 X;
; #pragma unroll
;             for (int i = 0; i < 16; ++i) X[i] = 8.f;
;             const LAS bf16* khp = KHL + (half * 128 + 32 * kt + r) * 72 + 8 * hi;
; #pragma unroll
;             for (int ks = 0; ks < 4; ++ks) {
;                 const bf16x8 kh = lds8(khp + 16 * ks);
;                 X = MFMA32(kh, qa[half][ks], X);
;     ...
;     for (int i = 0; i < 8; ++i) {
;         const unsigned cd = 255u - ((unsigned)my[i] & 255u), ca = cd >> 4, cb = cd & 15u;
;         const unsigned wa = (ca >> 2) == 0u ? P1[0] : (ca >> 2) == 1u ? P1[1] : (ca >> 2) == 2u ? P1[2] : P1[3];
;         const unsigned wb = (cb >> 2) == 0u ? P2[0] : (cb >> 2) == 1u ? P2[1] : (cb >> 2) == 2u ? P2[2] : P2[3];
;         bv[i] = (int)((((wa >> (8u * (ca & 3u))) & 255u) << 7) | ((wb >> (8u * (cb & 3u))) & 255u));
;     }
;     float e[8], se = 0.f;
; #pragma unroll
;     for (int i = 0; i < 8; ++i) { e[i] = __expf(__int_as_float(my[i]) - __int_as_float(bk[0])); se += e[i]; }
;     se += __shfl_xor(se, 32);
;     const float inv = 1.f / se;
;     {
;         int l2 = lane; asm volatile("" : "+v"(l2));
;         const int o2 = (tl0 + ((l2 & 31) >> 3)) * 128 + (l2 & 7) * 16 + 8 * (l2 >> 5);
;         LAS v4u* ip = (LAS v4u*)(EL + o2); typedef float f4v __attribute__((ext_vector_type(4))); LAS f4v* gp = (LAS f4v*)(GL + o2);
;         ip[0] = (v4u){(unsigned)bv[0] | ((unsigned)bv[1] << 16), (unsigned)bv[2] | ((unsigned)bv[3] << 16), (unsigned)bv[4] | ((unsigned)bv[5] << 16), (unsigned)bv[6] | ((unsigned)bv[7] << 16)};
;         gp[0] = (f4v){e[0] * inv, e[1] * inv, e[2] * inv, e[3] * inv}; gp[1] = (f4v){e[4] * inv, e[5] * inv, e[6] * inv, e[7] * inv};
;     }
; }
	v_cmp_gt_u32_e32 vcc, 4, v56
	v_bitop3_b32 v58, v34, 15, v34 bitop3:0xc
	s_nop 0
	v_cndmask_b32_e32 v56, v57, v18, vcc
	v_cmp_eq_u32_e32 vcc, 2, v59
	v_bitop3_b32 v57, v34, s3, v34 bitop3:0xc
	s_nop 0
	v_cndmask_b32_e32 v23, v25, v23, vcc
	v_cmp_eq_u32_e32 vcc, 1, v59
	v_sub_f32_e32 v25, v30, v32
	v_mul_f32_e32 v25, 0x3fb8aa3b, v25
	v_cndmask_b32_e32 v21, v23, v21, vcc
	v_cmp_gt_u32_e32 vcc, 64, v57
	v_lshrrev_b32_e32 v23, 1, v39
	v_and_b32_e32 v23, 24, v23
	v_cndmask_b32_e32 v19, v21, v19, vcc
	v_bfe_u32 v21, v43, 2, 2
	v_cmp_eq_u32_e32 vcc, 2, v21
	v_lshrrev_b32_e32 v23, v23, v51
	v_lshlrev_b32_e32 v23, 7, v23
	v_cndmask_b32_e32 v22, v24, v22, vcc
	v_cmp_eq_u32_e32 vcc, 1, v21
	v_lshrrev_b32_e32 v21, 1, v42
	v_and_b32_e32 v21, 24, v21
	v_cndmask_b32_e32 v20, v22, v20, vcc
	v_cmp_gt_u32_e32 vcc, 4, v58
	v_lshrrev_b32_e32 v21, v21, v55
	v_lshrrev_b32_e32 v22, 1, v40
	v_cndmask_b32_e32 v18, v20, v18, vcc
	v_lshlrev_b32_e32 v20, 3, v42
	v_lshlrev_b32_e32 v21, 7, v21
	v_and_b32_e32 v22, 24, v22
	v_lshrrev_b32_e32 v20, v20, v56
	v_and_b32_e32 v21, 0x7f80, v21
	v_lshrrev_b32_e32 v22, v22, v53
	v_and_or_b32 v21, v20, s3, v21
	v_lshlrev_b32_e32 v20, 3, v40
	v_lshlrev_b32_e32 v22, 7, v22
	v_lshrrev_b32_e32 v20, v20, v54
	v_and_b32_e32 v22, 0x7f80, v22
	v_and_or_b32 v20, v20, s3, v22
	v_lshlrev_b32_e32 v22, 3, v39
	v_lshrrev_b32_e32 v22, v22, v52
	v_and_b32_e32 v23, 0x7f80, v23
	v_and_or_b32 v39, v22, s3, v23
	v_lshrrev_b32_e32 v23, 1, v36
	v_and_b32_e32 v23, 24, v23
	v_lshrrev_b32_e32 v23, v23, v49
	v_lshlrev_b32_e32 v22, 3, v36
	v_lshlrev_b32_e32 v23, 7, v23
	v_lshrrev_b32_e32 v22, v22, v50
	v_and_b32_e32 v23, 0x7f80, v23
	v_and_or_b32 v36, v22, s3, v23
	v_lshrrev_b32_e32 v23, 1, v38
	v_and_b32_e32 v23, 24, v23
	v_lshrrev_b32_e32 v23, v23, v47
	v_lshlrev_b32_e32 v22, 3, v38
	v_lshlrev_b32_e32 v23, 7, v23
	v_lshrrev_b32_e32 v22, v22, v48
	v_and_b32_e32 v23, 0x7f80, v23
	v_and_or_b32 v38, v22, s3, v23
	v_lshrrev_b32_e32 v23, 1, v35
	v_and_b32_e32 v23, 24, v23
	v_lshrrev_b32_e32 v23, v23, v45
	v_lshlrev_b32_e32 v22, 3, v35
	v_lshlrev_b32_e32 v23, 7, v23
	v_lshrrev_b32_e32 v22, v22, v46
	v_and_b32_e32 v23, 0x7f80, v23
	v_and_or_b32 v35, v22, s3, v23
	v_lshrrev_b32_e32 v23, 1, v28
	v_and_b32_e32 v23, 24, v23
	v_lshrrev_b32_e32 v23, v23, v26
	v_lshlrev_b32_e32 v22, 3, v28
	v_lshlrev_b32_e32 v23, 7, v23
	v_lshrrev_b32_e32 v22, v22, v44
	v_and_b32_e32 v23, 0x7f80, v23
	v_and_or_b32 v40, v22, s3, v23
	v_sub_f32_e32 v22, v27, v32
	v_mul_f32_e32 v22, 0x3fb8aa3b, v22
	v_sub_f32_e32 v23, v31, v32
	v_exp_f32_e32 v22, v22
	v_mul_f32_e32 v23, 0x3fb8aa3b, v23
	v_sub_f32_e32 v24, v37, v32
	v_exp_f32_e32 v23, v23
	v_mul_f32_e32 v24, 0x3fb8aa3b, v24
	v_exp_f32_e32 v24, v24
	v_exp_f32_e32 v25, v25
	v_add_f32_e32 v26, 0, v22
	v_add_f32_e32 v26, v23, v26
	v_add_f32_e32 v26, v24, v26
	v_add_f32_e32 v30, v25, v26
	v_sub_f32_e32 v26, v33, v32
	v_mul_f32_e32 v26, 0x3fb8aa3b, v26
	v_sub_f32_e32 v27, v29, v32
	v_exp_f32_e32 v26, v26
	v_mul_f32_e32 v27, 0x3fb8aa3b, v27
	v_sub_f32_e32 v28, v41, v32
	v_exp_f32_e32 v27, v27
	v_mul_f32_e32 v28, 0x3fb8aa3b, v28
	v_sub_f32_e32 v29, v34, v32
	v_exp_f32_e32 v28, v28
	v_mul_f32_e32 v29, 0x3fb8aa3b, v29
	v_exp_f32_e32 v29, v29
	v_add_f32_e32 v30, v26, v30
	v_add_f32_e32 v30, v27, v30
	v_add_f32_e32 v30, v28, v30
	v_add_f32_e32 v30, v29, v30
	ds_bpermute_b32 v31, v123, v30
	v_lshrrev_b32_e32 v42, 1, v43
	v_and_b32_e32 v32, 24, v42
	v_lshrrev_b32_e32 v19, v32, v19
	v_lshlrev_b32_e32 v19, 7, v19
	s_waitcnt lgkmcnt(0)
	v_add_f32_e32 v30, v30, v31
	v_div_scale_f32 v31, s[12:13], v30, v30, 1.0
	v_rcp_f32_e32 v32, v31
	v_lshlrev_b32_e32 v33, 3, v43
	v_and_b32_e32 v19, 0x7f80, v19
	v_lshrrev_b32_e32 v18, v33, v18
	v_and_or_b32 v33, v18, s3, v19
	v_fma_f32 v18, -v31, v32, 1.0
	v_fmac_f32_e32 v32, v18, v32
	v_div_scale_f32 v18, vcc, 1.0, v30, 1.0
	v_mul_f32_e32 v19, v18, v32
	v_fma_f32 v34, -v31, v19, v18
	v_fmac_f32_e32 v19, v34, v32
	v_fma_f32 v18, -v31, v19, v18
	v_div_fmas_f32 v18, v18, v32, v19
	v_div_fixup_f32 v30, v18, v30, 1.0
	v_mov_b32_e32 v18, v1
	v_lshl_or_b32 v20, v20, 16, v39
	v_lshrrev_b32_e32 v19, 3, v18
	v_and_or_b32 v19, v19, 3, s55
	v_lshlrev_b32_e32 v31, 4, v18
	v_ashrrev_i32_e32 v18, 2, v18
	v_lshlrev_b32_e32 v19, 7, v19
	v_and_b32_e32 v31, 0x70, v31
	v_and_b32_e32 v18, -8, v18
	v_add3_u32 v18, v18, v31, v19
	v_lshl_add_u32 v31, v18, 1, s11
	v_lshl_add_u32 v32, v18, 2, s69
	v_lshl_or_b32 v18, v35, 16, v40
	v_lshl_or_b32 v19, v36, 16, v38
	v_lshl_or_b32 v21, v33, 16, v21
	ds_write_b128 v31, v[18:21]
	v_pk_mul_f32 v[20:21], v[24:25], v[30:31] op_sel_hi:[1,0]
	v_pk_mul_f32 v[18:19], v[22:23], v[30:31] op_sel_hi:[1,0]
	ds_write_b128 v32, v[18:21]
	v_pk_mul_f32 v[20:21], v[28:29], v[30:31] op_sel_hi:[1,0]
	v_pk_mul_f32 v[18:19], v[26:27], v[30:31] op_sel_hi:[1,0]
	ds_write_b128 v32, v[18:21] offset:16
	v_mov_b64_e32 v[32:33], s[30:31]
	v_lshl_add_u64 v[128:129], v[82:83], 1, s[80:81]
	s_waitcnt vmcnt(4)
	v_mov_b32_e32 v78, v150
	v_mov_b32_e32 v79, v151
	v_mov_b32_e32 v80, v152
	v_mov_b32_e32 v81, v153
	v_mov_b32_e32 v74, v154
	v_mov_b32_e32 v75, v155
	v_mov_b32_e32 v76, v156
	v_mov_b32_e32 v77, v157
	v_mov_b32_e32 v70, v158
	v_mov_b32_e32 v71, v159
	v_mov_b32_e32 v72, v160
	v_mov_b32_e32 v73, v161
	v_mov_b32_e32 v66, v162
	v_mov_b32_e32 v67, v163
	v_mov_b32_e32 v68, v164
	v_mov_b32_e32 v69, v165
	ds_read_b128 v[50:53], v94
	ds_read_b128 v[54:57], v94 offset:32
	v_mov_b64_e32 v[30:31], s[28:29]
	v_mov_b64_e32 v[28:29], s[26:27]
	v_mov_b64_e32 v[26:27], s[24:25]
	v_mov_b64_e32 v[24:25], s[22:23]
	v_mov_b64_e32 v[22:23], s[20:21]
	v_mov_b64_e32 v[20:21], s[18:19]
	v_mov_b64_e32 v[18:19], s[16:17]
	s_waitcnt vmcnt(3) lgkmcnt(1)
; #define LAS __attribute__((address_space(3)))
; #define MFMA32(a, b, c) __builtin_amdgcn_mfma_f32_32x32x16_bf16((a), (b), (c), 0, 0, 0)
; __device__ __forceinline__ void route_task(int task, int tl0, const bf16* QP  , const LAS bf16* KHL, LAS unsigned short* EL, LAS float* GL, int lane) {
;     ...
;         for (int kt = 0; kt < 4; ++kt) {
;             f32x16 X;
; #pragma unroll
;             for (int i = 0; i < 16; ++i) X[i] = 8.f;
;             const LAS bf16* khp = KHL + (half * 128 + 32 * kt + r) * 72 + 8 * hi;
; #pragma unroll
;             for (int ks = 0; ks < 4; ++ks) {
;                 const bf16x8 kh = lds8(khp + 16 * ks);
;                 X = MFMA32(kh, qa[half][ks], X);
;             }
;             int grp[16];
; #pragma unroll
;             for (int i = 0; i < 16; ++i) grp[i] = (int)((__float_as_uint(X[i]) | 127u) - (unsigned)(32 * kt + (i & 3) + 8 * (i >> 2)));
;             sort16_desc(grp);
	s_nop 0
	v_mfma_f32_32x32x16_bf16 v[34:49], v[50:53], v[78:81], v[18:33]
	ds_read_b128 v[50:53], v94 offset:64
	ds_read_b128 v[124:127], v94 offset:96
	s_waitcnt vmcnt(2) lgkmcnt(2)
	v_mfma_f32_32x32x16_bf16 v[34:49], v[54:57], v[74:77], v[34:49]
	s_waitcnt vmcnt(1) lgkmcnt(1)
	v_mfma_f32_32x32x16_bf16 v[34:49], v[50:53], v[70:73], v[34:49]
	s_waitcnt vmcnt(0)
	v_mov_b32_e32 v62, v166
	v_mov_b32_e32 v63, v167
	v_mov_b32_e32 v64, v168
	v_mov_b32_e32 v65, v169
	v_mov_b32_e32 v58, v170
	v_mov_b32_e32 v59, v171
	v_mov_b32_e32 v60, v172
	v_mov_b32_e32 v61, v173
	v_mov_b32_e32 v54, v174
	v_mov_b32_e32 v55, v175
	v_mov_b32_e32 v56, v176
	v_mov_b32_e32 v57, v177
	v_mov_b32_e32 v50, v178
	v_mov_b32_e32 v51, v179
	v_mov_b32_e32 v52, v180
	v_mov_b32_e32 v53, v181
	s_waitcnt vmcnt(4) lgkmcnt(0)
	v_mfma_f32_32x32x16_bf16 v[34:49], v[124:127], v[66:69], v[34:49]
	s_nop 11
	v_bitop3_b32 v37, v37, s42, 3 bitop3:0x56
	v_bitop3_b32 v48, v48, s42, 26 bitop3:0x56
	v_bitop3_b32 v38, v38, s42, 8 bitop3:0x56
	v_bitop3_b32 v42, v42, s42, 16 bitop3:0x56
	v_bitop3_b32 v47, v47, s42, 25 bitop3:0x56
	v_bitop3_b32 v39, v39, s42, 9 bitop3:0x56
	v_bitop3_b32 v40, v40, s42, 10 bitop3:0x56
	v_bitop3_b32 v43, v43, s42, 17 bitop3:0x56
	v_bitop3_b32 v44, v44, s42, 18 bitop3:0x56
	v_bitop3_b32 v36, v36, s42, 2 bitop3:0x56
	v_bitop3_b32 v49, v49, s42, 27 bitop3:0x56
	v_bitop3_b32 v41, v41, s42, 11 bitop3:0x56
	v_bitop3_b32 v45, v45, s42, 19 bitop3:0x56
	v_bitop3_b32 v35, v35, s42, 1 bitop3:0x56
	v_bitop3_b32 v46, v46, s42, 24 bitop3:0x56
	v_or_b32_e32 v34, 0x7f, v34
	v_max_i32_e32 v82, v37, v48
	v_max_i32_e32 v124, v38, v42
	v_max_i32_e32 v126, v34, v47
	v_max_i32_e32 v127, v39, v40
	v_min_i32_e32 v130, v43, v44
	v_min_i32_e32 v131, v36, v49
	v_min_i32_e32 v133, v41, v45
	v_min_i32_e32 v134, v35, v46
	v_min_i32_e32 v39, v39, v40
	v_min_i32_e32 v34, v34, v47
	v_min_i32_e32 v38, v38, v42
	v_min_i32_e32 v37, v37, v48
	v_max_i32_e32 v35, v35, v46
	v_max_i32_e32 v41, v41, v45
	v_max_i32_e32 v36, v36, v49
	v_max_i32_e32 v43, v43, v44
	v_min_i32_e32 v125, v82, v124
	v_min_i32_e32 v128, v126, v127
	v_max_i32_e32 v132, v130, v131
	v_max_i32_e32 v135, v133, v134
	v_max_i32_e32 v40, v39, v34
	v_max_i32_e32 v42, v38, v37
	v_min_i32_e32 v45, v35, v41
	v_min_i32_e32 v44, v36, v43
	v_min_i32_e32 v129, v125, v128
	v_max_i32_e32 v47, v40, v42
	v_max_i32_e32 v46, v45, v44
	v_min_i32_e32 v40, v40, v42
	v_min_i32_e32 v42, v45, v44
	v_max_i32_e32 v45, v125, v128
	v_max_i32_e32 v125, v132, v135
	v_min_i32_e32 v128, v45, v125
	v_min_i32_e32 v34, v39, v34
	v_max_i32_e32 v39, v126, v127
	v_max_i32_e32 v35, v35, v41
	v_max_i32_e32 v41, v82, v124
	v_max_i32_e32 v148, v45, v125
	ds_read_b128 v[124:127], v95
	v_max_i32_e32 v44, v40, v42
	v_min_i32_e32 v138, v40, v42
	v_min_i32_e32 v40, v133, v134
	v_min_i32_e32 v37, v38, v37
	v_min_i32_e32 v38, v130, v131
	v_max_i32_e32 v36, v36, v43
	v_min_i32_e32 v136, v132, v135
	v_min_i32_e32 v133, v40, v34
	v_min_i32_e32 v134, v37, v38
	v_max_i32_e32 v34, v40, v34
	v_max_i32_e32 v37, v37, v38
	v_min_i32_e32 v40, v39, v35
	v_min_i32_e32 v42, v36, v41
	v_max_i32_e32 v144, v39, v35
	v_max_i32_e32 v145, v36, v41
	v_max_i32_e32 v137, v129, v136
	v_min_i32_e32 v136, v129, v136
	v_max_i32_e32 v140, v133, v134
	v_min_i32_e32 v141, v34, v37
	v_max_i32_e32 v143, v40, v42
	v_min_i32_e32 v146, v144, v145
	v_max_i32_e32 v149, v47, v46
	v_min_i32_e32 v48, v47, v46
	v_max_i32_e32 v139, v138, v136
	v_max_i32_e32 v142, v140, v141
	v_min_i32_e32 v43, v40, v42
	v_max_i32_e32 v34, v34, v37
	v_min_i32_e32 v147, v143, v146
	v_min_i32_e32 v150, v148, v149
	v_min_i32_e32 v49, v137, v48
	v_min_i32_e32 v132, v44, v128
	v_max_i32_e32 v38, v139, v142
	v_min_i32_e32 v37, v43, v34
	v_max_i32_e32 v34, v43, v34
	v_min_i32_e32 v35, v147, v150
	v_max_i32_e32 v39, v137, v48
	v_max_i32_e32 v40, v44, v128
	v_max_i32_e32 v135, v49, v132
	v_max_i32_e32 v82, v38, v37
	v_min_i32_e32 v36, v34, v35
	v_min_i32_e32 v41, v39, v40
	v_max_i32_e32 v129, v135, v82
	v_min_i32_e32 v42, v36, v41
	v_min_i32_e32 v137, v129, v42
	v_max_i32_e32 v159, v129, v42
	ds_read_b128 v[128:131], v95 offset:32
	v_min_i32_e32 v82, v135, v82
	v_min_i32_e32 v132, v49, v132
	v_min_i32_e32 v135, v38, v37
	v_max_i32_e32 v154, v34, v35
	v_max_i32_e32 v155, v39, v40
	v_max_i32_e32 v157, v36, v41
	s_waitcnt lgkmcnt(1)
	v_mfma_f32_32x32x16_bf16 v[34:49], v[124:127], v[78:81], v[18:33]
	ds_read_b128 v[124:127], v95 offset:64
	v_max_i32_e32 v151, v132, v135
	v_max_i32_e32 v152, v82, v151
	v_min_i32_e32 v136, v138, v136
	v_min_i32_e32 v138, v140, v141
	v_min_i32_e32 v82, v82, v151
	v_max_i32_e32 v147, v147, v150
	s_waitcnt lgkmcnt(1)
	v_mfma_f32_32x32x16_bf16 v[34:49], v[128:131], v[74:77], v[34:49]
	ds_read_b128 v[128:131], v95 offset:96
	v_max_i32_e32 v143, v143, v146
	v_min_i32_e32 v133, v133, v134
	v_min_i32_e32 v156, v154, v155
	v_max_i32_e32 v140, v136, v138
	v_min_i32_e32 v139, v139, v142
	v_max_i32_e32 v142, v154, v155
	s_waitcnt lgkmcnt(1)
	v_mfma_f32_32x32x16_bf16 v[34:49], v[124:127], v[70:73], v[34:49]
	v_max_i32_e32 v124, v148, v149
	v_min_i32_e32 v136, v136, v138
	v_max_i32_e32 v141, v140, v139
	v_min_i32_e32 v139, v140, v139
	v_min_i32_e32 v125, v143, v124
	v_min_i32_e32 v158, v156, v157
	v_min_i32_e32 v132, v132, v135
	s_waitcnt lgkmcnt(0)
; #define LAS __attribute__((address_space(3)))
; #define MFMA32(a, b, c) __builtin_amdgcn_mfma_f32_32x32x16_bf16((a), (b), (c), 0, 0, 0)
; __device__ __forceinline__ void route_task(int task, int tl0, const bf16* QP  , const LAS bf16* KHL, LAS unsigned short* EL, LAS float* GL, int lane) {
;     ...
;         for (int kt = 0; kt < 4; ++kt) {
;             f32x16 X;
; #pragma unroll
;             for (int i = 0; i < 16; ++i) X[i] = 8.f;
;             const LAS bf16* khp = KHL + (half * 128 + 32 * kt + r) * 72 + 8 * hi;
; #pragma unroll
;             for (int ks = 0; ks < 4; ++ks) {
;                 const bf16x8 kh = lds8(khp + 16 * ks);
;                 X = MFMA32(kh, qa[half][ks], X);
;             }
;             int grp[16];
; #pragma unroll
;             for (int i = 0; i < 16; ++i) grp[i] = (int)((__float_as_uint(X[i]) | 127u) - (unsigned)(32 * kt + (i & 3) + 8 * (i >> 2)));
;             sort16_desc(grp);
;             if (kt == 0) {
; #pragma unroll
;                 for (int i = 0; i < 16; ++i) cur[i] = grp[i];
;             } else merge16_desc(cur, grp);
	v_mfma_f32_32x32x16_bf16 v[34:49], v[128:131], v[66:69], v[34:49]
	v_min_i32_e32 v126, v147, v125
	v_min_i32_e32 v153, v137, v152
	v_min_i32_e32 v160, v158, v159
	v_min_i32_e32 v135, v141, v132
	v_min_i32_e32 v127, v142, v126
	s_nop 6
	v_bitop3_b32 v37, v37, s42, 35 bitop3:0x56
	v_bitop3_b32 v48, v48, s42, 58 bitop3:0x56
	v_bitop3_b32 v38, v38, s42, 40 bitop3:0x56
	v_bitop3_b32 v42, v42, s42, 48 bitop3:0x56
	v_bitop3_b32 v34, v34, s42, 32 bitop3:0x56
	v_bitop3_b32 v47, v47, s42, 57 bitop3:0x56
	v_bitop3_b32 v39, v39, s42, 41 bitop3:0x56
	v_bitop3_b32 v40, v40, s42, 42 bitop3:0x56
	v_bitop3_b32 v43, v43, s42, 49 bitop3:0x56
	v_bitop3_b32 v44, v44, s42, 50 bitop3:0x56
	v_bitop3_b32 v36, v36, s42, 34 bitop3:0x56
	v_bitop3_b32 v49, v49, s42, 59 bitop3:0x56
	v_bitop3_b32 v41, v41, s42, 43 bitop3:0x56
	v_bitop3_b32 v45, v45, s42, 51 bitop3:0x56
	v_bitop3_b32 v35, v35, s42, 33 bitop3:0x56
	v_bitop3_b32 v46, v46, s42, 56 bitop3:0x56
	v_max_i32_e32 v128, v37, v48
	v_max_i32_e32 v129, v38, v42
	v_max_i32_e32 v131, v34, v47
	v_max_i32_e32 v134, v39, v40
	v_min_i32_e32 v146, v43, v44
	v_min_i32_e32 v148, v36, v49
	v_min_i32_e32 v150, v41, v45
	v_min_i32_e32 v151, v35, v46
	v_min_i32_e32 v39, v39, v40
	v_min_i32_e32 v34, v34, v47
	v_min_i32_e32 v38, v38, v42
	v_min_i32_e32 v37, v37, v48
	v_max_i32_e32 v35, v35, v46
	v_max_i32_e32 v41, v41, v45
	v_max_i32_e32 v36, v36, v49
	v_max_i32_e32 v43, v43, v44
	v_min_i32_e32 v130, v128, v129
	v_min_i32_e32 v138, v131, v134
	v_max_i32_e32 v149, v146, v148
	v_max_i32_e32 v154, v150, v151
	v_max_i32_e32 v40, v39, v34
	v_max_i32_e32 v42, v38, v37
	v_min_i32_e32 v45, v35, v41
	v_min_i32_e32 v44, v36, v43
	v_min_i32_e32 v150, v150, v151
	v_min_i32_e32 v34, v39, v34
	v_min_i32_e32 v37, v38, v37
	v_min_i32_e32 v38, v146, v148
	v_max_i32_e32 v131, v131, v134
	v_max_i32_e32 v35, v35, v41
	v_max_i32_e32 v36, v36, v43
	v_max_i32_e32 v43, v128, v129
	v_min_i32_e32 v140, v130, v138
	v_min_i32_e32 v155, v149, v154
	v_max_i32_e32 v47, v40, v42
	v_max_i32_e32 v46, v45, v44
	v_min_i32_e32 v40, v40, v42
	v_min_i32_e32 v42, v45, v44
	v_max_i32_e32 v45, v130, v138
	v_max_i32_e32 v130, v149, v154
	v_min_i32_e32 v39, v150, v34
	v_min_i32_e32 v146, v37, v38
	v_max_i32_e32 v34, v150, v34
	v_max_i32_e32 v37, v37, v38
	v_min_i32_e32 v41, v131, v35
	v_min_i32_e32 v128, v36, v43
	v_max_i32_e32 v35, v131, v35
	v_max_i32_e32 v36, v36, v43
	v_min_i32_e32 v48, v47, v46
	v_max_i32_e32 v44, v40, v42
	v_min_i32_e32 v138, v45, v130
	v_min_i32_e32 v40, v40, v42
	v_min_i32_e32 v42, v140, v155
	v_max_i32_e32 v148, v39, v146
	v_min_i32_e32 v38, v34, v37
	v_min_i32_e32 v129, v41, v128
	v_max_i32_e32 v41, v41, v128
	v_min_i32_e32 v43, v35, v36
	v_max_i32_e32 v45, v45, v130
	v_max_i32_e32 v46, v47, v46
	v_max_i32_e32 v161, v140, v155
	v_max_i32_e32 v140, v40, v42
	v_max_i32_e32 v150, v148, v38
	v_max_i32_e32 v34, v34, v37
	v_min_i32_e32 v128, v41, v43
	v_min_i32_e32 v47, v45, v46
	v_min_i32_e32 v49, v161, v48
	v_min_i32_e32 v149, v44, v138
	v_max_i32_e32 v151, v140, v150
	v_min_i32_e32 v37, v129, v34
	v_max_i32_e32 v34, v129, v34
	v_min_i32_e32 v129, v128, v47
	v_max_i32_e32 v48, v161, v48
	v_max_i32_e32 v44, v44, v138
	v_max_i32_e32 v154, v49, v149
	v_max_i32_e32 v134, v151, v37
	v_min_i32_e32 v130, v34, v129
	v_min_i32_e32 v131, v48, v44
	v_min_i32_e32 v49, v49, v149
	v_min_i32_e32 v37, v151, v37
	v_max_i32_e32 v34, v34, v129
	v_max_i32_e32 v44, v48, v44
	v_min_i32_e32 v40, v40, v42
	v_min_i32_e32 v38, v148, v38
	v_max_i32_e32 v41, v41, v43
	v_max_i32_e32 v43, v45, v46
	v_max_i32_e32 v155, v154, v134
	v_min_i32_e32 v138, v130, v131
	v_min_i32_e32 v134, v154, v134
	v_max_i32_e32 v149, v49, v37
	v_min_i32_e32 v48, v34, v44
	v_max_i32_e32 v129, v130, v131
	v_max_i32_e32 v42, v40, v38
	v_min_i32_e32 v140, v140, v150
	v_max_i32_e32 v34, v34, v44
	v_max_i32_e32 v44, v128, v47
	v_min_i32_e32 v45, v41, v43
	v_min_i32_e32 v161, v155, v138
	v_max_i32_e32 v151, v134, v149
	v_min_i32_e32 v130, v48, v129
	v_max_i32_e32 v131, v155, v138
	v_max_i32_e32 v148, v42, v140
	v_min_i32_e32 v37, v49, v37
	v_min_i32_e32 v46, v44, v45
	v_min_i32_e32 v154, v161, v151
	v_min_i32_e32 v138, v130, v131
	v_min_i32_e32 v49, v148, v37
	v_min_i32_e32 v134, v134, v149
	v_min_i32_e32 v47, v34, v46
	v_min_i32_e32 v42, v42, v140
	v_min_i32_e32 v38, v40, v38
	v_min_i32_e32 v39, v39, v146
	v_max3_i32 v39, v144, v145, v39
	v_max3_i32 v38, v143, v124, v38
	v_max3_i32 v40, v147, v125, v42
	v_max3_i32 v42, v142, v126, v49
	v_max3_i32 v37, v127, v148, v37
	v_max3_i32 v49, v156, v157, v134
	v_max3_i32 v124, v158, v159, v154
	v_max3_i32 v125, v160, v161, v151
	v_max3_i32 v126, v137, v152, v138
	v_max3_i32 v127, v153, v130, v131
	v_max3_i32 v48, v82, v48, v129
	v_max3_i32 v47, v141, v132, v47
	v_max3_i32 v34, v135, v34, v46
	v_max3_i32 v44, v139, v44, v45
	v_max3_i32 v41, v136, v41, v43
	v_max3_i32 v35, v133, v35, v36
	v_max_i32_e32 v36, v39, v126
	v_min_i32_e32 v39, v39, v126
	v_max_i32_e32 v43, v38, v127
	v_min_i32_e32 v38, v38, v127
	v_max_i32_e32 v45, v40, v48
	v_min_i32_e32 v40, v40, v48
	v_max_i32_e32 v46, v42, v47
	v_min_i32_e32 v42, v42, v47
	v_max_i32_e32 v47, v37, v34
	v_min_i32_e32 v34, v37, v34
	v_max_i32_e32 v37, v49, v44
	v_min_i32_e32 v44, v49, v44
	v_max_i32_e32 v48, v124, v41
	v_min_i32_e32 v41, v124, v41
	v_max_i32_e32 v49, v125, v35
	v_min_i32_e32 v35, v125, v35
	ds_read_b128 v[124:127], v94 offset:9216
	ds_read_b128 v[128:131], v94 offset:9248
	v_max_i32_e32 v82, v36, v47
	v_min_i32_e32 v132, v36, v47
	v_max_i32_e32 v36, v43, v37
	v_min_i32_e32 v133, v43, v37
	v_max_i32_e32 v37, v45, v48
	v_max_i32_e32 v43, v46, v49
	v_min_i32_e32 v134, v45, v48
	v_min_i32_e32 v135, v46, v49
	v_max_i32_e32 v136, v39, v34
	v_min_i32_e32 v137, v39, v34
	v_max_i32_e32 v138, v38, v44
	v_min_i32_e32 v139, v38, v44
	v_max_i32_e32 v140, v40, v41
	v_min_i32_e32 v141, v40, v41
	v_max_i32_e32 v142, v42, v35
	v_min_i32_e32 v143, v42, v35
	v_max_i32_e32 v144, v82, v37
	v_min_i32_e32 v82, v82, v37
	v_max_i32_e32 v145, v36, v43
	v_min_i32_e32 v146, v36, v43
	s_waitcnt lgkmcnt(1)
; #define LAS __attribute__((address_space(3)))
; #define MFMA32(a, b, c) __builtin_amdgcn_mfma_f32_32x32x16_bf16((a), (b), (c), 0, 0, 0)
; __device__ __forceinline__ void route_task(int task, int tl0, const bf16* QP  , const LAS bf16* KHL, LAS unsigned short* EL, LAS float* GL, int lane) {
;     ...
;         for (int kt = 0; kt < 4; ++kt) {
;             f32x16 X;
; #pragma unroll
;             for (int i = 0; i < 16; ++i) X[i] = 8.f;
;             const LAS bf16* khp = KHL + (half * 128 + 32 * kt + r) * 72 + 8 * hi;
; #pragma unroll
;             for (int ks = 0; ks < 4; ++ks) {
;                 const bf16x8 kh = lds8(khp + 16 * ks);
;                 X = MFMA32(kh, qa[half][ks], X);
;             }
;             int grp[16];
; #pragma unroll
;             for (int i = 0; i < 16; ++i) grp[i] = (int)((__float_as_uint(X[i]) | 127u) - (unsigned)(32 * kt + (i & 3) + 8 * (i >> 2)));
;             sort16_desc(grp);
;             if (kt == 0) {
; #pragma unroll
;                 for (int i = 0; i < 16; ++i) cur[i] = grp[i];
;             } else merge16_desc(cur, grp);
	v_mfma_f32_32x32x16_bf16 v[34:49], v[124:127], v[78:81], v[18:33]
	ds_read_b128 v[124:127], v94 offset:9280
	v_max_i32_e32 v147, v132, v134
	v_min_i32_e32 v132, v132, v134
	v_max_i32_e32 v134, v133, v135
	v_min_i32_e32 v133, v133, v135
	v_max_i32_e32 v135, v136, v140
	v_min_i32_e32 v136, v136, v140
	s_waitcnt lgkmcnt(1)
	v_mfma_f32_32x32x16_bf16 v[34:49], v[128:131], v[74:77], v[34:49]
	ds_read_b128 v[128:131], v94 offset:9312
	v_max_i32_e32 v140, v138, v142
	v_min_i32_e32 v138, v138, v142
	v_max_i32_e32 v142, v137, v141
	v_min_i32_e32 v137, v137, v141
	v_max_i32_e32 v141, v139, v143
	v_min_i32_e32 v139, v139, v143
	s_waitcnt lgkmcnt(1)
	v_mfma_f32_32x32x16_bf16 v[34:49], v[124:127], v[70:73], v[34:49]
	v_min_i32_e32 v143, v144, v145
	v_min_i32_e32 v124, v82, v146
	v_min_i32_e32 v127, v135, v140
	v_min_i32_e32 v125, v147, v134
	v_min_i32_e32 v126, v132, v133
	v_min_i32_e32 v149, v142, v141
	v_min_i32_e32 v148, v136, v138
	s_waitcnt lgkmcnt(0)
	v_mfma_f32_32x32x16_bf16 v[34:49], v[128:131], v[66:69], v[34:49]
	v_min_i32_e32 v150, v137, v139
	s_nop 10
	v_and_or_b32 v37, v37, s43, 60
	v_and_or_b32 v48, v48, s43, 37
	v_and_or_b32 v38, v38, s43, 55
	v_and_or_b32 v42, v42, s43, 47
	v_bitop3_b32 v34, v34, s42, 64 bitop3:0x56
	v_and_or_b32 v47, v47, s43, 38
	v_and_or_b32 v39, v39, s43, 54
	v_and_or_b32 v40, v40, s43, 53
	v_and_or_b32 v43, v43, s43, 46
	v_and_or_b32 v44, v44, s43, 45
	v_and_or_b32 v36, v36, s43, 61
	v_and_or_b32 v49, v49, s43, 36
	v_and_or_b32 v41, v41, s43, 52
	v_and_or_b32 v45, v45, s43, 44
	v_and_or_b32 v35, v35, s43, 62
	v_and_or_b32 v46, v46, s43, 39
	v_max_i32_e32 v128, v37, v48
	v_max_i32_e32 v129, v38, v42
	v_max_i32_e32 v131, v34, v47
	v_max_i32_e32 v151, v39, v40
	v_min_i32_e32 v154, v43, v44
	v_min_i32_e32 v155, v36, v49
	v_min_i32_e32 v157, v41, v45
	v_min_i32_e32 v158, v35, v46
	v_min_i32_e32 v39, v39, v40
	v_min_i32_e32 v34, v34, v47
	v_min_i32_e32 v38, v38, v42
	v_min_i32_e32 v37, v37, v48
	v_max_i32_e32 v35, v35, v46
	v_max_i32_e32 v41, v41, v45
	v_max_i32_e32 v36, v36, v49
	v_max_i32_e32 v43, v43, v44
	v_min_i32_e32 v130, v128, v129
	v_min_i32_e32 v152, v131, v151
	v_max_i32_e32 v156, v154, v155
	v_max_i32_e32 v159, v157, v158
	v_max_i32_e32 v40, v39, v34
	v_max_i32_e32 v42, v38, v37
	v_min_i32_e32 v45, v35, v41
	v_min_i32_e32 v44, v36, v43
	v_min_i32_e32 v157, v157, v158
	v_min_i32_e32 v34, v39, v34
	v_min_i32_e32 v37, v38, v37
	v_min_i32_e32 v38, v154, v155
	v_max_i32_e32 v131, v131, v151
	v_max_i32_e32 v35, v35, v41
	v_max_i32_e32 v36, v36, v43
	v_max_i32_e32 v43, v128, v129
	v_min_i32_e32 v153, v130, v152
	v_min_i32_e32 v160, v156, v159
	v_max_i32_e32 v47, v40, v42
	v_max_i32_e32 v46, v45, v44
	v_min_i32_e32 v40, v40, v42
	v_min_i32_e32 v42, v45, v44
	v_max_i32_e32 v45, v130, v152
	v_max_i32_e32 v130, v156, v159
	v_min_i32_e32 v39, v157, v34
	v_min_i32_e32 v154, v37, v38
	v_max_i32_e32 v34, v157, v34
	v_max_i32_e32 v37, v37, v38
	v_min_i32_e32 v41, v131, v35
	v_min_i32_e32 v128, v36, v43
	v_max_i32_e32 v35, v131, v35
	v_max_i32_e32 v36, v36, v43
	v_min_i32_e32 v48, v47, v46
	v_max_i32_e32 v44, v40, v42
	v_min_i32_e32 v152, v45, v130
	v_min_i32_e32 v40, v40, v42
	v_min_i32_e32 v42, v153, v160
	v_max_i32_e32 v155, v39, v154
	v_min_i32_e32 v38, v34, v37
	v_min_i32_e32 v129, v41, v128
	v_max_i32_e32 v41, v41, v128
	v_min_i32_e32 v43, v35, v36
	v_max_i32_e32 v45, v45, v130
	v_max_i32_e32 v46, v47, v46
	v_max_i32_e32 v161, v153, v160
	v_max_i32_e32 v153, v40, v42
	v_max_i32_e32 v157, v155, v38
	v_max_i32_e32 v34, v34, v37
	v_min_i32_e32 v128, v41, v43
	v_min_i32_e32 v47, v45, v46
	v_min_i32_e32 v49, v161, v48
	v_min_i32_e32 v156, v44, v152
	v_max_i32_e32 v158, v153, v157
	v_min_i32_e32 v37, v129, v34
	v_max_i32_e32 v34, v129, v34
	v_min_i32_e32 v129, v128, v47
	v_max_i32_e32 v48, v161, v48
	v_max_i32_e32 v44, v44, v152
	v_min_i32_e32 v40, v40, v42
	v_min_i32_e32 v38, v155, v38
	v_max_i32_e32 v159, v49, v156
	v_max_i32_e32 v151, v158, v37
	v_min_i32_e32 v130, v34, v129
	v_min_i32_e32 v131, v48, v44
	v_min_i32_e32 v49, v49, v156
	v_min_i32_e32 v37, v158, v37
	v_max_i32_e32 v34, v34, v129
	v_max_i32_e32 v44, v48, v44
	v_max_i32_e32 v42, v40, v38
	v_min_i32_e32 v153, v153, v157
	v_max_i32_e32 v160, v159, v151
	v_min_i32_e32 v152, v130, v131
	v_max_i32_e32 v156, v49, v37
	v_min_i32_e32 v48, v34, v44
	v_max_i32_e32 v129, v130, v131
	v_max_i32_e32 v155, v42, v153
	v_min_i32_e32 v37, v49, v37
	v_min_i32_e32 v151, v159, v151
	v_min_i32_e32 v130, v48, v129
	v_max_i32_e32 v131, v160, v152
	v_min_i32_e32 v49, v155, v37
	v_max_i32_e32 v41, v41, v43
	v_max_i32_e32 v43, v45, v46
	v_min_i32_e32 v42, v42, v153
	v_min_i32_e32 v38, v40, v38
	v_min_i32_e32 v161, v160, v152
	v_max_i32_e32 v158, v151, v156
	v_min_i32_e32 v151, v151, v156
	v_max_i32_e32 v34, v34, v44
	v_max_i32_e32 v44, v128, v47
	v_min_i32_e32 v45, v41, v43
	v_max_i32_e32 v40, v41, v43
	v_max_i32_e32 v38, v143, v38
	v_max3_i32 v41, v82, v146, v42
	v_max_i32_e32 v42, v124, v49
	v_max3_i32 v124, v127, v130, v131
	v_min_i32_e32 v46, v44, v45
	v_max_i32_e32 v43, v125, v151
	v_max3_i32 v49, v126, v161, v158
	v_max3_i32 v44, v149, v44, v45
	v_max_i32_e32 v45, v38, v124
	v_min_i32_e32 v38, v38, v124
	ds_read_b128 v[124:127], v96
	v_min_i32_e32 v159, v161, v158
	v_min_i32_e32 v152, v130, v131
	v_max_i32_e32 v37, v155, v37
	v_max_i32_e32 v48, v48, v129
	v_min_i32_e32 v47, v34, v46
	v_max_i32_e32 v34, v34, v46
	v_min_i32_e32 v39, v39, v154
	v_max3_i32 v39, v144, v145, v39
	v_max3_i32 v37, v147, v134, v37
	v_max3_i32 v46, v132, v133, v159
	v_max3_i32 v82, v135, v140, v152
	v_max3_i32 v48, v136, v138, v48
	v_max_i32_e32 v47, v148, v47
	v_max3_i32 v34, v142, v141, v34
	v_max3_i32 v40, v137, v139, v40
	v_max3_i32 v35, v150, v35, v36
	v_max_i32_e32 v36, v39, v82
	v_min_i32_e32 v39, v39, v82
	v_max_i32_e32 v82, v41, v48
	v_min_i32_e32 v41, v41, v48
	v_max_i32_e32 v48, v42, v47
	v_min_i32_e32 v42, v42, v47
	v_max_i32_e32 v47, v37, v34
	v_min_i32_e32 v34, v37, v34
	v_max_i32_e32 v37, v43, v44
	v_min_i32_e32 v43, v43, v44
	v_max_i32_e32 v44, v46, v40
	v_min_i32_e32 v40, v46, v40
	v_max_i32_e32 v46, v49, v35
	v_min_i32_e32 v35, v49, v35
	v_max_i32_e32 v49, v36, v47
	v_min_i32_e32 v132, v36, v47
	v_max_i32_e32 v36, v45, v37
	v_min_i32_e32 v133, v45, v37
	v_max_i32_e32 v37, v82, v44
	v_min_i32_e32 v82, v82, v44
	v_max_i32_e32 v44, v48, v46
	ds_read_b128 v[128:131], v96 offset:32
	v_min_i32_e32 v134, v48, v46
	v_max_i32_e32 v135, v39, v34
	v_min_i32_e32 v136, v39, v34
	v_max_i32_e32 v137, v38, v43
	v_min_i32_e32 v138, v38, v43
	v_max_i32_e32 v139, v41, v40
	v_min_i32_e32 v140, v41, v40
	v_max_i32_e32 v141, v42, v35
	v_min_i32_e32 v142, v42, v35
	v_max_i32_e32 v143, v49, v37
	v_min_i32_e32 v144, v49, v37
	v_max_i32_e32 v145, v36, v44
	v_min_i32_e32 v146, v36, v44
	s_waitcnt lgkmcnt(1)
; #define LAS __attribute__((address_space(3)))
; #define MFMA32(a, b, c) __builtin_amdgcn_mfma_f32_32x32x16_bf16((a), (b), (c), 0, 0, 0)
; __device__ __forceinline__ void route_task(int task, int tl0, const bf16* QP  , const LAS bf16* KHL, LAS unsigned short* EL, LAS float* GL, int lane) {
;     ...
;         for (int kt = 0; kt < 4; ++kt) {
;             f32x16 X;
; #pragma unroll
;             for (int i = 0; i < 16; ++i) X[i] = 8.f;
;             const LAS bf16* khp = KHL + (half * 128 + 32 * kt + r) * 72 + 8 * hi;
; #pragma unroll
;             for (int ks = 0; ks < 4; ++ks) {
;                 const bf16x8 kh = lds8(khp + 16 * ks);
;                 X = MFMA32(kh, qa[half][ks], X);
;             }
;             int grp[16];
; #pragma unroll
;             for (int i = 0; i < 16; ++i) grp[i] = (int)((__float_as_uint(X[i]) | 127u) - (unsigned)(32 * kt + (i & 3) + 8 * (i >> 2)));
;             sort16_desc(grp);
;             if (kt == 0) {
; #pragma unroll
;                 for (int i = 0; i < 16; ++i) cur[i] = grp[i];
;             } else merge16_desc(cur, grp);
	v_mfma_f32_32x32x16_bf16 v[34:49], v[124:127], v[78:81], v[18:33]
	ds_read_b128 v[78:81], v96 offset:64
	v_max_i32_e32 v147, v132, v82
	v_min_i32_e32 v82, v132, v82
	v_max_i32_e32 v132, v137, v141
	v_max_i32_e32 v124, v133, v134
	v_min_i32_e32 v125, v133, v134
	v_max_i32_e32 v126, v135, v139
	s_waitcnt lgkmcnt(1)
	v_mfma_f32_32x32x16_bf16 v[34:49], v[128:131], v[74:77], v[34:49]
	ds_read_b128 v[74:77], v96 offset:96
	v_min_i32_e32 v128, v137, v141
	v_max_i32_e32 v129, v136, v140
	v_min_i32_e32 v130, v136, v140
	v_min_i32_e32 v127, v135, v139
	v_max_i32_e32 v131, v138, v142
	v_min_i32_e32 v133, v138, v142
	s_waitcnt lgkmcnt(1)
	v_mfma_f32_32x32x16_bf16 v[34:49], v[78:81], v[70:73], v[34:49]
	v_min_i32_e32 v134, v143, v145
	v_min_i32_e32 v70, v144, v146
	v_min_i32_e32 v71, v147, v124
	v_min_i32_e32 v72, v82, v125
	v_min_i32_e32 v73, v126, v132
	v_min_i32_e32 v78, v127, v128
	v_min_i32_e32 v79, v129, v131
	s_waitcnt lgkmcnt(0)
	v_mfma_f32_32x32x16_bf16 v[34:49], v[74:77], v[66:69], v[34:49]
	v_min_i32_e32 v80, v130, v133
	s_nop 10
	v_and_or_b32 v41, v41, s43, 20
	v_and_or_b32 v45, v45, s43, 12
	v_and_or_b32 v35, v35, s43, 30
	v_and_or_b32 v46, v46, s43, 7
	v_and_or_b32 v39, v39, s43, 22
	v_and_or_b32 v40, v40, s43, 21
	v_and_or_b32 v34, v34, s43, 31
	v_and_or_b32 v47, v47, s43, 6
	v_and_or_b32 v38, v38, s43, 23
	v_and_or_b32 v42, v42, s43, 15
	v_and_or_b32 v37, v37, s43, 28
	v_and_or_b32 v48, v48, s43, 5
	v_and_or_b32 v43, v43, s43, 14
	v_and_or_b32 v44, v44, s43, 13
	v_and_or_b32 v36, v36, s43, 29
	v_and_or_b32 v49, v49, s43, 4
	v_min_i32_e32 v66, v41, v45
	v_min_i32_e32 v67, v35, v46
	v_min_i32_e32 v69, v39, v40
	v_min_i32_e32 v74, v34, v47
	v_min_i32_e32 v77, v38, v42
	v_min_i32_e32 v81, v37, v48
	v_min_i32_e32 v136, v43, v44
	v_min_i32_e32 v137, v36, v49
	v_max_i32_e32 v34, v34, v47
	v_max_i32_e32 v39, v39, v40
	v_max_i32_e32 v35, v35, v46
	v_max_i32_e32 v41, v41, v45
	v_max_i32_e32 v36, v36, v49
	v_max_i32_e32 v43, v43, v44
	v_max_i32_e32 v37, v37, v48
	v_max_i32_e32 v38, v38, v42
	v_max_i32_e32 v40, v34, v39
	v_max_i32_e32 v45, v35, v41
	v_max_i32_e32 v44, v36, v43
	v_max_i32_e32 v42, v37, v38
	v_min_i32_e32 v46, v40, v45
	v_min_i32_e32 v47, v44, v42
	v_min_i32_e32 v75, v69, v74
	v_min_i32_e32 v48, v46, v47
	v_max_i32_e32 v46, v46, v47
	v_min_i32_e32 v37, v37, v38
	v_min_i32_e32 v34, v34, v39
	v_max_i32_e32 v39, v136, v137
	v_max_i32_e32 v47, v66, v67
	v_max_i32_e32 v69, v69, v74
	v_max_i32_e32 v74, v77, v81
	v_min_i32_e32 v35, v35, v41
	v_min_i32_e32 v36, v36, v43
	v_min_i32_e32 v68, v66, v67
	v_min_i32_e32 v135, v77, v81
	v_min_i32_e32 v138, v136, v137
	v_max_i32_e32 v38, v37, v34
	v_max_i32_e32 v77, v69, v74
	v_max_i32_e32 v41, v35, v36
	v_min_i32_e32 v34, v37, v34
	v_min_i32_e32 v37, v39, v47
	v_min_i32_e32 v76, v68, v75
	v_min_i32_e32 v139, v135, v138
	v_max_i32_e32 v49, v68, v75
	v_max_i32_e32 v68, v135, v138
	v_max_i32_e32 v40, v40, v45
	v_max_i32_e32 v42, v44, v42
	v_max_i32_e32 v66, v39, v47
	v_max_i32_e32 v43, v77, v41
	v_max_i32_e32 v39, v34, v37
	v_min_i32_e32 v41, v77, v41
	v_min_i32_e32 v69, v69, v74
	v_min_i32_e32 v35, v35, v36
	v_max_i32_e32 v75, v49, v68
	v_min_i32_e32 v44, v40, v42
	v_max_i32_e32 v67, v38, v66
	v_max_i32_e32 v47, v39, v41
	v_max_i32_e32 v36, v69, v35
	v_min_i32_e32 v39, v39, v41
	v_min_i32_e32 v35, v69, v35
	v_min_i32_e32 v34, v34, v37
	v_max_i32_e32 v41, v76, v139
	v_min_i32_e32 v49, v49, v68
	v_min_i32_e32 v45, v46, v44
	v_min_i32_e32 v81, v67, v43
	v_min_i32_e32 v38, v38, v66
	v_max_i32_e32 v37, v35, v34
	v_max_i32_e32 v68, v41, v49
	v_max_i32_e32 v135, v48, v75
	v_min_i32_e32 v136, v45, v81
	v_max_i32_e32 v66, v36, v38
	v_min_i32_e32 v36, v36, v38
	v_max_i32_e32 v69, v37, v68
	v_min_i32_e32 v48, v48, v75
	v_max_i32_e32 v137, v135, v136
	v_max_i32_e32 v74, v47, v66
	v_min_i32_e32 v135, v135, v136
	v_min_i32_e32 v47, v47, v66
	v_max_i32_e32 v38, v39, v36
	v_max_i32_e32 v75, v69, v48
	v_min_i32_e32 v34, v35, v34
	v_min_i32_e32 v35, v41, v49
	v_min_i32_e32 v36, v39, v36
	v_min_i32_e32 v39, v69, v48
	v_max_i32_e32 v44, v46, v44
	v_max_i32_e32 v43, v67, v43
	v_min_i32_e32 v140, v76, v139
	v_min_i32_e32 v77, v137, v74
	v_max_i32_e32 v66, v135, v47
	v_max_i32_e32 v76, v38, v75
	v_min_i32_e32 v47, v135, v47
	v_max_i32_e32 v41, v34, v35
	v_min_i32_e32 v37, v37, v68
	v_min_i32_e32 v48, v36, v39
	v_max_i32_e32 v45, v45, v81
	v_min_i32_e32 v46, v44, v43
	v_min_i32_e32 v38, v38, v75
	v_max_i32_e32 v36, v36, v39
	v_min_i32_e32 v136, v77, v66
	v_max_i32_e32 v135, v76, v47
	v_max_i32_e32 v49, v41, v37
	v_max_i32_e32 v69, v137, v74
	v_min_i32_e32 v67, v45, v46
	v_min_i32_e32 v47, v76, v47
	v_max_i32_e32 v39, v38, v36
	v_min_i32_e32 v138, v136, v135
	v_max_i32_e32 v68, v49, v48
	v_max_i32_e32 v74, v69, v67
	v_min_i32_e32 v37, v41, v37
	v_max_i32_e32 v41, v77, v66
	v_min_i32_e32 v75, v47, v39
	v_max_i32_e32 v43, v44, v43
	v_min_i32_e32 v34, v34, v35
	v_min_i32_e32 v36, v38, v36
	v_min_i32_e32 v48, v49, v48
	v_min_i32_e32 v49, v69, v67
	v_max3_i32 v140, v143, v145, v140
	v_max3_i32 v126, v126, v132, v138
	v_max3_i32 v68, v147, v124, v68
	v_max3_i32 v74, v129, v131, v74
	v_max3_i32 v37, v144, v146, v37
	v_max3_i32 v41, v127, v128, v41
	v_max3_i32 v75, v82, v125, v75
	v_max3_i32 v43, v130, v133, v43
	v_max_i32_e32 v34, v134, v34
	v_max3_i32 v35, v73, v136, v135
	v_max_i32_e32 v36, v71, v36
	v_max3_i32 v38, v79, v45, v46
	v_max_i32_e32 v48, v70, v48
	v_max_i32_e32 v49, v78, v49
	v_max3_i32 v39, v72, v47, v39
	v_max3_i32 v40, v80, v40, v42
	v_min_i32_e32 v81, v68, v74
	v_min_i32_e32 v66, v37, v41
	v_min_i32_e32 v73, v34, v35
	v_min_i32_e32 v45, v36, v38
	v_min_i32_e32 v42, v39, v40
	v_max_i32_e32 v71, v140, v126
; #define LAS __attribute__((address_space(3)))
; #define MFMA32(a, b, c) __builtin_amdgcn_mfma_f32_32x32x16_bf16((a), (b), (c), 0, 0, 0)
; __device__ __forceinline__ void route_task(int task, int tl0, const bf16* QP  , const LAS bf16* KHL, LAS unsigned short* EL, LAS float* GL, int lane) {
;     ...
;     for (int half = 0; half < 2; ++half) {
;         int cur[16];
; #pragma unroll
;         for (int kt = 0; kt < 4; ++kt) {
;             f32x16 X;
; #pragma unroll
;             for (int i = 0; i < 16; ++i) X[i] = 8.f;
;             const LAS bf16* khp = KHL + (half * 128 + 32 * kt + r) * 72 + 8 * hi;
; #pragma unroll
;             for (int ks = 0; ks < 4; ++ks) {
;                 const bf16x8 kh = lds8(khp + 16 * ks);
;                 X = MFMA32(kh, qa[half][ks], X);
;     ...
;         { const unsigned h4 = 4u * (unsigned)hi;
; #pragma unroll
;           for (int i = 0; i < 16; ++i) cur[i] -= (int)h4; }
;         int oth[16];
; #pragma unroll
;         for (int i = 0; i < 16; ++i) oth[i] = __shfl_xor(cur[i], 32);
;         merge16_desc(cur, oth);
; #pragma unroll
;         for (int i = 0; i < 16; ++i) top[half][i] = cur[i];
	v_max_i32_e32 v68, v68, v74
	v_max_i32_e32 v37, v37, v41
	v_max_i32_e32 v41, v75, v43
	v_max_i32_e32 v34, v34, v35
	v_max_i32_e32 v35, v36, v38
	v_max_i32_e32 v38, v48, v49
	v_max_i32_e32 v39, v39, v40
	v_min_i32_e32 v44, v75, v43
	v_max_i32_e32 v72, v71, v68
	v_max_i32_e32 v43, v37, v41
	v_max_i32_e32 v36, v34, v35
	v_max_i32_e32 v40, v38, v39
	v_min_i32_e32 v67, v48, v49
	v_max_i32_e32 v74, v72, v43
	v_max_i32_e32 v48, v36, v40
	v_min_i32_e32 v43, v72, v43
	v_min_i32_e32 v36, v36, v40
	v_max_i32_e32 v40, v43, v36
	v_min_i32_e32 v36, v43, v36
	v_min_i32_e32 v43, v71, v68
	v_min_i32_e32 v37, v37, v41
	v_min_i32_e32 v34, v34, v35
	v_min_i32_e32 v35, v38, v39
	v_min_i32_e32 v132, v140, v126
	v_max_i32_e32 v41, v43, v37
	v_max_i32_e32 v38, v34, v35
	v_min_i32_e32 v37, v43, v37
	v_min_i32_e32 v34, v34, v35
	v_min_i32_e32 v76, v66, v44
	v_min_i32_e32 v47, v67, v42
	v_max_i32_e32 v39, v41, v38
	v_min_i32_e32 v38, v41, v38
	v_max_i32_e32 v35, v37, v34
	v_min_i32_e32 v34, v37, v34
	v_max_i32_e32 v37, v132, v81
	v_max_i32_e32 v41, v66, v44
	v_max_i32_e32 v44, v73, v45
	v_max_i32_e32 v42, v67, v42
	v_min_i32_e32 v124, v132, v81
	v_min_i32_e32 v46, v73, v45
	v_max_i32_e32 v43, v37, v41
	v_min_i32_e32 v37, v37, v41
	v_min_i32_e32 v41, v44, v42
	v_min_i32_e32 v77, v124, v76
	v_min_i32_e32 v69, v46, v47
	v_max_i32_e32 v45, v44, v42
	v_max_i32_e32 v42, v37, v41
	v_min_i32_e32 v37, v37, v41
	v_max_i32_e32 v41, v124, v76
	v_max_i32_e32 v44, v46, v47
	v_min_i32_e32 v70, v77, v69
	v_max_i32_e32 v49, v74, v48
	v_min_i32_e32 v48, v74, v48
	v_max_i32_e32 v66, v43, v45
	v_min_i32_e32 v43, v43, v45
	v_max_i32_e32 v45, v41, v44
	v_min_i32_e32 v41, v41, v44
	v_max_i32_e32 v44, v77, v69
	v_sub_u32_e32 v46, v49, v87
	v_sub_u32_e32 v47, v48, v87
	v_sub_u32_e32 v40, v40, v87
	v_sub_u32_e32 v36, v36, v87
	v_sub_u32_e32 v39, v39, v87
	v_sub_u32_e32 v38, v38, v87
	v_sub_u32_e32 v35, v35, v87
	v_sub_u32_e32 v34, v34, v87
	v_sub_u32_e32 v48, v66, v87
	v_sub_u32_e32 v43, v43, v87
	v_sub_u32_e32 v42, v42, v87
	v_sub_u32_e32 v37, v37, v87
	v_sub_u32_e32 v45, v45, v87
	v_sub_u32_e32 v41, v41, v87
	v_sub_u32_e32 v44, v44, v87
	v_sub_u32_e32 v49, v70, v87
	ds_bpermute_b32 v66, v123, v46
	ds_bpermute_b32 v67, v123, v47
	ds_bpermute_b32 v68, v123, v40
	ds_bpermute_b32 v69, v123, v36
	ds_bpermute_b32 v70, v123, v39
	ds_bpermute_b32 v71, v123, v38
	ds_bpermute_b32 v72, v123, v35
	ds_bpermute_b32 v73, v123, v34
	ds_bpermute_b32 v74, v123, v48
	ds_bpermute_b32 v75, v123, v43
	ds_bpermute_b32 v76, v123, v42
	ds_bpermute_b32 v77, v123, v49
	ds_bpermute_b32 v78, v123, v44
	ds_bpermute_b32 v79, v123, v41
	ds_bpermute_b32 v80, v123, v45
	ds_bpermute_b32 v81, v123, v37
	s_waitcnt lgkmcnt(4)
	v_max_i32_e32 v46, v46, v77
	s_waitcnt lgkmcnt(3)
	v_max_i32_e32 v47, v47, v78
	s_waitcnt lgkmcnt(2)
	v_max_i32_e32 v40, v40, v79
	s_waitcnt lgkmcnt(1)
	v_max_i32_e32 v36, v36, v80
	s_waitcnt lgkmcnt(0)
	v_max_i32_e32 v39, v39, v81
	v_max_i32_e32 v38, v38, v76
	v_max_i32_e32 v35, v35, v75
	v_max_i32_e32 v34, v34, v74
	v_max_i32_e32 v48, v48, v73
	v_max_i32_e32 v43, v43, v72
	v_max_i32_e32 v42, v42, v71
	v_max_i32_e32 v37, v37, v70
	v_max_i32_e32 v45, v45, v69
	v_max_i32_e32 v41, v41, v68
	v_max_i32_e32 v44, v44, v67
	v_max_i32_e32 v49, v49, v66
	v_max_i32_e32 v66, v46, v48
	v_min_i32_e32 v46, v46, v48
	v_max_i32_e32 v48, v47, v43
	v_min_i32_e32 v43, v47, v43
	v_max_i32_e32 v47, v40, v42
	v_min_i32_e32 v40, v40, v42
	v_max_i32_e32 v42, v36, v37
	v_min_i32_e32 v36, v36, v37
	v_max_i32_e32 v37, v39, v45
	v_min_i32_e32 v39, v39, v45
	v_max_i32_e32 v45, v38, v41
	v_min_i32_e32 v38, v38, v41
	v_max_i32_e32 v41, v35, v44
	v_min_i32_e32 v35, v35, v44
	v_max_i32_e32 v44, v34, v49
	v_min_i32_e32 v34, v34, v49
	v_max_i32_e32 v49, v66, v37
	v_min_i32_e32 v37, v66, v37
	v_max_i32_e32 v66, v48, v45
	v_min_i32_e32 v45, v48, v45
	v_max_i32_e32 v48, v47, v41
	v_min_i32_e32 v41, v47, v41
	v_max_i32_e32 v47, v42, v44
	v_max_i32_e32 v80, v66, v47
	v_min_i32_e32 v124, v66, v47
	ds_read_b128 v[66:69], v94 offset:18432
	ds_read_b128 v[70:73], v94 offset:18464
	v_min_i32_e32 v42, v42, v44
	v_max_i32_e32 v44, v46, v39
	v_min_i32_e32 v74, v46, v39
	v_max_i32_e32 v39, v43, v38
	v_min_i32_e32 v75, v43, v38
	v_max_i32_e32 v38, v40, v35
	v_min_i32_e32 v76, v40, v35
	v_max_i32_e32 v35, v36, v34
	v_min_i32_e32 v77, v36, v34
	v_max_i32_e32 v78, v49, v48
	v_min_i32_e32 v82, v49, v48
	v_max_i32_e32 v125, v37, v41
	v_min_i32_e32 v126, v37, v41
	v_max_i32_e32 v127, v45, v42
	v_min_i32_e32 v128, v45, v42
	v_max_i32_e32 v129, v44, v38
	v_min_i32_e32 v130, v44, v38
	v_max_i32_e32 v131, v39, v35
	v_min_i32_e32 v132, v39, v35
	s_waitcnt vmcnt(3) lgkmcnt(1)
	v_mfma_f32_32x32x16_bf16 v[34:49], v[66:69], v[62:65], v[18:33]
	ds_read_b128 v[66:69], v94 offset:18496
	v_max_i32_e32 v133, v74, v76
	v_min_i32_e32 v134, v74, v76
	v_max_i32_e32 v135, v75, v77
	v_min_i32_e32 v136, v75, v77
	v_max_i32_e32 v79, v78, v80
	v_min_i32_e32 v81, v78, v80
	s_waitcnt vmcnt(2) lgkmcnt(1)
	v_mfma_f32_32x32x16_bf16 v[34:49], v[70:73], v[58:61], v[34:49]
	v_max_i32_e32 v80, v82, v124
	v_min_i32_e32 v78, v82, v124
	v_max_i32_e32 v77, v125, v127
	v_min_i32_e32 v76, v125, v127
	v_max_i32_e32 v75, v126, v128
	v_min_i32_e32 v73, v126, v128
	ds_read_b128 v[124:127], v94 offset:18528
	s_waitcnt vmcnt(1) lgkmcnt(1)
	v_mfma_f32_32x32x16_bf16 v[34:49], v[66:69], v[54:57], v[34:49]
	v_max_i32_e32 v71, v129, v131
	v_min_i32_e32 v74, v129, v131
	v_max_i32_e32 v72, v130, v132
	v_min_i32_e32 v70, v130, v132
	v_max_i32_e32 v69, v133, v135
	v_min_i32_e32 v68, v133, v135
	v_max_i32_e32 v67, v134, v136
	s_waitcnt vmcnt(0) lgkmcnt(0)
; #define LAS __attribute__((address_space(3)))
; #define MFMA32(a, b, c) __builtin_amdgcn_mfma_f32_32x32x16_bf16((a), (b), (c), 0, 0, 0)
; __device__ __forceinline__ void route_task(int task, int tl0, const bf16* QP  , const LAS bf16* KHL, LAS unsigned short* EL, LAS float* GL, int lane) {
;     ...
;         for (int kt = 0; kt < 4; ++kt) {
;             f32x16 X;
; #pragma unroll
;             for (int i = 0; i < 16; ++i) X[i] = 8.f;
;             const LAS bf16* khp = KHL + (half * 128 + 32 * kt + r) * 72 + 8 * hi;
; #pragma unroll
;             for (int ks = 0; ks < 4; ++ks) {
;                 const bf16x8 kh = lds8(khp + 16 * ks);
;                 X = MFMA32(kh, qa[half][ks], X);
;             }
;             int grp[16];
; #pragma unroll
;             for (int i = 0; i < 16; ++i) grp[i] = (int)((__float_as_uint(X[i]) | 127u) - (unsigned)(32 * kt + (i & 3) + 8 * (i >> 2)));
;             sort16_desc(grp);
;             if (kt == 0) {
; #pragma unroll
;                 for (int i = 0; i < 16; ++i) cur[i] = grp[i];
;             } else merge16_desc(cur, grp);
	v_mfma_f32_32x32x16_bf16 v[34:49], v[124:127], v[50:53], v[34:49]
	v_min_i32_e32 v66, v134, v136
	s_nop 10
	v_bitop3_b32 v37, v37, s42, 3 bitop3:0x56
	v_bitop3_b32 v48, v48, s42, 26 bitop3:0x56
	v_bitop3_b32 v38, v38, s42, 8 bitop3:0x56
	v_bitop3_b32 v42, v42, s42, 16 bitop3:0x56
	v_bitop3_b32 v47, v47, s42, 25 bitop3:0x56
	v_bitop3_b32 v39, v39, s42, 9 bitop3:0x56
	v_bitop3_b32 v40, v40, s42, 10 bitop3:0x56
	v_bitop3_b32 v43, v43, s42, 17 bitop3:0x56
	v_bitop3_b32 v44, v44, s42, 18 bitop3:0x56
	v_bitop3_b32 v36, v36, s42, 2 bitop3:0x56
	v_bitop3_b32 v49, v49, s42, 27 bitop3:0x56
	v_bitop3_b32 v41, v41, s42, 11 bitop3:0x56
	v_bitop3_b32 v45, v45, s42, 19 bitop3:0x56
	v_bitop3_b32 v35, v35, s42, 1 bitop3:0x56
	v_bitop3_b32 v46, v46, s42, 24 bitop3:0x56
	v_or_b32_e32 v34, 0x7f, v34
	v_max_i32_e32 v82, v37, v48
	v_max_i32_e32 v124, v38, v42
	v_max_i32_e32 v126, v34, v47
	v_max_i32_e32 v127, v39, v40
	v_min_i32_e32 v130, v43, v44
	v_min_i32_e32 v131, v36, v49
	v_min_i32_e32 v133, v41, v45
	v_min_i32_e32 v134, v35, v46
	v_min_i32_e32 v39, v39, v40
	v_min_i32_e32 v34, v34, v47
	v_min_i32_e32 v38, v38, v42
	v_min_i32_e32 v37, v37, v48
	v_max_i32_e32 v35, v35, v46
	v_max_i32_e32 v41, v41, v45
	v_max_i32_e32 v36, v36, v49
	v_max_i32_e32 v43, v43, v44
	v_min_i32_e32 v125, v82, v124
	v_min_i32_e32 v128, v126, v127
	v_max_i32_e32 v132, v130, v131
	v_max_i32_e32 v135, v133, v134
	v_max_i32_e32 v40, v39, v34
	v_max_i32_e32 v42, v38, v37
	v_min_i32_e32 v45, v35, v41
	v_min_i32_e32 v44, v36, v43
	v_min_i32_e32 v129, v125, v128
	v_max_i32_e32 v47, v40, v42
	v_max_i32_e32 v46, v45, v44
	v_min_i32_e32 v40, v40, v42
	v_min_i32_e32 v42, v45, v44
	v_max_i32_e32 v45, v125, v128
	v_max_i32_e32 v125, v132, v135
	v_min_i32_e32 v128, v45, v125
	v_min_i32_e32 v34, v39, v34
	v_max_i32_e32 v39, v126, v127
	v_max_i32_e32 v35, v35, v41
	v_max_i32_e32 v41, v82, v124
	v_max_i32_e32 v148, v45, v125
	ds_read_b128 v[124:127], v97
	v_max_i32_e32 v44, v40, v42
	v_min_i32_e32 v138, v40, v42
	v_min_i32_e32 v40, v133, v134
	v_min_i32_e32 v37, v38, v37
	v_min_i32_e32 v38, v130, v131
	v_max_i32_e32 v36, v36, v43
	v_min_i32_e32 v136, v132, v135
	v_min_i32_e32 v133, v40, v34
	v_min_i32_e32 v134, v37, v38
	v_max_i32_e32 v34, v40, v34
	v_max_i32_e32 v37, v37, v38
	v_min_i32_e32 v40, v39, v35
	v_min_i32_e32 v42, v36, v41
	v_max_i32_e32 v144, v39, v35
	v_max_i32_e32 v145, v36, v41
	v_max_i32_e32 v137, v129, v136
	v_min_i32_e32 v136, v129, v136
	v_max_i32_e32 v140, v133, v134
	v_min_i32_e32 v141, v34, v37
	v_max_i32_e32 v143, v40, v42
	v_min_i32_e32 v146, v144, v145
	v_max_i32_e32 v149, v47, v46
	v_min_i32_e32 v48, v47, v46
	v_max_i32_e32 v139, v138, v136
	v_max_i32_e32 v142, v140, v141
	v_min_i32_e32 v43, v40, v42
	v_max_i32_e32 v34, v34, v37
	v_min_i32_e32 v147, v143, v146
	v_min_i32_e32 v150, v148, v149
	v_min_i32_e32 v49, v137, v48
	v_min_i32_e32 v132, v44, v128
	v_max_i32_e32 v38, v139, v142
	v_min_i32_e32 v37, v43, v34
	v_max_i32_e32 v34, v43, v34
	v_min_i32_e32 v35, v147, v150
	v_max_i32_e32 v39, v137, v48
	v_max_i32_e32 v40, v44, v128
	v_max_i32_e32 v135, v49, v132
	v_max_i32_e32 v82, v38, v37
	v_min_i32_e32 v36, v34, v35
	v_min_i32_e32 v41, v39, v40
	v_max_i32_e32 v129, v135, v82
	v_min_i32_e32 v42, v36, v41
	v_min_i32_e32 v137, v129, v42
	v_max_i32_e32 v159, v129, v42
	ds_read_b128 v[128:131], v97 offset:32
	v_min_i32_e32 v82, v135, v82
	v_min_i32_e32 v132, v49, v132
	v_min_i32_e32 v135, v38, v37
	v_max_i32_e32 v154, v34, v35
	v_max_i32_e32 v155, v39, v40
	v_max_i32_e32 v157, v36, v41
	s_waitcnt lgkmcnt(1)
	v_mfma_f32_32x32x16_bf16 v[34:49], v[124:127], v[62:65], v[18:33]
	ds_read_b128 v[124:127], v97 offset:64
	v_max_i32_e32 v151, v132, v135
	v_max_i32_e32 v152, v82, v151
	v_min_i32_e32 v136, v138, v136
	v_min_i32_e32 v138, v140, v141
	v_min_i32_e32 v82, v82, v151
	v_max_i32_e32 v147, v147, v150
	s_waitcnt lgkmcnt(1)
	v_mfma_f32_32x32x16_bf16 v[34:49], v[128:131], v[58:61], v[34:49]
	ds_read_b128 v[128:131], v97 offset:96
	v_max_i32_e32 v143, v143, v146
	v_min_i32_e32 v133, v133, v134
	v_min_i32_e32 v156, v154, v155
	v_max_i32_e32 v140, v136, v138
	v_min_i32_e32 v139, v139, v142
	v_max_i32_e32 v142, v154, v155
	s_waitcnt lgkmcnt(1)
	v_mfma_f32_32x32x16_bf16 v[34:49], v[124:127], v[54:57], v[34:49]
	v_max_i32_e32 v124, v148, v149
	v_min_i32_e32 v136, v136, v138
	v_max_i32_e32 v141, v140, v139
	v_min_i32_e32 v139, v140, v139
	v_min_i32_e32 v125, v143, v124
	v_min_i32_e32 v158, v156, v157
	v_min_i32_e32 v132, v132, v135
	s_waitcnt lgkmcnt(0)
; #define LAS __attribute__((address_space(3)))
; #define MFMA32(a, b, c) __builtin_amdgcn_mfma_f32_32x32x16_bf16((a), (b), (c), 0, 0, 0)
; __device__ __forceinline__ void route_task(int task, int tl0, const bf16* QP  , const LAS bf16* KHL, LAS unsigned short* EL, LAS float* GL, int lane) {
;     ...
;         for (int kt = 0; kt < 4; ++kt) {
;             f32x16 X;
; #pragma unroll
;             for (int i = 0; i < 16; ++i) X[i] = 8.f;
;             const LAS bf16* khp = KHL + (half * 128 + 32 * kt + r) * 72 + 8 * hi;
; #pragma unroll
;             for (int ks = 0; ks < 4; ++ks) {
;                 const bf16x8 kh = lds8(khp + 16 * ks);
;                 X = MFMA32(kh, qa[half][ks], X);
;             }
;             int grp[16];
; #pragma unroll
;             for (int i = 0; i < 16; ++i) grp[i] = (int)((__float_as_uint(X[i]) | 127u) - (unsigned)(32 * kt + (i & 3) + 8 * (i >> 2)));
;             sort16_desc(grp);
;             if (kt == 0) {
; #pragma unroll
;                 for (int i = 0; i < 16; ++i) cur[i] = grp[i];
;             } else merge16_desc(cur, grp);
	v_mfma_f32_32x32x16_bf16 v[34:49], v[128:131], v[50:53], v[34:49]
	v_min_i32_e32 v126, v147, v125
	v_min_i32_e32 v153, v137, v152
	v_min_i32_e32 v160, v158, v159
	v_min_i32_e32 v135, v141, v132
	v_min_i32_e32 v127, v142, v126
	s_nop 6
	v_bitop3_b32 v37, v37, s42, 35 bitop3:0x56
	v_bitop3_b32 v48, v48, s42, 58 bitop3:0x56
	v_bitop3_b32 v38, v38, s42, 40 bitop3:0x56
	v_bitop3_b32 v42, v42, s42, 48 bitop3:0x56
	v_bitop3_b32 v34, v34, s42, 32 bitop3:0x56
	v_bitop3_b32 v47, v47, s42, 57 bitop3:0x56
	v_bitop3_b32 v39, v39, s42, 41 bitop3:0x56
	v_bitop3_b32 v40, v40, s42, 42 bitop3:0x56
	v_bitop3_b32 v43, v43, s42, 49 bitop3:0x56
	v_bitop3_b32 v44, v44, s42, 50 bitop3:0x56
	v_bitop3_b32 v36, v36, s42, 34 bitop3:0x56
	v_bitop3_b32 v49, v49, s42, 59 bitop3:0x56
	v_bitop3_b32 v41, v41, s42, 43 bitop3:0x56
	v_bitop3_b32 v45, v45, s42, 51 bitop3:0x56
	v_bitop3_b32 v35, v35, s42, 33 bitop3:0x56
	v_bitop3_b32 v46, v46, s42, 56 bitop3:0x56
	v_max_i32_e32 v128, v37, v48
	v_max_i32_e32 v129, v38, v42
	v_max_i32_e32 v131, v34, v47
	v_max_i32_e32 v134, v39, v40
	v_min_i32_e32 v146, v43, v44
	v_min_i32_e32 v148, v36, v49
	v_min_i32_e32 v150, v41, v45
	v_min_i32_e32 v151, v35, v46
	v_min_i32_e32 v39, v39, v40
	v_min_i32_e32 v34, v34, v47
	v_min_i32_e32 v38, v38, v42
	v_min_i32_e32 v37, v37, v48
	v_max_i32_e32 v35, v35, v46
	v_max_i32_e32 v41, v41, v45
	v_max_i32_e32 v36, v36, v49
	v_max_i32_e32 v43, v43, v44
	v_min_i32_e32 v130, v128, v129
	v_min_i32_e32 v138, v131, v134
	v_max_i32_e32 v149, v146, v148
	v_max_i32_e32 v154, v150, v151
	v_max_i32_e32 v40, v39, v34
	v_max_i32_e32 v42, v38, v37
	v_min_i32_e32 v45, v35, v41
	v_min_i32_e32 v44, v36, v43
	v_min_i32_e32 v150, v150, v151
	v_min_i32_e32 v34, v39, v34
	v_min_i32_e32 v37, v38, v37
	v_min_i32_e32 v38, v146, v148
	v_max_i32_e32 v131, v131, v134
	v_max_i32_e32 v35, v35, v41
	v_max_i32_e32 v36, v36, v43
	v_max_i32_e32 v43, v128, v129
	v_min_i32_e32 v140, v130, v138
	v_min_i32_e32 v155, v149, v154
	v_max_i32_e32 v47, v40, v42
	v_max_i32_e32 v46, v45, v44
	v_min_i32_e32 v40, v40, v42
	v_min_i32_e32 v42, v45, v44
	v_max_i32_e32 v45, v130, v138
	v_max_i32_e32 v130, v149, v154
	v_min_i32_e32 v39, v150, v34
	v_min_i32_e32 v146, v37, v38
	v_max_i32_e32 v34, v150, v34
	v_max_i32_e32 v37, v37, v38
	v_min_i32_e32 v41, v131, v35
	v_min_i32_e32 v128, v36, v43
	v_max_i32_e32 v35, v131, v35
	v_max_i32_e32 v36, v36, v43
	v_min_i32_e32 v48, v47, v46
	v_max_i32_e32 v44, v40, v42
	v_min_i32_e32 v138, v45, v130
	v_min_i32_e32 v40, v40, v42
	v_min_i32_e32 v42, v140, v155
	v_max_i32_e32 v148, v39, v146
	v_min_i32_e32 v38, v34, v37
	v_min_i32_e32 v129, v41, v128
	v_max_i32_e32 v41, v41, v128
	v_min_i32_e32 v43, v35, v36
	v_max_i32_e32 v45, v45, v130
	v_max_i32_e32 v46, v47, v46
	v_max_i32_e32 v161, v140, v155
	v_max_i32_e32 v140, v40, v42
	v_max_i32_e32 v150, v148, v38
	v_max_i32_e32 v34, v34, v37
	v_min_i32_e32 v128, v41, v43
	v_min_i32_e32 v47, v45, v46
	v_min_i32_e32 v49, v161, v48
	v_min_i32_e32 v149, v44, v138
	v_max_i32_e32 v151, v140, v150
	v_min_i32_e32 v37, v129, v34
	v_max_i32_e32 v34, v129, v34
	v_min_i32_e32 v129, v128, v47
	v_max_i32_e32 v48, v161, v48
	v_max_i32_e32 v44, v44, v138
	v_max_i32_e32 v154, v49, v149
	v_max_i32_e32 v134, v151, v37
	v_min_i32_e32 v130, v34, v129
	v_min_i32_e32 v131, v48, v44
	v_min_i32_e32 v49, v49, v149
	v_min_i32_e32 v37, v151, v37
	v_max_i32_e32 v34, v34, v129
	v_max_i32_e32 v44, v48, v44
	v_min_i32_e32 v40, v40, v42
	v_min_i32_e32 v38, v148, v38
	v_max_i32_e32 v41, v41, v43
	v_max_i32_e32 v43, v45, v46
	v_max_i32_e32 v155, v154, v134
	v_min_i32_e32 v138, v130, v131
	v_min_i32_e32 v134, v154, v134
	v_max_i32_e32 v149, v49, v37
	v_min_i32_e32 v48, v34, v44
	v_max_i32_e32 v129, v130, v131
	v_max_i32_e32 v42, v40, v38
	v_min_i32_e32 v140, v140, v150
	v_max_i32_e32 v34, v34, v44
	v_max_i32_e32 v44, v128, v47
	v_min_i32_e32 v45, v41, v43
	v_min_i32_e32 v161, v155, v138
	v_max_i32_e32 v151, v134, v149
	v_min_i32_e32 v130, v48, v129
	v_max_i32_e32 v131, v155, v138
	v_max_i32_e32 v148, v42, v140
	v_min_i32_e32 v37, v49, v37
	v_min_i32_e32 v46, v44, v45
	v_min_i32_e32 v154, v161, v151
	v_min_i32_e32 v138, v130, v131
	v_min_i32_e32 v49, v148, v37
	v_min_i32_e32 v134, v134, v149
	v_min_i32_e32 v47, v34, v46
	v_min_i32_e32 v42, v42, v140
	v_min_i32_e32 v38, v40, v38
	v_min_i32_e32 v39, v39, v146
	v_max3_i32 v39, v144, v145, v39
	v_max3_i32 v38, v143, v124, v38
	v_max3_i32 v40, v147, v125, v42
	v_max3_i32 v42, v142, v126, v49
	v_max3_i32 v37, v127, v148, v37
	v_max3_i32 v49, v156, v157, v134
	v_max3_i32 v124, v158, v159, v154
	v_max3_i32 v125, v160, v161, v151
	v_max3_i32 v126, v137, v152, v138
	v_max3_i32 v127, v153, v130, v131
	v_max3_i32 v48, v82, v48, v129
	v_max3_i32 v47, v141, v132, v47
	v_max3_i32 v34, v135, v34, v46
	v_max3_i32 v44, v139, v44, v45
	v_max3_i32 v41, v136, v41, v43
	v_max3_i32 v35, v133, v35, v36
	v_max_i32_e32 v36, v39, v126
	v_min_i32_e32 v39, v39, v126
	v_max_i32_e32 v43, v38, v127
	v_min_i32_e32 v38, v38, v127
	v_max_i32_e32 v45, v40, v48
	v_min_i32_e32 v40, v40, v48
	v_max_i32_e32 v46, v42, v47
	v_min_i32_e32 v42, v42, v47
	v_max_i32_e32 v47, v37, v34
	v_min_i32_e32 v34, v37, v34
	v_max_i32_e32 v37, v49, v44
	v_min_i32_e32 v44, v49, v44
	v_max_i32_e32 v48, v124, v41
	v_min_i32_e32 v41, v124, v41
	v_max_i32_e32 v49, v125, v35
	v_min_i32_e32 v35, v125, v35
	ds_read_b128 v[124:127], v94 offset:27648
	ds_read_b128 v[128:131], v94 offset:27680
	v_max_i32_e32 v82, v36, v47
	v_min_i32_e32 v132, v36, v47
	v_max_i32_e32 v36, v43, v37
	v_min_i32_e32 v133, v43, v37
	v_max_i32_e32 v37, v45, v48
	v_max_i32_e32 v43, v46, v49
	v_min_i32_e32 v134, v45, v48
	v_min_i32_e32 v135, v46, v49
	v_max_i32_e32 v136, v39, v34
	v_min_i32_e32 v137, v39, v34
	v_max_i32_e32 v138, v38, v44
	v_min_i32_e32 v139, v38, v44
	v_max_i32_e32 v140, v40, v41
	v_min_i32_e32 v141, v40, v41
	v_max_i32_e32 v142, v42, v35
	v_min_i32_e32 v143, v42, v35
	v_max_i32_e32 v144, v82, v37
	v_min_i32_e32 v82, v82, v37
	v_max_i32_e32 v145, v36, v43
	v_min_i32_e32 v146, v36, v43
	s_waitcnt lgkmcnt(1)
; #define LAS __attribute__((address_space(3)))
; #define MFMA32(a, b, c) __builtin_amdgcn_mfma_f32_32x32x16_bf16((a), (b), (c), 0, 0, 0)
; __device__ __forceinline__ void route_task(int task, int tl0, const bf16* QP  , const LAS bf16* KHL, LAS unsigned short* EL, LAS float* GL, int lane) {
;     ...
;         for (int kt = 0; kt < 4; ++kt) {
;             f32x16 X;
; #pragma unroll
;             for (int i = 0; i < 16; ++i) X[i] = 8.f;
;             const LAS bf16* khp = KHL + (half * 128 + 32 * kt + r) * 72 + 8 * hi;
; #pragma unroll
;             for (int ks = 0; ks < 4; ++ks) {
;                 const bf16x8 kh = lds8(khp + 16 * ks);
;                 X = MFMA32(kh, qa[half][ks], X);
;             }
;             int grp[16];
; #pragma unroll
;             for (int i = 0; i < 16; ++i) grp[i] = (int)((__float_as_uint(X[i]) | 127u) - (unsigned)(32 * kt + (i & 3) + 8 * (i >> 2)));
;             sort16_desc(grp);
;             if (kt == 0) {
; #pragma unroll
;                 for (int i = 0; i < 16; ++i) cur[i] = grp[i];
;             } else merge16_desc(cur, grp);
	v_mfma_f32_32x32x16_bf16 v[34:49], v[124:127], v[62:65], v[18:33]
	ds_read_b128 v[124:127], v94 offset:27712
	v_max_i32_e32 v147, v132, v134
	v_min_i32_e32 v132, v132, v134
	v_max_i32_e32 v134, v133, v135
	v_min_i32_e32 v133, v133, v135
	v_max_i32_e32 v135, v136, v140
	v_min_i32_e32 v136, v136, v140
	s_waitcnt lgkmcnt(1)
	v_mfma_f32_32x32x16_bf16 v[34:49], v[128:131], v[58:61], v[34:49]
	ds_read_b128 v[128:131], v94 offset:27744
	v_max_i32_e32 v140, v138, v142
	v_min_i32_e32 v138, v138, v142
	v_max_i32_e32 v142, v137, v141
	v_min_i32_e32 v137, v137, v141
	v_max_i32_e32 v141, v139, v143
	v_min_i32_e32 v139, v139, v143
	s_waitcnt lgkmcnt(1)
	v_mfma_f32_32x32x16_bf16 v[34:49], v[124:127], v[54:57], v[34:49]
	v_min_i32_e32 v143, v144, v145
	v_min_i32_e32 v124, v82, v146
	v_min_i32_e32 v127, v135, v140
	v_min_i32_e32 v125, v147, v134
	v_min_i32_e32 v126, v132, v133
	v_min_i32_e32 v149, v142, v141
	v_min_i32_e32 v148, v136, v138
	s_waitcnt lgkmcnt(0)
	v_mfma_f32_32x32x16_bf16 v[34:49], v[128:131], v[50:53], v[34:49]
	v_min_i32_e32 v150, v137, v139
	s_nop 10
	v_and_or_b32 v37, v37, s43, 60
	v_and_or_b32 v48, v48, s43, 37
	v_and_or_b32 v38, v38, s43, 55
	v_and_or_b32 v42, v42, s43, 47
	v_bitop3_b32 v34, v34, s42, 64 bitop3:0x56
	v_and_or_b32 v47, v47, s43, 38
	v_and_or_b32 v39, v39, s43, 54
	v_and_or_b32 v40, v40, s43, 53
	v_and_or_b32 v43, v43, s43, 46
	v_and_or_b32 v44, v44, s43, 45
	v_and_or_b32 v36, v36, s43, 61
	v_and_or_b32 v49, v49, s43, 36
	v_and_or_b32 v41, v41, s43, 52
	v_and_or_b32 v45, v45, s43, 44
	v_and_or_b32 v35, v35, s43, 62
	v_and_or_b32 v46, v46, s43, 39
	v_max_i32_e32 v128, v37, v48
	v_max_i32_e32 v129, v38, v42
	v_max_i32_e32 v131, v34, v47
	v_max_i32_e32 v151, v39, v40
	v_min_i32_e32 v154, v43, v44
	v_min_i32_e32 v155, v36, v49
	v_min_i32_e32 v157, v41, v45
	v_min_i32_e32 v158, v35, v46
	v_min_i32_e32 v39, v39, v40
	v_min_i32_e32 v34, v34, v47
	v_min_i32_e32 v38, v38, v42
	v_min_i32_e32 v37, v37, v48
	v_max_i32_e32 v35, v35, v46
	v_max_i32_e32 v41, v41, v45
	v_max_i32_e32 v36, v36, v49
	v_max_i32_e32 v43, v43, v44
	v_min_i32_e32 v130, v128, v129
	v_min_i32_e32 v152, v131, v151
	v_max_i32_e32 v156, v154, v155
	v_max_i32_e32 v159, v157, v158
	v_max_i32_e32 v40, v39, v34
	v_max_i32_e32 v42, v38, v37
	v_min_i32_e32 v45, v35, v41
	v_min_i32_e32 v44, v36, v43
	v_min_i32_e32 v157, v157, v158
	v_min_i32_e32 v34, v39, v34
	v_min_i32_e32 v37, v38, v37
	v_min_i32_e32 v38, v154, v155
	v_max_i32_e32 v131, v131, v151
	v_max_i32_e32 v35, v35, v41
	v_max_i32_e32 v36, v36, v43
	v_max_i32_e32 v43, v128, v129
	v_min_i32_e32 v153, v130, v152
	v_min_i32_e32 v160, v156, v159
	v_max_i32_e32 v47, v40, v42
	v_max_i32_e32 v46, v45, v44
	v_min_i32_e32 v40, v40, v42
	v_min_i32_e32 v42, v45, v44
	v_max_i32_e32 v45, v130, v152
	v_max_i32_e32 v130, v156, v159
	v_min_i32_e32 v39, v157, v34
	v_min_i32_e32 v154, v37, v38
	v_max_i32_e32 v34, v157, v34
	v_max_i32_e32 v37, v37, v38
	v_min_i32_e32 v41, v131, v35
	v_min_i32_e32 v128, v36, v43
	v_max_i32_e32 v35, v131, v35
	v_max_i32_e32 v36, v36, v43
	v_min_i32_e32 v48, v47, v46
	v_max_i32_e32 v44, v40, v42
	v_min_i32_e32 v152, v45, v130
	v_min_i32_e32 v40, v40, v42
	v_min_i32_e32 v42, v153, v160
	v_max_i32_e32 v155, v39, v154
	v_min_i32_e32 v38, v34, v37
	v_min_i32_e32 v129, v41, v128
	v_max_i32_e32 v41, v41, v128
	v_min_i32_e32 v43, v35, v36
	v_max_i32_e32 v45, v45, v130
	v_max_i32_e32 v46, v47, v46
	v_max_i32_e32 v161, v153, v160
	v_max_i32_e32 v153, v40, v42
	v_max_i32_e32 v157, v155, v38
	v_max_i32_e32 v34, v34, v37
	v_min_i32_e32 v128, v41, v43
	v_min_i32_e32 v47, v45, v46
	v_min_i32_e32 v49, v161, v48
	v_min_i32_e32 v156, v44, v152
	v_max_i32_e32 v158, v153, v157
	v_min_i32_e32 v37, v129, v34
	v_max_i32_e32 v34, v129, v34
	v_min_i32_e32 v129, v128, v47
	v_max_i32_e32 v48, v161, v48
	v_max_i32_e32 v44, v44, v152
	v_min_i32_e32 v40, v40, v42
	v_min_i32_e32 v38, v155, v38
	v_max_i32_e32 v159, v49, v156
	v_max_i32_e32 v151, v158, v37
	v_min_i32_e32 v130, v34, v129
	v_min_i32_e32 v131, v48, v44
	v_min_i32_e32 v49, v49, v156
	v_min_i32_e32 v37, v158, v37
	v_max_i32_e32 v34, v34, v129
	v_max_i32_e32 v44, v48, v44
	v_max_i32_e32 v42, v40, v38
	v_min_i32_e32 v153, v153, v157
	v_max_i32_e32 v160, v159, v151
	v_min_i32_e32 v152, v130, v131
	v_max_i32_e32 v156, v49, v37
	v_min_i32_e32 v48, v34, v44
	v_max_i32_e32 v129, v130, v131
	v_max_i32_e32 v155, v42, v153
	v_min_i32_e32 v37, v49, v37
	v_min_i32_e32 v151, v159, v151
	v_min_i32_e32 v130, v48, v129
	v_max_i32_e32 v131, v160, v152
	v_min_i32_e32 v49, v155, v37
	v_max_i32_e32 v41, v41, v43
	v_max_i32_e32 v43, v45, v46
	v_min_i32_e32 v42, v42, v153
	v_min_i32_e32 v38, v40, v38
	v_min_i32_e32 v161, v160, v152
	v_max_i32_e32 v158, v151, v156
	v_min_i32_e32 v151, v151, v156
	v_max_i32_e32 v34, v34, v44
	v_max_i32_e32 v44, v128, v47
	v_min_i32_e32 v45, v41, v43
	v_max_i32_e32 v40, v41, v43
	v_max_i32_e32 v38, v143, v38
	v_max3_i32 v41, v82, v146, v42
	v_max_i32_e32 v42, v124, v49
	v_max3_i32 v124, v127, v130, v131
	v_min_i32_e32 v46, v44, v45
	v_max_i32_e32 v43, v125, v151
	v_max3_i32 v49, v126, v161, v158
	v_max3_i32 v44, v149, v44, v45
	v_max_i32_e32 v45, v38, v124
	v_min_i32_e32 v38, v38, v124
	ds_read_b128 v[124:127], v98
	v_min_i32_e32 v159, v161, v158
	v_min_i32_e32 v152, v130, v131
	v_max_i32_e32 v37, v155, v37
	v_max_i32_e32 v48, v48, v129
	v_min_i32_e32 v47, v34, v46
	v_max_i32_e32 v34, v34, v46
	v_min_i32_e32 v39, v39, v154
	v_max3_i32 v39, v144, v145, v39
	v_max3_i32 v37, v147, v134, v37
	v_max3_i32 v46, v132, v133, v159
	v_max3_i32 v82, v135, v140, v152
	v_max3_i32 v48, v136, v138, v48
	v_max_i32_e32 v47, v148, v47
	v_max3_i32 v34, v142, v141, v34
	v_max3_i32 v40, v137, v139, v40
	v_max3_i32 v35, v150, v35, v36
	v_max_i32_e32 v36, v39, v82
	v_min_i32_e32 v39, v39, v82
	v_max_i32_e32 v82, v41, v48
	v_min_i32_e32 v41, v41, v48
	v_max_i32_e32 v48, v42, v47
	v_min_i32_e32 v42, v42, v47
	v_max_i32_e32 v47, v37, v34
	v_min_i32_e32 v34, v37, v34
	v_max_i32_e32 v37, v43, v44
	v_min_i32_e32 v43, v43, v44
	v_max_i32_e32 v44, v46, v40
	v_min_i32_e32 v40, v46, v40
	v_max_i32_e32 v46, v49, v35
	v_min_i32_e32 v35, v49, v35
	v_max_i32_e32 v49, v36, v47
	v_min_i32_e32 v132, v36, v47
	v_max_i32_e32 v36, v45, v37
	v_min_i32_e32 v133, v45, v37
	v_max_i32_e32 v37, v82, v44
	v_min_i32_e32 v82, v82, v44
	v_max_i32_e32 v44, v48, v46
	ds_read_b128 v[128:131], v98 offset:32
	v_min_i32_e32 v134, v48, v46
	v_max_i32_e32 v135, v39, v34
	v_min_i32_e32 v136, v39, v34
	v_max_i32_e32 v137, v38, v43
	v_min_i32_e32 v138, v38, v43
	v_max_i32_e32 v139, v41, v40
	v_min_i32_e32 v140, v41, v40
	v_max_i32_e32 v141, v42, v35
	v_min_i32_e32 v142, v42, v35
	v_max_i32_e32 v143, v49, v37
	v_min_i32_e32 v144, v49, v37
	v_max_i32_e32 v145, v36, v44
	v_min_i32_e32 v146, v36, v44
	s_waitcnt lgkmcnt(1)
; #define LAS __attribute__((address_space(3)))
; #define MFMA32(a, b, c) __builtin_amdgcn_mfma_f32_32x32x16_bf16((a), (b), (c), 0, 0, 0)
; __device__ __forceinline__ void route_task(int task, int tl0, const bf16* QP  , const LAS bf16* KHL, LAS unsigned short* EL, LAS float* GL, int lane) {
;     ...
;         for (int kt = 0; kt < 4; ++kt) {
;             f32x16 X;
; #pragma unroll
;             for (int i = 0; i < 16; ++i) X[i] = 8.f;
;             const LAS bf16* khp = KHL + (half * 128 + 32 * kt + r) * 72 + 8 * hi;
; #pragma unroll
;             for (int ks = 0; ks < 4; ++ks) {
;                 const bf16x8 kh = lds8(khp + 16 * ks);
;                 X = MFMA32(kh, qa[half][ks], X);
;             }
;             int grp[16];
; #pragma unroll
;             for (int i = 0; i < 16; ++i) grp[i] = (int)((__float_as_uint(X[i]) | 127u) - (unsigned)(32 * kt + (i & 3) + 8 * (i >> 2)));
;             sort16_desc(grp);
;             if (kt == 0) {
; #pragma unroll
;                 for (int i = 0; i < 16; ++i) cur[i] = grp[i];
;             } else merge16_desc(cur, grp);
	v_mfma_f32_32x32x16_bf16 v[34:49], v[124:127], v[62:65], v[18:33]
	v_max_i32_e32 v147, v132, v82
	s_nop 5
	ds_read_b128 v[18:21], v98 offset:64
	ds_read_b128 v[22:25], v98 offset:96
	s_waitcnt lgkmcnt(2)
	v_mfma_f32_32x32x16_bf16 v[34:49], v[128:131], v[58:61], v[34:49]
	v_min_i32_e32 v26, v132, v82
	v_max_i32_e32 v27, v133, v134
	v_min_i32_e32 v30, v135, v139
	v_min_i32_e32 v32, v137, v141
	v_max_i32_e32 v33, v136, v140
	v_max_i32_e32 v59, v138, v142
	v_min_i32_e32 v28, v133, v134
	s_waitcnt lgkmcnt(1)
	v_mfma_f32_32x32x16_bf16 v[34:49], v[18:21], v[54:57], v[34:49]
	v_min_i32_e32 v19, v147, v27
	v_min_i32_e32 v54, v30, v32
	v_min_i32_e32 v55, v33, v59
	v_max_i32_e32 v29, v135, v139
	v_max_i32_e32 v31, v137, v141
	v_min_i32_e32 v58, v136, v140
	v_min_i32_e32 v60, v138, v142
	s_waitcnt lgkmcnt(0)
	v_mfma_f32_32x32x16_bf16 v[34:49], v[22:25], v[50:53], v[34:49]
	v_min_i32_e32 v18, v144, v146
	v_min_i32_e32 v61, v143, v145
	v_min_i32_e32 v20, v26, v28
	v_min_i32_e32 v21, v29, v31
	v_min_i32_e32 v56, v58, v60
	s_nop 6
	v_or_b32_e32 v22, 0x7f, v41
	v_or_b32_e32 v23, 0x7f, v45
	v_or_b32_e32 v25, 0x7f, v35
	v_or_b32_e32 v35, 0x7f, v46
	v_and_or_b32 v39, v39, s43, 22
	v_and_or_b32 v40, v40, s43, 21
	v_and_or_b32 v34, v34, s43, 31
	v_and_or_b32 v47, v47, s43, 6
	v_and_or_b32 v38, v38, s43, 23
	v_and_or_b32 v42, v42, s43, 15
	v_and_or_b32 v37, v37, s43, 28
	v_and_or_b32 v48, v48, s43, 5
	v_and_or_b32 v43, v43, s43, 14
	v_and_or_b32 v44, v44, s43, 13
	v_and_or_b32 v36, v36, s43, 29
	v_and_or_b32 v49, v49, s43, 4
	v_add_u32_e32 v22, 0xffffff95, v22
	v_add_u32_e32 v23, 0xffffff8d, v23
	v_add_u32_e32 v25, 0xffffff9f, v25
	v_add_u32_e32 v35, 0xffffff88, v35
	v_min_i32_e32 v24, v22, v23
	v_min_i32_e32 v41, v25, v35
	v_min_i32_e32 v46, v39, v40
	v_min_i32_e32 v50, v34, v47
	v_min_i32_e32 v53, v38, v42
	v_min_i32_e32 v57, v37, v48
	v_min_i32_e32 v63, v43, v44
	v_min_i32_e32 v64, v36, v49
	v_max_i32_e32 v34, v34, v47
	v_max_i32_e32 v39, v39, v40
	v_max_i32_e32 v25, v25, v35
	v_max_i32_e32 v22, v22, v23
	v_max_i32_e32 v36, v36, v49
	v_max_i32_e32 v43, v43, v44
	v_max_i32_e32 v37, v37, v48
	v_max_i32_e32 v38, v38, v42
	v_min_i32_e32 v45, v24, v41
	v_min_i32_e32 v51, v46, v50
	v_max_i32_e32 v40, v34, v39
	v_max_i32_e32 v23, v25, v22
	v_max_i32_e32 v44, v36, v43
	v_max_i32_e32 v42, v37, v38
	v_min_i32_e32 v37, v37, v38
	v_min_i32_e32 v34, v34, v39
	v_max_i32_e32 v39, v63, v64
	v_max_i32_e32 v24, v24, v41
	v_max_i32_e32 v46, v46, v50
	v_max_i32_e32 v50, v53, v57
	v_min_i32_e32 v22, v25, v22
	v_min_i32_e32 v25, v36, v43
	v_min_i32_e32 v62, v53, v57
	v_min_i32_e32 v65, v63, v64
	v_min_i32_e32 v35, v40, v23
	v_min_i32_e32 v47, v44, v42
	v_max_i32_e32 v23, v40, v23
	v_max_i32_e32 v40, v44, v42
	v_max_i32_e32 v38, v37, v34
	v_max_i32_e32 v41, v39, v24
	v_max_i32_e32 v53, v46, v50
	v_max_i32_e32 v36, v22, v25
	v_min_i32_e32 v46, v46, v50
	v_min_i32_e32 v22, v22, v25
	v_min_i32_e32 v52, v45, v51
	v_min_i32_e32 v82, v62, v65
	v_min_i32_e32 v48, v35, v47
	v_max_i32_e32 v45, v45, v51
	v_max_i32_e32 v49, v62, v65
	v_max_i32_e32 v35, v35, v47
	v_min_i32_e32 v42, v23, v40
	v_max_i32_e32 v47, v38, v41
	v_max_i32_e32 v43, v53, v36
	v_min_i32_e32 v34, v37, v34
	v_min_i32_e32 v24, v39, v24
	v_max_i32_e32 v25, v46, v22
	v_min_i32_e32 v38, v38, v41
	v_max_i32_e32 v51, v45, v49
	v_min_i32_e32 v44, v35, v42
	v_min_i32_e32 v57, v47, v43
	v_max_i32_e32 v37, v34, v24
	v_min_i32_e32 v36, v53, v36
	v_max_i32_e32 v41, v25, v38
	v_min_i32_e32 v25, v25, v38
	v_min_i32_e32 v22, v46, v22
	v_min_i32_e32 v24, v34, v24
	v_max_i32_e32 v38, v52, v82
	v_min_i32_e32 v45, v45, v49
	v_max_i32_e32 v62, v48, v51
	v_min_i32_e32 v63, v44, v57
	v_max_i32_e32 v39, v37, v36
	v_max_i32_e32 v34, v22, v24
	v_max_i32_e32 v46, v38, v45
	v_max_i32_e32 v64, v62, v63
	v_max_i32_e32 v50, v39, v41
	v_min_i32_e32 v62, v62, v63
	v_min_i32_e32 v39, v39, v41
	v_min_i32_e32 v36, v37, v36
	v_max_i32_e32 v49, v34, v46
	v_min_i32_e32 v48, v48, v51
	v_min_i32_e32 v22, v22, v24
	v_min_i32_e32 v24, v38, v45
	v_min_i32_e32 v53, v64, v50
	v_max_i32_e32 v41, v62, v39
	v_max_i32_e32 v37, v36, v25
	v_max_i32_e32 v51, v49, v48
	v_max_i32_e32 v38, v22, v24
	v_min_i32_e32 v34, v34, v46
	v_min_i32_e32 v25, v36, v25
	v_min_i32_e32 v36, v49, v48
	v_min_i32_e32 v124, v52, v82
	v_max_i32_e32 v52, v37, v51
	v_min_i32_e32 v39, v62, v39
	v_max_i32_e32 v45, v38, v34
	v_min_i32_e32 v46, v25, v36
	v_max_i32_e32 v35, v35, v42
	v_max_i32_e32 v42, v47, v43
	v_min_i32_e32 v34, v38, v34
	v_max_i32_e32 v38, v53, v41
	v_min_i32_e32 v37, v37, v51
	v_max_i32_e32 v25, v25, v36
	v_max_i32_e32 v48, v45, v46
	v_max_i32_e32 v44, v44, v57
	v_min_i32_e32 v43, v35, v42
	v_max3_i32 v30, v30, v32, v38
	v_min_i32_e32 v38, v52, v39
	v_max_i32_e32 v36, v37, v25
	v_min_i32_e32 v25, v37, v25
	v_min_i32_e32 v63, v53, v41
	v_max_i32_e32 v62, v52, v39
	v_max3_i32 v27, v147, v27, v48
	v_max_i32_e32 v48, v64, v50
	v_min_i32_e32 v47, v44, v43
	v_min_i32_e32 v39, v38, v36
	v_max_i32_e32 v19, v19, v25
	v_max3_i32 v25, v55, v44, v43
	v_min_i32_e32 v43, v45, v46
	v_min_i32_e32 v65, v63, v62
	v_max_i32_e32 v49, v48, v47
	v_max3_i32 v26, v26, v28, v39
	v_max_i32_e32 v28, v35, v42
	v_min_i32_e32 v22, v22, v24
	v_max_i32_e32 v18, v18, v43
	v_min_i32_e32 v43, v48, v47
	v_max3_i32 v124, v143, v145, v124
	v_max3_i32 v29, v29, v31, v65
	v_max3_i32 v33, v33, v59, v49
	v_max3_i32 v34, v144, v146, v34
	v_max3_i32 v28, v58, v60, v28
	v_max_i32_e32 v22, v61, v22
	v_max3_i32 v21, v21, v63, v62
	v_max_i32_e32 v43, v54, v43
	v_max3_i32 v20, v20, v38, v36
	v_max3_i32 v23, v56, v23, v40
	v_min_i32_e32 v31, v124, v29
	v_min_i32_e32 v49, v27, v33
	v_min_i32_e32 v32, v34, v30
	v_min_i32_e32 v35, v26, v28
; __device__ __forceinline__ void route_task(int task, int tl0, const bf16* QP  , const LAS bf16* KHL, LAS unsigned short* EL, LAS float* GL, int lane) {
;     ...
;         { const unsigned h4 = 4u * (unsigned)hi;
; #pragma unroll
;           for (int i = 0; i < 16; ++i) cur[i] -= (int)h4; }
;         int oth[16];
; #pragma unroll
;         for (int i = 0; i < 16; ++i) oth[i] = __shfl_xor(cur[i], 32);
;         merge16_desc(cur, oth);
; #pragma unroll
;         for (int i = 0; i < 16; ++i) top[half][i] = cur[i];
;     }
;     unsigned P1[4], P2[4];
; #pragma unroll
;     for (int q = 0; q < 4; ++q) { P1[q] = 0u; P2[q] = 0u;
; #pragma unroll
;         for (int s = 0; s < 4; ++s) { P1[q] |= (127u - ((unsigned)top[0][4 * q + s] & 127u)) << (8 * s); P2[q] |= (127u - ((unsigned)top[1][4 * q + s] & 127u)) << (8 * s); } }
	v_min_i32_e32 v24, v22, v21
	v_min_i32_e32 v37, v19, v25
	v_min_i32_e32 v44, v18, v43
	v_min_i32_e32 v36, v20, v23
	v_max_i32_e32 v29, v124, v29
	v_max_i32_e32 v27, v27, v33
	v_max_i32_e32 v30, v34, v30
	v_max_i32_e32 v26, v26, v28
	v_max_i32_e32 v21, v22, v21
	v_max_i32_e32 v19, v19, v25
	v_max_i32_e32 v18, v18, v43
	v_max_i32_e32 v20, v20, v23
	v_max_i32_e32 v33, v29, v27
	v_max_i32_e32 v28, v30, v26
	v_max_i32_e32 v22, v21, v19
	v_max_i32_e32 v23, v18, v20
	v_max_i32_e32 v34, v33, v28
	v_max_i32_e32 v25, v22, v23
	v_min_i32_e32 v28, v33, v28
	v_min_i32_e32 v22, v22, v23
	v_min_i32_e32 v27, v29, v27
	v_min_i32_e32 v26, v30, v26
	v_min_i32_e32 v19, v21, v19
	v_min_i32_e32 v18, v18, v20
	v_max_i32_e32 v23, v28, v22
	v_min_i32_e32 v22, v28, v22
	v_max_i32_e32 v28, v27, v26
	v_max_i32_e32 v20, v19, v18
	v_min_i32_e32 v26, v27, v26
	v_min_i32_e32 v18, v19, v18
	v_min_i32_e32 v42, v24, v37
	v_max_i32_e32 v19, v26, v18
	v_min_i32_e32 v18, v26, v18
	v_max_i32_e32 v26, v31, v49
	v_max_i32_e32 v27, v32, v35
	v_max_i32_e32 v24, v24, v37
	v_max_i32_e32 v29, v44, v36
	v_min_i32_e32 v50, v31, v49
	v_min_i32_e32 v39, v32, v35
	v_min_i32_e32 v38, v44, v36
	v_max_i32_e32 v21, v28, v20
	v_min_i32_e32 v20, v28, v20
	v_max_i32_e32 v28, v26, v27
	v_max_i32_e32 v30, v24, v29
	v_min_i32_e32 v26, v26, v27
	v_min_i32_e32 v24, v24, v29
	v_min_i32_e32 v41, v50, v39
	v_min_i32_e32 v40, v42, v38
	v_max_i32_e32 v27, v26, v24
	v_min_i32_e32 v24, v26, v24
	v_max_i32_e32 v26, v50, v39
	v_max_i32_e32 v29, v42, v38
	v_min_i32_e32 v45, v41, v40
	v_max_i32_e32 v43, v34, v25
	v_min_i32_e32 v25, v34, v25
	v_max_i32_e32 v31, v28, v30
	v_min_i32_e32 v28, v28, v30
	v_max_i32_e32 v30, v26, v29
	v_min_i32_e32 v26, v26, v29
	v_max_i32_e32 v29, v41, v40
	v_sub_u32_e32 v32, v43, v87
	v_sub_u32_e32 v25, v25, v87
	v_sub_u32_e32 v23, v23, v87
	v_sub_u32_e32 v22, v22, v87
	v_sub_u32_e32 v21, v21, v87
	v_sub_u32_e32 v20, v20, v87
	v_sub_u32_e32 v19, v19, v87
	v_sub_u32_e32 v18, v18, v87
	v_sub_u32_e32 v31, v31, v87
	v_sub_u32_e32 v28, v28, v87
	v_sub_u32_e32 v27, v27, v87
	v_sub_u32_e32 v24, v24, v87
	v_sub_u32_e32 v30, v30, v87
	v_sub_u32_e32 v26, v26, v87
	v_sub_u32_e32 v29, v29, v87
	v_sub_u32_e32 v33, v45, v87
	ds_bpermute_b32 v34, v123, v32
	ds_bpermute_b32 v35, v123, v25
	ds_bpermute_b32 v36, v123, v23
	ds_bpermute_b32 v37, v123, v22
	ds_bpermute_b32 v38, v123, v21
	ds_bpermute_b32 v39, v123, v20
	ds_bpermute_b32 v40, v123, v19
	ds_bpermute_b32 v41, v123, v18
	ds_bpermute_b32 v42, v123, v31
	ds_bpermute_b32 v43, v123, v28
	ds_bpermute_b32 v44, v123, v27
	ds_bpermute_b32 v45, v123, v33
	ds_bpermute_b32 v46, v123, v29
	ds_bpermute_b32 v47, v123, v26
	ds_bpermute_b32 v48, v123, v30
	ds_bpermute_b32 v49, v123, v24
	s_waitcnt lgkmcnt(4)
	v_max_i32_e32 v32, v32, v45
	s_waitcnt lgkmcnt(3)
	v_max_i32_e32 v25, v25, v46
	s_waitcnt lgkmcnt(2)
	v_max_i32_e32 v23, v23, v47
	s_waitcnt lgkmcnt(1)
	v_max_i32_e32 v22, v22, v48
	s_waitcnt lgkmcnt(0)
	v_max_i32_e32 v21, v21, v49
	v_max_i32_e32 v20, v20, v44
	v_max_i32_e32 v19, v19, v43
	v_max_i32_e32 v18, v18, v42
	v_max_i32_e32 v31, v31, v41
	v_max_i32_e32 v28, v28, v40
	v_max_i32_e32 v27, v27, v39
	v_max_i32_e32 v24, v24, v38
	v_max_i32_e32 v30, v30, v37
	v_max_i32_e32 v26, v26, v36
	v_max_i32_e32 v29, v29, v35
	v_max_i32_e32 v33, v33, v34
	v_max_i32_e32 v34, v32, v31
	v_min_i32_e32 v31, v32, v31
	v_max_i32_e32 v32, v25, v28
	v_min_i32_e32 v25, v25, v28
	v_max_i32_e32 v28, v23, v27
	v_min_i32_e32 v23, v23, v27
	v_max_i32_e32 v27, v22, v24
	v_min_i32_e32 v22, v22, v24
	v_max_i32_e32 v24, v21, v30
	v_min_i32_e32 v21, v21, v30
	v_max_i32_e32 v30, v20, v26
	v_min_i32_e32 v20, v20, v26
	v_max_i32_e32 v26, v19, v29
	v_min_i32_e32 v19, v19, v29
	v_max_i32_e32 v29, v18, v33
	v_min_i32_e32 v18, v18, v33
	v_max_i32_e32 v33, v34, v24
	v_min_i32_e32 v24, v34, v24
	v_max_i32_e32 v34, v32, v30
	v_min_i32_e32 v30, v32, v30
	v_max_i32_e32 v32, v28, v26
	v_min_i32_e32 v26, v28, v26
	v_max_i32_e32 v28, v27, v29
	v_min_i32_e32 v27, v27, v29
	v_max_i32_e32 v29, v31, v21
	v_min_i32_e32 v21, v31, v21
	v_max_i32_e32 v31, v25, v20
	v_min_i32_e32 v20, v25, v20
	v_max_i32_e32 v25, v23, v19
	v_min_i32_e32 v19, v23, v19
	v_max_i32_e32 v23, v22, v18
	v_min_i32_e32 v18, v22, v18
	v_max_i32_e32 v22, v33, v32
	v_min_i32_e32 v32, v33, v32
	v_max_i32_e32 v33, v34, v28
	v_min_i32_e32 v28, v34, v28
	v_max_i32_e32 v34, v24, v26
	v_min_i32_e32 v24, v24, v26
	v_max_i32_e32 v35, v30, v27
	v_min_i32_e32 v27, v30, v27
	v_max_i32_e32 v30, v29, v25
	v_min_i32_e32 v25, v29, v25
	v_max_i32_e32 v29, v31, v23
	v_min_i32_e32 v23, v31, v23
	v_max_i32_e32 v31, v21, v19
	v_min_i32_e32 v19, v21, v19
	v_max_i32_e32 v21, v20, v18
	v_min_i32_e32 v18, v20, v18
	v_max_i32_e32 v26, v22, v33
	v_min_i32_e32 v33, v22, v33
	v_lshlrev_b32_e32 v20, 8, v81
	v_lshlrev_b32_e32 v22, 16, v80
	v_max_i32_e32 v36, v32, v28
	v_max_i32_e32 v40, v19, v18
	v_min_i32_e32 v41, v19, v18
	v_and_b32_e32 v18, 0x7f, v79
	v_and_b32_e32 v20, 0x7f00, v20
	v_and_b32_e32 v22, 0x7f0000, v22
	v_max_i32_e32 v39, v31, v21
	v_min_i32_e32 v31, v31, v21
	v_lshlrev_b32_e32 v21, 8, v33
	v_or3_b32 v18, v20, v18, v22
	v_lshlrev_b32_e32 v20, 16, v36
	v_and_b32_e32 v19, 0x7f, v26
	v_and_b32_e32 v21, 0x7f00, v21
	v_and_b32_e32 v20, 0x7f0000, v20
	v_or3_b32 v20, v21, v19, v20
	v_lshlrev_b32_e32 v19, 24, v78
	v_min_i32_e32 v28, v32, v28
	v_and_b32_e32 v19, 0x7f000000, v19
	v_bitop3_b32 v19, v18, s68, v19 bitop3:0x36
	v_lshlrev_b32_e32 v18, 24, v28
	v_max_i32_e32 v32, v34, v35
	v_min_i32_e32 v34, v34, v35
	v_max_i32_e32 v35, v24, v27
	v_min_i32_e32 v27, v24, v27
	v_and_b32_e32 v18, 0x7f000000, v18
	v_lshlrev_b32_e32 v22, 8, v76
	v_lshlrev_b32_e32 v24, 16, v75
; __device__ __forceinline__ void route_task(int task, int tl0, const bf16* QP  , const LAS bf16* KHL, LAS unsigned short* EL, LAS float* GL, int lane) {
;     ...
;     unsigned P1[4], P2[4];
; #pragma unroll
;     for (int q = 0; q < 4; ++q) { P1[q] = 0u; P2[q] = 0u;
; #pragma unroll
;         for (int s = 0; s < 4; ++s) { P1[q] |= (127u - ((unsigned)top[0][4 * q + s] & 127u)) << (8 * s); P2[q] |= (127u - ((unsigned)top[1][4 * q + s] & 127u)) << (8 * s); } }
;     int bk[16];
;     {
;         int hi2 = hi; asm volatile("" : "+v"(hi2));
;         const bool h1 = hi2 != 0;
;         constexpr int A1[16] = {1, 1, 1, 1, 1, 1, 1, 1, 2, 2, 2, 2, 2, 3, 3, 3}, B1[16] = {0, 1, 2, 3, 4, 5, 6, 7, 0, 1, 2, 3, 4, 0, 1, 2};
; #pragma unroll
;         for (int i = 0; i < 16; ++i) { const float ta = __int_as_float(h1 ? top[0][A1[i]] : top[0][0]), tb = __int_as_float(h1 ? top[1][B1[i]] : top[1][i]); const unsigned code = h1 ? (unsigned)(A1[i] * 16 + B1[i]) : (unsigned)i;
;             bk[i] = (int)((__float_as_uint(ta + tb) | 255u) - code); }
;         sort16_desc(bk);
	v_bitop3_b32 v18, v20, s68, v18 bitop3:0x36
	v_and_b32_e32 v20, 0x7f, v77
	v_and_b32_e32 v22, 0x7f00, v22
	v_and_b32_e32 v24, 0x7f0000, v24
	v_max_i32_e32 v37, v30, v29
	v_min_i32_e32 v29, v30, v29
	v_max_i32_e32 v30, v25, v23
	v_min_i32_e32 v38, v25, v23
	v_lshlrev_b32_e32 v23, 8, v34
	v_or3_b32 v20, v22, v20, v24
	v_lshlrev_b32_e32 v22, 16, v35
	v_and_b32_e32 v21, 0x7f, v32
	v_and_b32_e32 v23, 0x7f00, v23
	v_and_b32_e32 v22, 0x7f0000, v22
	v_or3_b32 v22, v23, v21, v22
	v_lshlrev_b32_e32 v21, 24, v73
	v_and_b32_e32 v21, 0x7f000000, v21
	v_bitop3_b32 v21, v20, s68, v21 bitop3:0x36
	v_lshlrev_b32_e32 v20, 24, v27
	v_and_b32_e32 v20, 0x7f000000, v20
	v_lshlrev_b32_e32 v24, 8, v74
	v_lshlrev_b32_e32 v42, 16, v72
	v_bitop3_b32 v20, v22, s68, v20 bitop3:0x36
	v_and_b32_e32 v22, 0x7f, v71
	v_and_b32_e32 v24, 0x7f00, v24
	v_and_b32_e32 v42, 0x7f0000, v42
	v_lshlrev_b32_e32 v25, 8, v29
	v_or3_b32 v22, v24, v22, v42
	v_lshlrev_b32_e32 v24, 16, v30
	v_and_b32_e32 v23, 0x7f, v37
	v_and_b32_e32 v25, 0x7f00, v25
	v_and_b32_e32 v24, 0x7f0000, v24
	v_or3_b32 v24, v25, v23, v24
	v_lshlrev_b32_e32 v23, 24, v70
	v_and_b32_e32 v23, 0x7f000000, v23
	v_bitop3_b32 v23, v22, s68, v23 bitop3:0x36
	v_lshlrev_b32_e32 v22, 24, v38
	v_and_b32_e32 v22, 0x7f000000, v22
	v_lshlrev_b32_e32 v42, 8, v68
	v_lshlrev_b32_e32 v44, 16, v67
	v_bitop3_b32 v22, v24, s68, v22 bitop3:0x36
	v_and_b32_e32 v24, 0x7f, v69
	v_and_b32_e32 v42, 0x7f00, v42
	v_and_b32_e32 v44, 0x7f0000, v44
	v_lshlrev_b32_e32 v43, 8, v31
	v_or3_b32 v24, v42, v24, v44
	v_lshlrev_b32_e32 v42, 16, v40
	v_and_b32_e32 v25, 0x7f, v39
	v_and_b32_e32 v43, 0x7f00, v43
	v_and_b32_e32 v42, 0x7f0000, v42
	v_or3_b32 v42, v43, v25, v42
	v_lshlrev_b32_e32 v25, 24, v66
	v_and_b32_e32 v25, 0x7f000000, v25
	v_bitop3_b32 v25, v24, s68, v25 bitop3:0x36
	v_lshlrev_b32_e32 v24, 24, v41
	v_and_b32_e32 v24, 0x7f000000, v24
	v_bitop3_b32 v24, v42, s68, v24 bitop3:0x36
	v_mov_b32_e32 v42, v86
	v_add_f32_e32 v62, v74, v26
	v_cmp_eq_u32_e32 vcc, 0, v42
	v_add_f32_e32 v63, v72, v26
	v_add_f32_e32 v64, v70, v26
	v_cndmask_b32_e32 v42, v81, v79, vcc
	v_add_f32_e32 v44, v42, v26
	v_cndmask_b32_e64 v43, -16, 0, vcc
	v_or_b32_e32 v44, 0xff, v44
	v_add_f32_e32 v45, v42, v33
	v_add_u32_e32 v43, v44, v43
	v_cndmask_b32_e64 v44, v99, -1, vcc
	v_or_b32_e32 v45, 0xff, v45
	v_add_f32_e32 v46, v42, v36
	v_add_u32_e32 v44, v45, v44
	v_cndmask_b32_e64 v45, v100, -2, vcc
	v_or_b32_e32 v46, 0xff, v46
	v_add_f32_e32 v47, v42, v28
	v_add_u32_e32 v45, v46, v45
	v_cndmask_b32_e64 v46, v101, -3, vcc
	v_or_b32_e32 v47, 0xff, v47
	v_add_f32_e32 v48, v42, v32
	v_add_u32_e32 v46, v47, v46
	v_cndmask_b32_e64 v47, v102, -4, vcc
	v_or_b32_e32 v48, 0xff, v48
	v_add_f32_e32 v34, v42, v34
	v_add_f32_e32 v35, v42, v35
	v_add_f32_e32 v27, v42, v27
	v_cndmask_b32_e32 v42, v80, v79, vcc
	v_cndmask_b32_e32 v32, v32, v39, vcc
	v_add_u32_e32 v47, v48, v47
	v_cndmask_b32_e64 v48, v103, -5, vcc
	v_or_b32_e32 v34, 0xff, v34
	v_add_f32_e32 v32, v42, v32
	v_add_u32_e32 v34, v34, v48
	v_cndmask_b32_e64 v48, v104, -6, vcc
	v_or_b32_e32 v35, 0xff, v35
	v_cndmask_b32_e32 v37, v26, v37, vcc
	v_cndmask_b32_e64 v39, v116, -12, vcc
	v_or_b32_e32 v32, 0xff, v32
	v_add_u32_e32 v35, v35, v48
	v_cndmask_b32_e64 v48, v105, -7, vcc
	v_or_b32_e32 v27, 0xff, v27
	v_add_f32_e32 v37, v42, v37
	v_cndmask_b32_e32 v29, v33, v29, vcc
	v_add_u32_e32 v32, v32, v39
	v_cndmask_b32_e32 v39, v78, v79, vcc
	v_cndmask_b32_e32 v31, v26, v31, vcc
	v_add_u32_e32 v27, v27, v48
	v_cndmask_b32_e64 v48, v106, -8, vcc
	v_or_b32_e32 v37, 0xff, v37
	v_add_f32_e32 v29, v42, v29
	v_cndmask_b32_e32 v30, v36, v30, vcc
	v_cndmask_b32_e32 v38, v28, v38, vcc
	v_add_f32_e32 v31, v39, v31
	v_cndmask_b32_e32 v40, v33, v40, vcc
	v_add_u32_e32 v37, v37, v48
	v_cndmask_b32_e64 v48, v107, -9, vcc
	v_or_b32_e32 v29, 0xff, v29
	v_add_f32_e32 v30, v42, v30
	v_add_f32_e32 v38, v42, v38
	v_cndmask_b32_e64 v42, v117, -13, vcc
	v_or_b32_e32 v31, 0xff, v31
	v_add_f32_e32 v40, v39, v40
	v_cndmask_b32_e32 v41, v36, v41, vcc
	v_add_u32_e32 v29, v29, v48
	v_cndmask_b32_e64 v48, v114, -10, vcc
	v_or_b32_e32 v30, 0xff, v30
	v_add_u32_e32 v31, v31, v42
	v_cndmask_b32_e64 v42, v118, -14, vcc
	v_or_b32_e32 v40, 0xff, v40
	v_add_f32_e32 v39, v39, v41
	v_add_u32_e32 v30, v30, v48
	v_cndmask_b32_e64 v48, v115, -11, vcc
	v_or_b32_e32 v38, 0xff, v38
	v_add_u32_e32 v40, v40, v42
	v_cndmask_b32_e64 v42, v119, -15, vcc
	v_or_b32_e32 v39, 0xff, v39
	v_add_u32_e32 v38, v38, v48
	v_add_u32_e32 v39, v39, v42
	v_max_i32_e32 v41, v43, v31
	v_min_i32_e32 v31, v43, v31
	v_max_i32_e32 v42, v44, v32
	v_min_i32_e32 v32, v44, v32
	v_max_i32_e32 v43, v45, v39
	v_min_i32_e32 v39, v45, v39
	v_max_i32_e32 v44, v46, v40
	v_min_i32_e32 v40, v46, v40
	v_max_i32_e32 v45, v47, v37
	v_min_i32_e32 v37, v47, v37
	v_max_i32_e32 v46, v34, v35
	v_min_i32_e32 v34, v34, v35
	v_max_i32_e32 v35, v27, v38
	v_min_i32_e32 v27, v27, v38
	v_max_i32_e32 v38, v29, v30
	v_min_i32_e32 v29, v29, v30
	v_max_i32_e32 v30, v41, v46
	v_min_i32_e32 v41, v41, v46
	v_max_i32_e32 v46, v42, v35
	v_min_i32_e32 v35, v42, v35
	v_max_i32_e32 v42, v43, v38
	v_min_i32_e32 v38, v43, v38
	v_max_i32_e32 v43, v44, v45
	v_min_i32_e32 v44, v44, v45
	v_max_i32_e32 v45, v34, v31
	v_min_i32_e32 v31, v34, v31
	v_max_i32_e32 v34, v37, v40
	v_min_i32_e32 v37, v37, v40
	v_max_i32_e32 v40, v29, v39
	v_min_i32_e32 v29, v29, v39
	v_max_i32_e32 v39, v27, v32
	v_min_i32_e32 v27, v27, v32
	v_max_i32_e32 v32, v30, v46
	v_min_i32_e32 v30, v30, v46
	v_max_i32_e32 v46, v42, v43
	v_min_i32_e32 v42, v42, v43
	v_max_i32_e32 v43, v44, v41
	v_min_i32_e32 v41, v44, v41
	v_max_i32_e32 v44, v45, v34
	v_min_i32_e32 v34, v45, v34
; #define CAND(a, b) (int)((__float_as_uint(__int_as_float(top[0][a]) + __int_as_float(top[1][b])) | 255u) - (unsigned)((a) * 16 + (b)))
; __device__ __forceinline__ void route_task(int task, int tl0, const bf16* QP  , const LAS bf16* KHL, LAS unsigned short* EL, LAS float* GL, int lane) {
;     ...
;         sort16_desc(bk);
;         int oth[16];
; #pragma unroll
;         for (int i = 0; i < 16; ++i) oth[i] = __shfl_xor(bk[i], 32);
;         merge16_desc(bk, oth);
;     }
;     ...
;     {
;         int gk[16];
;         gk[0] = CAND(3, 3); gk[1] = CAND(4, 0); gk[2] = CAND(4, 1); gk[3] = CAND(4, 2); gk[4] = CAND(5, 0); gk[5] = CAND(5, 1); gk[6] = CAND(6, 0); gk[7] = CAND(6, 1);
;         gk[8] = CAND(7, 0); gk[9] = CAND(7, 1); gk[10] = CAND(8, 0); gk[11] = CAND(9, 0); gk[12] = CAND(10, 0); gk[13] = CAND(11, 0); gk[14] = CAND(12, 0); gk[15] = CAND(13, 0);
;         sort16_desc(gk);
	v_max_i32_e32 v45, v35, v38
	v_min_i32_e32 v35, v35, v38
	v_max_i32_e32 v38, v40, v39
	v_min_i32_e32 v39, v40, v39
	v_max_i32_e32 v40, v27, v31
	v_min_i32_e32 v27, v27, v31
	v_max_i32_e32 v31, v37, v29
	v_min_i32_e32 v29, v37, v29
	v_max_i32_e32 v37, v32, v46
	v_min_i32_e32 v32, v32, v46
	v_max_i32_e32 v46, v30, v42
	v_min_i32_e32 v30, v30, v42
	v_max_i32_e32 v42, v43, v38
	v_min_i32_e32 v38, v43, v38
	v_max_i32_e32 v43, v41, v39
	v_min_i32_e32 v39, v41, v39
	v_max_i32_e32 v41, v44, v45
	v_min_i32_e32 v44, v44, v45
	v_max_i32_e32 v45, v34, v35
	v_min_i32_e32 v34, v34, v35
	v_max_i32_e32 v35, v40, v31
	v_min_i32_e32 v31, v40, v31
	v_max_i32_e32 v40, v27, v29
	v_min_i32_e32 v27, v27, v29
	v_max_i32_e32 v29, v46, v32
	v_min_i32_e32 v32, v46, v32
	v_max_i32_e32 v46, v30, v35
	v_min_i32_e32 v30, v30, v35
	v_max_i32_e32 v35, v42, v41
	v_min_i32_e32 v41, v42, v41
	v_max_i32_e32 v42, v43, v44
	v_min_i32_e32 v43, v43, v44
	v_max_i32_e32 v44, v45, v38
	v_min_i32_e32 v38, v45, v38
	v_max_i32_e32 v45, v34, v39
	v_min_i32_e32 v34, v34, v39
	v_max_i32_e32 v39, v40, v31
	v_min_i32_e32 v31, v40, v31
	v_max_i32_e32 v40, v29, v35
	v_min_i32_e32 v29, v29, v35
	v_max_i32_e32 v35, v32, v41
	v_min_i32_e32 v32, v32, v41
	v_max_i32_e32 v41, v42, v44
	v_min_i32_e32 v42, v42, v44
	v_max_i32_e32 v44, v43, v38
	v_min_i32_e32 v38, v43, v38
	v_max_i32_e32 v43, v45, v39
	v_min_i32_e32 v39, v45, v39
	v_max_i32_e32 v45, v34, v31
	v_min_i32_e32 v31, v34, v31
	v_max_i32_e32 v34, v35, v29
	v_min_i32_e32 v29, v35, v29
	v_max_i32_e32 v35, v46, v32
	v_min_i32_e32 v32, v46, v32
	v_max_i32_e32 v46, v43, v30
	v_min_i32_e32 v30, v43, v30
	v_max_i32_e32 v43, v45, v39
	v_min_i32_e32 v39, v45, v39
	v_max_i32_e32 v45, v35, v41
	v_min_i32_e32 v35, v35, v41
	v_max_i32_e32 v41, v32, v42
	v_min_i32_e32 v32, v32, v42
	v_max_i32_e32 v42, v44, v46
	v_min_i32_e32 v44, v44, v46
	v_max_i32_e32 v46, v38, v30
	v_min_i32_e32 v30, v38, v30
	v_max_i32_e32 v38, v45, v29
	v_min_i32_e32 v29, v45, v29
	v_max_i32_e32 v45, v35, v41
	v_min_i32_e32 v35, v35, v41
	v_max_i32_e32 v41, v42, v32
	v_min_i32_e32 v32, v42, v32
	v_max_i32_e32 v42, v44, v46
	v_min_i32_e32 v44, v44, v46
	v_max_i32_e32 v46, v43, v30
	v_min_i32_e32 v30, v43, v30
	v_max_i32_e32 v43, v35, v41
	v_min_i32_e32 v35, v35, v41
	v_max_i32_e32 v41, v32, v42
	v_min_i32_e32 v32, v32, v42
	ds_bpermute_b32 v54, v123, v41
	ds_bpermute_b32 v55, v123, v32
	ds_bpermute_b32 v56, v123, v44
	ds_bpermute_b32 v57, v123, v27
	ds_bpermute_b32 v58, v123, v31
	ds_bpermute_b32 v59, v123, v39
	ds_bpermute_b32 v60, v123, v30
	ds_bpermute_b32 v61, v123, v46
	ds_bpermute_b32 v42, v123, v37
	ds_bpermute_b32 v47, v123, v40
	ds_bpermute_b32 v48, v123, v34
	ds_bpermute_b32 v49, v123, v38
	ds_bpermute_b32 v50, v123, v29
	ds_bpermute_b32 v51, v123, v45
	ds_bpermute_b32 v52, v123, v43
	ds_bpermute_b32 v53, v123, v35
	s_waitcnt lgkmcnt(12)
	v_max_i32_e32 v37, v37, v57
	s_waitcnt lgkmcnt(11)
	v_max_i32_e32 v40, v40, v58
	s_waitcnt lgkmcnt(10)
	v_max_i32_e32 v34, v34, v59
	s_waitcnt lgkmcnt(9)
	v_max_i32_e32 v38, v38, v60
	s_waitcnt lgkmcnt(8)
	v_max_i32_e32 v29, v29, v61
	v_max_i32_e32 v45, v45, v56
	v_max_i32_e32 v43, v43, v55
	v_max_i32_e32 v35, v35, v54
	v_add_f32_e32 v28, v78, v28
	v_add_f32_e32 v54, v77, v26
	v_add_f32_e32 v55, v77, v33
	v_add_f32_e32 v36, v77, v36
	v_add_f32_e32 v56, v76, v26
	v_add_f32_e32 v57, v76, v33
	v_add_f32_e32 v58, v75, v26
	v_add_f32_e32 v59, v75, v33
	v_add_f32_e32 v60, v73, v26
	v_add_f32_e32 v33, v73, v33
	v_add_f32_e32 v61, v71, v26
	v_add_f32_e32 v65, v69, v26
	v_add_f32_e32 v68, v68, v26
	v_or_b32_e32 v28, 0xff, v28
	v_or_b32_e32 v54, 0xff, v54
	v_or_b32_e32 v55, 0xff, v55
	v_or_b32_e32 v36, 0xff, v36
	v_or_b32_e32 v56, 0xff, v56
	v_or_b32_e32 v57, 0xff, v57
	v_or_b32_e32 v58, 0xff, v58
	v_or_b32_e32 v59, 0xff, v59
	v_or_b32_e32 v60, 0xff, v60
	v_or_b32_e32 v33, 0xff, v33
	v_or_b32_e32 v61, 0xff, v61
	v_or_b32_e32 v62, 0xff, v62
	v_or_b32_e32 v63, 0xff, v63
	v_or_b32_e32 v64, 0xff, v64
	v_or_b32_e32 v65, 0xff, v65
	v_or_b32_e32 v68, 0xff, v68
	v_subrev_u32_e32 v28, 51, v28
	v_subrev_u32_e32 v54, 64, v54
	v_add_u32_e32 v55, 0xffffffbf, v55
	v_add_u32_e32 v36, 0xffffffbe, v36
	v_add_u32_e32 v56, 0xffffffb0, v56
	v_add_u32_e32 v57, 0xffffffaf, v57
	v_add_u32_e32 v58, 0xffffffa0, v58
	v_add_u32_e32 v59, 0xffffff9f, v59
	v_add_u32_e32 v60, 0xffffff90, v60
	v_add_u32_e32 v33, 0xffffff8f, v33
	v_add_u32_e32 v61, 0xffffff80, v61
	v_add_u32_e32 v62, 0xffffff70, v62
	v_add_u32_e32 v63, 0xffffff60, v63
	v_add_u32_e32 v64, 0xffffff50, v64
	v_add_u32_e32 v65, 0xffffff40, v65
	v_add_u32_e32 v68, 0xffffff30, v68
	v_max_i32_e32 v69, v28, v64
	v_min_i32_e32 v28, v28, v64
	v_max_i32_e32 v64, v54, v63
	v_min_i32_e32 v54, v54, v63
	v_max_i32_e32 v63, v55, v68
	v_min_i32_e32 v55, v55, v68
	v_max_i32_e32 v68, v36, v65
	v_min_i32_e32 v36, v36, v65
	v_max_i32_e32 v65, v56, v60
	v_min_i32_e32 v56, v56, v60
	v_max_i32_e32 v60, v57, v58
	v_min_i32_e32 v57, v57, v58
	v_max_i32_e32 v58, v59, v62
	v_min_i32_e32 v59, v59, v62
	v_max_i32_e32 v62, v33, v61
	v_min_i32_e32 v33, v33, v61
	v_max_i32_e32 v61, v69, v60
	v_min_i32_e32 v60, v69, v60
	v_max_i32_e32 v69, v64, v58
	v_min_i32_e32 v58, v64, v58
	v_max_i32_e32 v64, v63, v62
	v_min_i32_e32 v62, v63, v62
	v_max_i32_e32 v63, v68, v65
	v_min_i32_e32 v65, v68, v65
	v_max_i32_e32 v68, v57, v28
	v_min_i32_e32 v28, v57, v28
	v_max_i32_e32 v57, v56, v36
	v_min_i32_e32 v36, v56, v36
	v_max_i32_e32 v56, v33, v55
	v_min_i32_e32 v33, v33, v55
	v_max_i32_e32 v55, v59, v54
	v_min_i32_e32 v54, v59, v54
	v_max_i32_e32 v59, v61, v69
	v_min_i32_e32 v61, v61, v69
	v_max_i32_e32 v69, v64, v63
	v_min_i32_e32 v63, v64, v63
	v_max_i32_e32 v64, v65, v60
	v_min_i32_e32 v60, v65, v60
	v_max_i32_e32 v65, v68, v57
	v_min_i32_e32 v57, v68, v57
	v_max_i32_e32 v68, v58, v62
	v_min_i32_e32 v58, v58, v62
	v_max_i32_e32 v62, v56, v55
	v_min_i32_e32 v55, v56, v55
	v_max_i32_e32 v56, v54, v28
	v_min_i32_e32 v28, v54, v28
	v_max_i32_e32 v54, v36, v33
	v_min_i32_e32 v33, v36, v33
	v_min_i32_e32 v36, v59, v69
	v_max_i32_e32 v70, v61, v63
	v_min_i32_e32 v61, v61, v63
	v_max_i32_e32 v63, v64, v62
	v_min_i32_e32 v62, v64, v62
	v_max_i32_e32 v64, v60, v55
	v_min_i32_e32 v55, v60, v55
	v_max_i32_e32 v60, v65, v68
	v_min_i32_e32 v65, v65, v68
	v_max_i32_e32 v68, v57, v58
	v_min_i32_e32 v57, v57, v58
	v_max_i32_e32 v58, v56, v54
	v_min_i32_e32 v54, v56, v54
	v_max_i32_e32 v56, v28, v33
	v_min_i32_e32 v28, v28, v33
	v_max_i32_e32 v33, v70, v36
	v_min_i32_e32 v36, v70, v36
	v_max_i32_e32 v70, v61, v58
	v_min_i32_e32 v58, v61, v58
	v_max_i32_e32 v61, v63, v60
	v_min_i32_e32 v60, v63, v60
	v_max_i32_e32 v63, v64, v65
	v_min_i32_e32 v64, v64, v65
	v_max_i32_e32 v65, v68, v62
	v_min_i32_e32 v62, v68, v62
	v_max_i32_e32 v68, v57, v55
	v_min_i32_e32 v55, v57, v55
	v_max_i32_e32 v57, v56, v54
	s_waitcnt lgkmcnt(0)
; #define CAND(a, b) (int)((__float_as_uint(__int_as_float(top[0][a]) + __int_as_float(top[1][b])) | 255u) - (unsigned)((a) * 16 + (b)))
; __device__ __forceinline__ void route_task(int task, int tl0, const bf16* QP  , const LAS bf16* KHL, LAS unsigned short* EL, LAS float* GL, int lane) {
;     ...
;         merge16_desc(bk, oth);
;     }
;     ...
;     {
;         int gk[16];
;         gk[0] = CAND(3, 3); gk[1] = CAND(4, 0); gk[2] = CAND(4, 1); gk[3] = CAND(4, 2); gk[4] = CAND(5, 0); gk[5] = CAND(5, 1); gk[6] = CAND(6, 0); gk[7] = CAND(6, 1);
;         gk[8] = CAND(7, 0); gk[9] = CAND(7, 1); gk[10] = CAND(8, 0); gk[11] = CAND(9, 0); gk[12] = CAND(10, 0); gk[13] = CAND(11, 0); gk[14] = CAND(12, 0); gk[15] = CAND(13, 0);
;         sort16_desc(gk);
;         merge16_desc(bk, gk);
;     }
;     {
;         const int c14 = CAND(14, 0), c15 = CAND(15, 0);
;         const int n14 = max(bk[14], c14), n15 = max(min(bk[14], c14), max(bk[15], c15));
;         bk[14] = n14; bk[15] = n15;
	v_max_i32_e32 v41, v41, v53
	v_max_i32_e32 v32, v32, v52
	v_max_i32_e32 v44, v44, v51
	v_max_i32_e32 v46, v46, v50
	v_max_i32_e32 v30, v30, v49
	v_max_i32_e32 v39, v39, v48
	v_max_i32_e32 v31, v31, v47
	v_max_i32_e32 v27, v27, v42
	v_min_i32_e32 v54, v56, v54
	v_max_i32_e32 v56, v33, v61
	v_min_i32_e32 v33, v33, v61
	v_max_i32_e32 v61, v36, v60
	v_min_i32_e32 v36, v36, v60
	v_max_i32_e32 v60, v63, v65
	v_min_i32_e32 v63, v63, v65
	v_max_i32_e32 v65, v64, v62
	v_min_i32_e32 v62, v64, v62
	v_max_i32_e32 v64, v68, v57
	v_max_i32_e32 v42, v37, v41
	v_min_i32_e32 v37, v37, v41
	v_max_i32_e32 v41, v40, v32
	v_min_i32_e32 v32, v40, v32
	v_max_i32_e32 v40, v34, v44
	v_min_i32_e32 v34, v34, v44
	v_max_i32_e32 v44, v38, v46
	v_min_i32_e32 v38, v38, v46
	v_max_i32_e32 v46, v29, v30
	v_min_i32_e32 v29, v29, v30
	v_max_i32_e32 v30, v45, v39
	v_min_i32_e32 v39, v45, v39
	v_max_i32_e32 v45, v43, v31
	v_min_i32_e32 v31, v43, v31
	v_max_i32_e32 v43, v35, v27
	v_min_i32_e32 v27, v35, v27
	v_min_i32_e32 v57, v68, v57
	v_max_i32_e32 v68, v55, v54
	v_max_i32_e32 v71, v70, v36
	v_min_i32_e32 v36, v70, v36
	v_max_i32_e32 v70, v64, v58
	v_min_i32_e32 v58, v64, v58
	v_max_i32_e32 v35, v42, v46
	v_min_i32_e32 v42, v42, v46
	v_max_i32_e32 v46, v41, v30
	v_min_i32_e32 v30, v41, v30
	v_max_i32_e32 v41, v40, v45
	v_min_i32_e32 v40, v40, v45
	v_max_i32_e32 v45, v44, v43
	v_min_i32_e32 v43, v44, v43
	v_max_i32_e32 v44, v37, v29
	v_min_i32_e32 v29, v37, v29
	v_max_i32_e32 v37, v32, v39
	v_min_i32_e32 v32, v32, v39
	v_max_i32_e32 v39, v34, v31
	v_min_i32_e32 v31, v34, v31
	v_max_i32_e32 v34, v38, v27
	v_min_i32_e32 v27, v38, v27
	v_min_i32_e32 v54, v55, v54
	v_min_i32_e32 v55, v61, v33
	v_max_i32_e32 v64, v68, v57
	v_min_i32_e32 v57, v68, v57
	v_max_i32_e32 v68, v71, v60
	v_min_i32_e32 v60, v71, v60
	v_max_i32_e32 v71, v36, v63
	v_min_i32_e32 v36, v36, v63
	v_max_i32_e32 v63, v65, v70
	v_min_i32_e32 v65, v65, v70
	v_max_i32_e32 v70, v62, v58
	v_max_i32_e32 v38, v35, v41
	v_min_i32_e32 v35, v35, v41
	v_max_i32_e32 v41, v46, v45
	v_min_i32_e32 v45, v46, v45
	v_max_i32_e32 v46, v42, v40
	v_min_i32_e32 v40, v42, v40
	v_max_i32_e32 v42, v30, v43
	v_min_i32_e32 v30, v30, v43
	v_max_i32_e32 v43, v44, v39
	v_min_i32_e32 v39, v44, v39
	v_max_i32_e32 v44, v37, v34
	v_min_i32_e32 v34, v37, v34
	v_max_i32_e32 v37, v29, v31
	v_min_i32_e32 v29, v29, v31
	v_max_i32_e32 v31, v32, v27
	v_min_i32_e32 v27, v32, v27
	v_min_i32_e32 v58, v62, v58
	v_max_i32_e32 v62, v68, v55
	v_min_i32_e32 v55, v68, v55
	v_max_i32_e32 v68, v60, v71
	v_min_i32_e32 v60, v60, v71
	v_max_i32_e32 v71, v63, v36
	v_min_i32_e32 v36, v63, v36
	v_max_i32_e32 v63, v65, v70
	v_min_i32_e32 v32, v38, v41
	v_min_i32_e32 v47, v35, v45
	v_min_i32_e32 v48, v46, v42
	v_min_i32_e32 v49, v40, v30
	v_min_i32_e32 v50, v43, v44
	v_min_i32_e32 v51, v39, v34
	v_min_i32_e32 v52, v37, v31
	v_min_i32_e32 v53, v29, v27
	v_min_i32_e32 v65, v65, v70
	v_max_i32_e32 v70, v64, v58
	v_min_i32_e32 v58, v64, v58
	v_min_i32_e32 v64, v60, v71
	v_min_i32_e32 v72, v36, v63
	v_max3_i32 v28, v38, v41, v28
	v_max_i32_e32 v32, v32, v54
	v_max3_i32 v35, v35, v45, v57
	v_max_i32_e32 v38, v47, v58
	v_max3_i32 v41, v46, v42, v70
	v_max_i32_e32 v42, v48, v65
	v_max3_i32 v30, v40, v30, v72
	v_max3_i32 v36, v49, v36, v63
	v_max3_i32 v40, v43, v44, v64
	v_max3_i32 v43, v50, v60, v71
	v_max3_i32 v34, v39, v34, v68
	v_max_i32_e32 v39, v51, v55
	v_max3_i32 v31, v37, v31, v62
	v_max3_i32 v33, v52, v61, v33
	v_max3_i32 v27, v29, v27, v56
	v_max3_i32 v29, v53, v59, v69
	v_max_i32_e32 v37, v28, v40
	v_min_i32_e32 v28, v28, v40
	v_max_i32_e32 v40, v32, v43
	v_min_i32_e32 v32, v32, v43
	v_max_i32_e32 v43, v35, v34
	v_min_i32_e32 v34, v35, v34
	v_max_i32_e32 v35, v38, v39
	v_min_i32_e32 v38, v38, v39
	v_max_i32_e32 v39, v41, v31
	v_min_i32_e32 v31, v41, v31
	v_max_i32_e32 v41, v42, v33
	v_min_i32_e32 v33, v42, v33
	v_max_i32_e32 v42, v30, v27
	v_min_i32_e32 v27, v30, v27
	v_max_i32_e32 v30, v36, v29
	v_min_i32_e32 v29, v36, v29
	v_max_i32_e32 v36, v37, v39
	v_min_i32_e32 v37, v37, v39
	v_max_i32_e32 v39, v40, v41
	v_min_i32_e32 v40, v40, v41
	v_max_i32_e32 v41, v43, v42
	v_min_i32_e32 v42, v43, v42
	v_max_i32_e32 v43, v35, v30
	v_min_i32_e32 v30, v35, v30
	v_max_i32_e32 v35, v28, v31
	v_min_i32_e32 v28, v28, v31
	v_max_i32_e32 v31, v32, v33
	v_min_i32_e32 v32, v32, v33
	v_max_i32_e32 v33, v34, v27
	v_min_i32_e32 v27, v34, v27
	v_max_i32_e32 v34, v38, v29
	v_min_i32_e32 v29, v38, v29
	v_max_i32_e32 v38, v36, v41
	v_min_i32_e32 v36, v36, v41
	v_max_i32_e32 v41, v39, v43
	v_min_i32_e32 v39, v39, v43
	v_max_i32_e32 v43, v37, v42
	v_min_i32_e32 v37, v37, v42
	v_max_i32_e32 v42, v40, v30
	v_min_i32_e32 v30, v40, v30
	v_max_i32_e32 v40, v35, v33
	v_min_i32_e32 v33, v35, v33
	v_max_i32_e32 v35, v31, v34
	v_min_i32_e32 v31, v31, v34
	v_max_i32_e32 v34, v28, v27
	v_min_i32_e32 v27, v28, v27
	v_max_i32_e32 v28, v32, v29
	v_min_i32_e32 v29, v32, v29
	v_max_i32_e32 v32, v38, v41
	v_min_i32_e32 v38, v38, v41
	v_max_i32_e32 v41, v36, v39
	v_min_i32_e32 v36, v36, v39
	v_max_i32_e32 v39, v43, v42
	v_min_i32_e32 v42, v43, v42
	v_max_i32_e32 v43, v37, v30
	v_min_i32_e32 v30, v37, v30
	v_max_i32_e32 v37, v40, v35
	v_min_i32_e32 v35, v40, v35
	v_max_i32_e32 v40, v33, v31
	v_min_i32_e32 v31, v33, v31
	v_max_i32_e32 v33, v34, v28
	v_min_i32_e32 v28, v34, v28
	v_max_i32_e32 v34, v27, v29
	v_min_i32_e32 v27, v27, v29
	v_add_f32_e32 v29, v67, v26
	v_or_b32_e32 v29, 0xff, v29
	v_add_f32_e32 v26, v66, v26
	v_add_u32_e32 v29, 0xffffff20, v29
	v_or_b32_e32 v26, 0xff, v26
	v_add_u32_e32 v26, 0xffffff10, v26
	v_max_i32_e32 v44, v34, v29
	v_min_i32_e32 v29, v34, v29
	v_max3_i32 v26, v29, v27, v26
; __device__ __forceinline__ void route_task(int task, int tl0, const bf16* QP  , const LAS bf16* KHL, LAS unsigned short* EL, LAS float* GL, int lane) {
;     ...
;     int my[8];
; #pragma unroll
;     for (int i = 0; i < 8; ++i) { int lo_ = bk[i], hi_ = bk[8 + i]; asm volatile("" : "+v"(lo_), "+v"(hi_)); my[i] = hi ? hi_ : lo_; }
;     int bv[8];
; #pragma unroll
;     for (int i = 0; i < 8; ++i) {
;         const unsigned cd = 255u - ((unsigned)my[i] & 255u), ca = cd >> 4, cb = cd & 15u;
;         const unsigned wa = (ca >> 2) == 0u ? P1[0] : (ca >> 2) == 1u ? P1[1] : (ca >> 2) == 2u ? P1[2] : P1[3];
;         const unsigned wb = (cb >> 2) == 0u ? P2[0] : (cb >> 2) == 1u ? P2[1] : (cb >> 2) == 2u ? P2[2] : P2[3];
;         bv[i] = (int)((((wa >> (8u * (ca & 3u))) & 255u) << 7) | ((wb >> (8u * (cb & 3u))) & 255u));
;     }
;     float e[8], se = 0.f;
; #pragma unroll
;     for (int i = 0; i < 8; ++i) { e[i] = __expf(__int_as_float(my[i]) - __int_as_float(bk[0])); se += e[i]; }
	v_mov_b32_e32 v27, v32
	s_nop 0
	v_cndmask_b32_e64 v27, v37, v27, s[6:7]
	v_not_b32_e32 v29, v27
	v_bfe_u32 v45, v29, 6, 2
	v_cmp_eq_u32_e32 vcc, 2, v45
	v_cndmask_b32_e64 v30, v26, v30, s[6:7]
	v_bitop3_b32 v26, v27, s3, v27 bitop3:0xc
	v_cndmask_b32_e32 v46, v25, v23, vcc
	v_cmp_eq_u32_e32 vcc, 1, v45
	v_cndmask_b32_e64 v34, v35, v38, s[6:7]
	v_not_b32_e32 v35, v34
	v_cndmask_b32_e32 v45, v46, v21, vcc
	v_cmp_gt_u32_e32 vcc, 64, v26
	v_cndmask_b32_e64 v37, v40, v41, s[6:7]
	v_cndmask_b32_e64 v41, v44, v43, s[6:7]
	v_cndmask_b32_e32 v26, v45, v19, vcc
	v_bfe_u32 v45, v29, 2, 2
	v_cmp_eq_u32_e32 vcc, 2, v45
	v_bitop3_b32 v44, v27, 15, v27 bitop3:0xc
	v_bfe_u32 v47, v35, 6, 2
	v_cndmask_b32_e32 v46, v24, v22, vcc
	v_cmp_eq_u32_e32 vcc, 1, v45
	v_not_b32_e32 v38, v37
	v_bfe_u32 v49, v38, 6, 2
	v_cndmask_b32_e32 v45, v46, v20, vcc
	v_cmp_gt_u32_e32 vcc, 4, v44
	v_bitop3_b32 v46, v34, 15, v34 bitop3:0xc
	v_cndmask_b32_e64 v31, v31, v36, s[6:7]
	v_cndmask_b32_e32 v44, v45, v18, vcc
	v_cmp_eq_u32_e32 vcc, 2, v47
	v_bitop3_b32 v45, v34, s3, v34 bitop3:0xc
	v_not_b32_e32 v36, v31
	v_cndmask_b32_e32 v48, v25, v23, vcc
	v_cmp_eq_u32_e32 vcc, 1, v47
	v_bfe_u32 v51, v36, 6, 2
	v_cndmask_b32_e64 v33, v33, v39, s[6:7]
	v_cndmask_b32_e32 v47, v48, v21, vcc
	v_cmp_gt_u32_e32 vcc, 64, v45
	v_not_b32_e32 v39, v33
	v_bfe_u32 v53, v39, 6, 2
	v_cndmask_b32_e32 v45, v47, v19, vcc
	v_bfe_u32 v47, v35, 2, 2
	v_cmp_eq_u32_e32 vcc, 2, v47
	v_cndmask_b32_e64 v28, v28, v42, s[6:7]
	v_not_b32_e32 v40, v28
	v_cndmask_b32_e32 v48, v24, v22, vcc
	v_cmp_eq_u32_e32 vcc, 1, v47
	v_bfe_u32 v55, v40, 6, 2
	v_not_b32_e32 v42, v41
	v_cndmask_b32_e32 v47, v48, v20, vcc
	v_cmp_gt_u32_e32 vcc, 4, v46
	v_bitop3_b32 v48, v37, 15, v37 bitop3:0xc
	v_bfe_u32 v57, v42, 6, 2
	v_cndmask_b32_e32 v46, v47, v18, vcc
	v_cmp_eq_u32_e32 vcc, 2, v49
	v_bitop3_b32 v47, v37, s3, v37 bitop3:0xc
	v_not_b32_e32 v43, v30
	v_cndmask_b32_e32 v50, v25, v23, vcc
	v_cmp_eq_u32_e32 vcc, 1, v49
	v_bfe_u32 v59, v43, 6, 2
	s_nop 0
	v_cndmask_b32_e32 v49, v50, v21, vcc
	v_cmp_gt_u32_e32 vcc, 64, v47
	s_nop 1
	v_cndmask_b32_e32 v47, v49, v19, vcc
	v_bfe_u32 v49, v38, 2, 2
	v_cmp_eq_u32_e32 vcc, 2, v49
	s_nop 1
	v_cndmask_b32_e32 v50, v24, v22, vcc
	v_cmp_eq_u32_e32 vcc, 1, v49
	s_nop 1
	v_cndmask_b32_e32 v49, v50, v20, vcc
	v_cmp_gt_u32_e32 vcc, 4, v48
	v_bitop3_b32 v50, v31, 15, v31 bitop3:0xc
	s_nop 0
	v_cndmask_b32_e32 v48, v49, v18, vcc
	v_cmp_eq_u32_e32 vcc, 2, v51
	v_bitop3_b32 v49, v31, s3, v31 bitop3:0xc
	s_nop 0
	v_cndmask_b32_e32 v52, v25, v23, vcc
	v_cmp_eq_u32_e32 vcc, 1, v51
	s_nop 1
	v_cndmask_b32_e32 v51, v52, v21, vcc
	v_cmp_gt_u32_e32 vcc, 64, v49
	s_nop 1
	v_cndmask_b32_e32 v49, v51, v19, vcc
	v_bfe_u32 v51, v36, 2, 2
	v_cmp_eq_u32_e32 vcc, 2, v51
	s_nop 1
	v_cndmask_b32_e32 v52, v24, v22, vcc
	v_cmp_eq_u32_e32 vcc, 1, v51
	s_nop 1
	v_cndmask_b32_e32 v51, v52, v20, vcc
	v_cmp_gt_u32_e32 vcc, 4, v50
	v_bitop3_b32 v52, v33, 15, v33 bitop3:0xc
	s_nop 0
	v_cndmask_b32_e32 v50, v51, v18, vcc
	v_cmp_eq_u32_e32 vcc, 2, v53
	v_bitop3_b32 v51, v33, s3, v33 bitop3:0xc
	s_nop 0
	v_cndmask_b32_e32 v54, v25, v23, vcc
	v_cmp_eq_u32_e32 vcc, 1, v53
	s_nop 1
	v_cndmask_b32_e32 v53, v54, v21, vcc
	v_cmp_gt_u32_e32 vcc, 64, v51
	s_nop 1
	v_cndmask_b32_e32 v51, v53, v19, vcc
	v_bfe_u32 v53, v39, 2, 2
	v_cmp_eq_u32_e32 vcc, 2, v53
	s_nop 1
	v_cndmask_b32_e32 v54, v24, v22, vcc
	v_cmp_eq_u32_e32 vcc, 1, v53
	s_nop 1
	v_cndmask_b32_e32 v53, v54, v20, vcc
	v_cmp_gt_u32_e32 vcc, 4, v52
	v_bitop3_b32 v54, v28, 15, v28 bitop3:0xc
	s_nop 0
	v_cndmask_b32_e32 v52, v53, v18, vcc
	v_cmp_eq_u32_e32 vcc, 2, v55
	v_bitop3_b32 v53, v28, s3, v28 bitop3:0xc
	s_nop 0
	v_cndmask_b32_e32 v56, v25, v23, vcc
	v_cmp_eq_u32_e32 vcc, 1, v55
	s_nop 1
	v_cndmask_b32_e32 v55, v56, v21, vcc
	v_cmp_gt_u32_e32 vcc, 64, v53
	s_nop 1
	v_cndmask_b32_e32 v53, v55, v19, vcc
	v_bfe_u32 v55, v40, 2, 2
	v_cmp_eq_u32_e32 vcc, 2, v55
	s_nop 1
	v_cndmask_b32_e32 v56, v24, v22, vcc
	v_cmp_eq_u32_e32 vcc, 1, v55
	s_nop 1
	v_cndmask_b32_e32 v55, v56, v20, vcc
	v_cmp_gt_u32_e32 vcc, 4, v54
	v_bitop3_b32 v56, v41, 15, v41 bitop3:0xc
	s_nop 0
	v_cndmask_b32_e32 v54, v55, v18, vcc
	v_cmp_eq_u32_e32 vcc, 2, v57
	v_bitop3_b32 v55, v41, s3, v41 bitop3:0xc
	s_nop 0
	v_cndmask_b32_e32 v58, v25, v23, vcc
	v_cmp_eq_u32_e32 vcc, 1, v57
	s_nop 1
	v_cndmask_b32_e32 v57, v58, v21, vcc
	v_cmp_gt_u32_e32 vcc, 64, v55
	s_nop 1
	v_cndmask_b32_e32 v55, v57, v19, vcc
	v_bfe_u32 v57, v42, 2, 2
	v_cmp_eq_u32_e32 vcc, 2, v57
	s_nop 1
	v_cndmask_b32_e32 v58, v24, v22, vcc
	v_cmp_eq_u32_e32 vcc, 1, v57
	s_nop 1
	v_cndmask_b32_e32 v57, v58, v20, vcc
	v_cmp_gt_u32_e32 vcc, 4, v56
	v_bitop3_b32 v58, v30, 15, v30 bitop3:0xc
	s_nop 0
	v_cndmask_b32_e32 v56, v57, v18, vcc
	v_cmp_eq_u32_e32 vcc, 2, v59
	v_bitop3_b32 v57, v30, s3, v30 bitop3:0xc
	s_nop 0
	v_cndmask_b32_e32 v23, v25, v23, vcc
	v_cmp_eq_u32_e32 vcc, 1, v59
	v_sub_f32_e32 v25, v31, v32
	v_mul_f32_e32 v25, 0x3fb8aa3b, v25
	v_cndmask_b32_e32 v21, v23, v21, vcc
	v_cmp_gt_u32_e32 vcc, 64, v57
	v_lshrrev_b32_e32 v23, 1, v39
	v_and_b32_e32 v23, 24, v23
	v_cndmask_b32_e32 v19, v21, v19, vcc
	v_bfe_u32 v21, v43, 2, 2
	v_cmp_eq_u32_e32 vcc, 2, v21
	v_lshrrev_b32_e32 v23, v23, v51
	v_lshlrev_b32_e32 v23, 7, v23
	v_cndmask_b32_e32 v22, v24, v22, vcc
	v_cmp_eq_u32_e32 vcc, 1, v21
	v_lshrrev_b32_e32 v21, 1, v42
	v_and_b32_e32 v21, 24, v21
	v_cndmask_b32_e32 v20, v22, v20, vcc
	v_cmp_gt_u32_e32 vcc, 4, v58
	v_lshrrev_b32_e32 v21, v21, v55
	v_lshrrev_b32_e32 v22, 1, v40
	v_cndmask_b32_e32 v18, v20, v18, vcc
	v_lshlrev_b32_e32 v20, 3, v42
	v_lshlrev_b32_e32 v21, 7, v21
	v_and_b32_e32 v22, 24, v22
	v_lshrrev_b32_e32 v20, v20, v56
; #define LAS __attribute__((address_space(3)))
; __device__ __forceinline__ void route_task(int task, int tl0, const bf16* QP  , const LAS bf16* KHL, LAS unsigned short* EL, LAS float* GL, int lane) {
;     ...
;     for (int i = 0; i < 8; ++i) {
;         const unsigned cd = 255u - ((unsigned)my[i] & 255u), ca = cd >> 4, cb = cd & 15u;
;         const unsigned wa = (ca >> 2) == 0u ? P1[0] : (ca >> 2) == 1u ? P1[1] : (ca >> 2) == 2u ? P1[2] : P1[3];
;         const unsigned wb = (cb >> 2) == 0u ? P2[0] : (cb >> 2) == 1u ? P2[1] : (cb >> 2) == 2u ? P2[2] : P2[3];
;         bv[i] = (int)((((wa >> (8u * (ca & 3u))) & 255u) << 7) | ((wb >> (8u * (cb & 3u))) & 255u));
;     }
;     float e[8], se = 0.f;
; #pragma unroll
;     for (int i = 0; i < 8; ++i) { e[i] = __expf(__int_as_float(my[i]) - __int_as_float(bk[0])); se += e[i]; }
;     se += __shfl_xor(se, 32);
;     const float inv = 1.f / se;
;     {
;         int l2 = lane; asm volatile("" : "+v"(l2));
;         const int o2 = (tl0 + ((l2 & 31) >> 3)) * 128 + (l2 & 7) * 16 + 8 * (l2 >> 5);
;         LAS v4u* ip = (LAS v4u*)(EL + o2); typedef float f4v __attribute__((ext_vector_type(4))); LAS f4v* gp = (LAS f4v*)(GL + o2);
;         ip[0] = (v4u){(unsigned)bv[0] | ((unsigned)bv[1] << 16), (unsigned)bv[2] | ((unsigned)bv[3] << 16), (unsigned)bv[4] | ((unsigned)bv[5] << 16), (unsigned)bv[6] | ((unsigned)bv[7] << 16)};
;         gp[0] = (f4v){e[0] * inv, e[1] * inv, e[2] * inv, e[3] * inv}; gp[1] = (f4v){e[4] * inv, e[5] * inv, e[6] * inv, e[7] * inv};
;     }
; }
; __global__ void __launch_bounds__(NTHR, 2) k_main(Args a) {
;     ...
;             __syncthreads();
	v_and_b32_e32 v21, 0x7f80, v21
	v_lshrrev_b32_e32 v22, v22, v53
	v_and_or_b32 v21, v20, s3, v21
	v_lshlrev_b32_e32 v20, 3, v40
	v_lshlrev_b32_e32 v22, 7, v22
	v_lshrrev_b32_e32 v20, v20, v54
	v_and_b32_e32 v22, 0x7f80, v22
	v_and_or_b32 v20, v20, s3, v22
	v_lshlrev_b32_e32 v22, 3, v39
	v_lshrrev_b32_e32 v22, v22, v52
	v_and_b32_e32 v23, 0x7f80, v23
	v_and_or_b32 v39, v22, s3, v23
	v_lshrrev_b32_e32 v23, 1, v36
	v_and_b32_e32 v23, 24, v23
	v_lshrrev_b32_e32 v23, v23, v49
	v_lshlrev_b32_e32 v22, 3, v36
	v_lshlrev_b32_e32 v23, 7, v23
	v_lshrrev_b32_e32 v22, v22, v50
	v_and_b32_e32 v23, 0x7f80, v23
	v_and_or_b32 v36, v22, s3, v23
	v_lshrrev_b32_e32 v23, 1, v38
	v_and_b32_e32 v23, 24, v23
	v_lshrrev_b32_e32 v23, v23, v47
	v_lshlrev_b32_e32 v22, 3, v38
	v_lshlrev_b32_e32 v23, 7, v23
	v_lshrrev_b32_e32 v22, v22, v48
	v_and_b32_e32 v23, 0x7f80, v23
	v_and_or_b32 v38, v22, s3, v23
	v_lshrrev_b32_e32 v23, 1, v35
	v_and_b32_e32 v23, 24, v23
	v_lshrrev_b32_e32 v23, v23, v45
	v_lshlrev_b32_e32 v22, 3, v35
	v_lshlrev_b32_e32 v23, 7, v23
	v_lshrrev_b32_e32 v22, v22, v46
	v_and_b32_e32 v23, 0x7f80, v23
	v_and_or_b32 v35, v22, s3, v23
	v_lshrrev_b32_e32 v23, 1, v29
	v_and_b32_e32 v23, 24, v23
	v_lshrrev_b32_e32 v23, v23, v26
	v_lshlrev_b32_e32 v22, 3, v29
	v_lshlrev_b32_e32 v23, 7, v23
	v_lshrrev_b32_e32 v22, v22, v44
	v_and_b32_e32 v23, 0x7f80, v23
	v_and_or_b32 v40, v22, s3, v23
	v_sub_f32_e32 v22, v27, v32
	v_mul_f32_e32 v22, 0x3fb8aa3b, v22
	v_sub_f32_e32 v23, v34, v32
	v_exp_f32_e32 v22, v22
	v_mul_f32_e32 v23, 0x3fb8aa3b, v23
	v_sub_f32_e32 v24, v37, v32
	v_exp_f32_e32 v23, v23
	v_mul_f32_e32 v24, 0x3fb8aa3b, v24
	v_exp_f32_e32 v24, v24
	v_exp_f32_e32 v25, v25
	v_add_f32_e32 v26, 0, v22
	v_add_f32_e32 v26, v23, v26
	v_add_f32_e32 v26, v24, v26
	v_add_f32_e32 v31, v25, v26
	v_sub_f32_e32 v26, v33, v32
	v_mul_f32_e32 v26, 0x3fb8aa3b, v26
	v_sub_f32_e32 v27, v28, v32
	v_exp_f32_e32 v26, v26
	v_mul_f32_e32 v27, 0x3fb8aa3b, v27
	v_sub_f32_e32 v28, v41, v32
	v_exp_f32_e32 v27, v27
	v_mul_f32_e32 v28, 0x3fb8aa3b, v28
	v_sub_f32_e32 v29, v30, v32
	v_exp_f32_e32 v28, v28
	v_mul_f32_e32 v29, 0x3fb8aa3b, v29
	v_exp_f32_e32 v29, v29
	v_add_f32_e32 v30, v26, v31
	v_add_f32_e32 v30, v27, v30
	v_add_f32_e32 v30, v28, v30
	v_add_f32_e32 v30, v29, v30
	ds_bpermute_b32 v31, v123, v30
	v_lshrrev_b32_e32 v42, 1, v43
	v_and_b32_e32 v32, 24, v42
	v_lshrrev_b32_e32 v19, v32, v19
	v_lshlrev_b32_e32 v19, 7, v19
	s_waitcnt lgkmcnt(0)
	v_add_f32_e32 v30, v30, v31
	v_div_scale_f32 v31, s[12:13], v30, v30, 1.0
	v_rcp_f32_e32 v32, v31
	v_lshlrev_b32_e32 v33, 3, v43
	v_and_b32_e32 v19, 0x7f80, v19
	v_lshrrev_b32_e32 v18, v33, v18
	v_and_or_b32 v33, v18, s3, v19
	v_fma_f32 v18, -v31, v32, 1.0
	v_fmac_f32_e32 v32, v18, v32
	v_div_scale_f32 v18, vcc, 1.0, v30, 1.0
	v_mul_f32_e32 v19, v18, v32
	v_fma_f32 v34, -v31, v19, v18
	v_fmac_f32_e32 v19, v34, v32
	v_fma_f32 v18, -v31, v19, v18
	v_div_fmas_f32 v18, v18, v32, v19
	v_div_fixup_f32 v30, v18, v30, 1.0
	v_mov_b32_e32 v18, v1
	v_lshl_or_b32 v20, v20, 16, v39
	v_lshrrev_b32_e32 v19, 3, v18
	v_and_or_b32 v19, v19, 3, s57
	v_lshlrev_b32_e32 v31, 4, v18
	v_ashrrev_i32_e32 v18, 2, v18
	v_lshlrev_b32_e32 v19, 7, v19
	v_and_b32_e32 v31, 0x70, v31
	v_and_b32_e32 v18, -8, v18
	v_add3_u32 v18, v18, v31, v19
	v_lshl_add_u32 v31, v18, 1, s11
	v_lshl_add_u32 v32, v18, 2, s69
	v_lshl_or_b32 v18, v35, 16, v40
	v_lshl_or_b32 v19, v36, 16, v38
	v_lshl_or_b32 v21, v33, 16, v21
	ds_write_b128 v31, v[18:21]
	v_pk_mul_f32 v[20:21], v[24:25], v[30:31] op_sel_hi:[1,0]
	v_pk_mul_f32 v[18:19], v[22:23], v[30:31] op_sel_hi:[1,0]
	ds_write_b128 v32, v[18:21]
	v_pk_mul_f32 v[20:21], v[28:29], v[30:31] op_sel_hi:[1,0]
	v_pk_mul_f32 v[18:19], v[26:27], v[30:31] op_sel_hi:[1,0]
	ds_write_b128 v32, v[18:21] offset:16
	v_xor_b32_e32 v18, 4, v112
	v_cmp_lt_i32_e32 vcc, v18, v122
	s_waitcnt lgkmcnt(0)
	s_barrier
; #define LAS __attribute__((address_space(3)))
; __device__ __forceinline__ void peer_u_item(int p, int j, const LAS unsigned short* EL  , const unsigned char* __restrict__ XQ, const unsigned char* __restrict__ U8, LAS int* ACC  , int lane, int wave) {
;     asm volatile("" : "+v"(lane));
;     const int gidx = lane >> 3; const unsigned coff = (unsigned)(p * 128 + (lane & 7) * 16), toff = (unsigned)(p * (16384 * 128) + (lane & 7) * 16);
; #pragma unroll 1
;     for (int it = 0; it < 8; ++it) {
;         const int t = j * 64 + it * 8 + wave;
;         unsigned E[8];
;         { const LAS v4u* ep = (const LAS v4u*)(EL + (it * 8 + wave) * 128 + 16 * gidx); const v4u e0 = ep[0], e1 = ep[1];
;           E[0] = e0.x; E[1] = e0.y; E[2] = e0.z; E[3] = e0.w; E[4] = e1.x; E[5] = e1.y; E[6] = e1.z; E[7] = e1.w; }
;         uint4 uu[16];
; #pragma unroll
;         for (int i = 0; i < 16; ++i) uu[i] = *(const uint4*)(U8 + (size_t)(PE_ID(E, i) * 128u + toff));
;         const uint4 xh = *(const uint4*)(XQ + (size_t)t * 512 + coff), xl = *(const uint4*)(XQ + 8 * MiB + (size_t)t * 512 + coff);
	v_cndmask_b32_e32 v18, v112, v18, vcc
	v_lshlrev_b32_e32 v30, 2, v18
	v_xor_b32_e32 v18, 2, v112
	v_cmp_lt_i32_e32 vcc, v18, v122
	s_nop 1
	v_cndmask_b32_e32 v18, v112, v18, vcc
	v_lshlrev_b32_e32 v31, 2, v18
	v_xor_b32_e32 v18, 1, v112
	v_cmp_lt_i32_e32 vcc, v18, v122
	s_nop 1
	v_cndmask_b32_e32 v18, v112, v18, vcc
	v_lshlrev_b32_e32 v32, 2, v18
	s_nop 0
	s_nop 0
	s_nop 0
	s_nop 0
	s_nop 0
	s_nop 0
	s_nop 0
	s_nop 0
	s_nop 0
	s_nop 0
	s_nop 0
	s_nop 0
	s_nop 0
	s_nop 0
	s_nop 0
	v_lshlrev_b32_e32 v56, 4, v1
	v_and_b32_e32 v56, 0x70, v56
	v_lshrrev_b32_e32 v59, 3, v1
	v_lshlrev_b32_e32 v59, 5, v59
	v_add_u32_e32 v59, s66, v59
	v_add_u32_e32 v59, -16, v59
	v_lshl_add_u32 v60, v1, 3, s64
	v_and_b32_e32 v38, 4, v1
	v_cmp_ne_u32_e64 s[10:11], 0, v38
	v_and_b32_e32 v38, 2, v1
	v_cmp_ne_u32_e64 s[12:13], 0, v38
	v_and_b32_e32 v38, 1, v1
	v_cmp_ne_u32_e64 s[14:15], 0, v38
	s_movk_i32 s94, 0x80
	s_mov_b32 s42, 0
	s_mov_b32 s43, 0
	s_mov_b32 s44, 1
	s_mov_b32 s45, 0
	s_lshl_b32 s32, s42, 11
	v_add_u32_e32 v39, s32, v59
	ds_read_b128 v[202:205], v39
	ds_read_b128 v[206:209], v39 offset:16
	s_lshl_b32 s46, s42, 3
	s_add_i32 s46, s46, s40
	s_lshl_b32 s46, s46, 9
	s_lshl_b32 s32, s43, 7
	s_add_i32 s46, s46, s32
	v_add_u32_e32 v57, s46, v56
	global_load_dwordx4 v[186:189], v57, s[34:35]
	global_load_dwordx4 v[190:193], v57, s[36:37]
	v_mov_b32_e32 v58, v56
	s_waitcnt lgkmcnt(0)
	v_and_b32_e32 v38, 0xffff, v202
	v_lshl_add_u32 v38, v38, 7, v58
	global_load_dwordx4 v[122:125], v38, s[96:97]
	v_lshrrev_b32_e32 v38, 16, v202
	v_lshl_add_u32 v38, v38, 7, v58
	global_load_dwordx4 v[126:129], v38, s[96:97]
	v_and_b32_e32 v38, 0xffff, v203
	v_lshl_add_u32 v38, v38, 7, v58
	global_load_dwordx4 v[130:133], v38, s[96:97]
	v_lshrrev_b32_e32 v38, 16, v203
	v_lshl_add_u32 v38, v38, 7, v58
	global_load_dwordx4 v[134:137], v38, s[96:97]
	v_and_b32_e32 v38, 0xffff, v204
	v_lshl_add_u32 v38, v38, 7, v58
	global_load_dwordx4 v[138:141], v38, s[96:97]
	v_lshrrev_b32_e32 v38, 16, v204
	v_lshl_add_u32 v38, v38, 7, v58
	global_load_dwordx4 v[142:145], v38, s[96:97]
	v_and_b32_e32 v38, 0xffff, v205
	v_lshl_add_u32 v38, v38, 7, v58
	global_load_dwordx4 v[146:149], v38, s[96:97]
	v_lshrrev_b32_e32 v38, 16, v205
	v_lshl_add_u32 v38, v38, 7, v58
	global_load_dwordx4 v[150:153], v38, s[96:97]
	v_and_b32_e32 v38, 0xffff, v206
	v_lshl_add_u32 v38, v38, 7, v58
	global_load_dwordx4 v[154:157], v38, s[96:97]
	v_lshrrev_b32_e32 v38, 16, v206
	v_lshl_add_u32 v38, v38, 7, v58
	global_load_dwordx4 v[158:161], v38, s[96:97]
	v_and_b32_e32 v38, 0xffff, v207
	v_lshl_add_u32 v38, v38, 7, v58
	global_load_dwordx4 v[162:165], v38, s[96:97]
	v_lshrrev_b32_e32 v38, 16, v207
	v_lshl_add_u32 v38, v38, 7, v58
	global_load_dwordx4 v[166:169], v38, s[96:97]
	v_and_b32_e32 v38, 0xffff, v208
	v_lshl_add_u32 v38, v38, 7, v58
	global_load_dwordx4 v[170:173], v38, s[96:97]
	v_lshrrev_b32_e32 v38, 16, v208
	v_lshl_add_u32 v38, v38, 7, v58
	global_load_dwordx4 v[174:177], v38, s[96:97]
	v_and_b32_e32 v38, 0xffff, v209
	v_lshl_add_u32 v38, v38, 7, v58
	global_load_dwordx4 v[178:181], v38, s[96:97]
	v_lshrrev_b32_e32 v38, 16, v209
	v_lshl_add_u32 v38, v38, 7, v58
	global_load_dwordx4 v[182:185], v38, s[96:97]
	s_mov_b32 s47, 15
